# trailing barrier of every GEMM MFMA segment moved one MFMA up (the last MFMA issues behind the barrier)
# speedup vs baseline: 1.0141x; 1.0014x over previous
; #define PG8_STAGE(bufoff, gbase, voff) do { _Pragma("unroll") for (int _i = 0; _i < 2; ++_i) \
;         __builtin_amdgcn_global_load_lds((const unsigned*)((const char*)(gbase) + (voff)[_i]), (PG8_LAS unsigned*)(lds + (bufoff) + ldsw + _i * 8192), 16, 0, 0); } while (0)
; #define PG8_LDA(dst, b, h) do { _Pragma("unroll") for (int m = 0; m < 4; ++m) _Pragma("unroll") for (int k = 0; k < 2; ++k) dst[m][k] = *(const PG8_LAS bf16x8*)(lds + PG8_SA(b, h) + aoff + m * 2048 + k * 1024); } while (0)
; #define PG8_LDB(dst, b, h) do { _Pragma("unroll") for (int n = 0; n < 2; ++n) _Pragma("unroll") for (int k = 0; k < 2; ++k) dst[n][k] = *(const PG8_LAS bf16x8*)(lds + PG8_SB(b, h) + boff + n * 2048 + k * 1024); } while (0)
; #define PG8_MMA(ai, bj, At, Bt) do { __builtin_amdgcn_s_setprio(1); _Pragma("unroll") for (int m = 0; m < 4; ++m) _Pragma("unroll") for (int n = 0; n < 2; ++n) _Pragma("unroll") for (int k = 0; k < 2; ++k) \
;         acc[ai][bj][m][n] = __builtin_amdgcn_mfma_f32_16x16x32_bf16(Bt[n][k], At[m][k], acc[ai][bj][m][n], 0, 0, 0); __builtin_amdgcn_s_setprio(0); } while (0)
; #define PG8_WAIT_V(n) asm volatile("s_waitcnt vmcnt(" #n ")" ::: "memory")
; #define PG8_WAIT_L(n) asm volatile("s_waitcnt lgkmcnt(" #n ")" ::: "memory")
; #define PG8_BAR __builtin_amdgcn_s_barrier()
; #define PG8_SCHED __builtin_amdgcn_sched_barrier(0)
; template <class Epi, class Sched, bool ALIGN_EPI = false, bool SP2 = false>
; __device__ __forceinline__ void gemm_phase(PG8_LAS unsigned char* lds, const Gemm g, const Sched& S, const Epi& E) {
;     ...
;             PG8_LDB(B0, 0, 0); PG8_LDB(B1, 0, 1); PG8_SCHED; PG8_LDA(At, 0, 0); PG8_STAGE(PG8_SA(1, 1), a1 + hstep, voffA);
;             PG8_WAIT_V(8); PG8_WAIT_L(0); PG8_BAR; PG8_MMA(0, 0, At, B0); PG8_MMA(0, 1, At, B1); PG8_BAR; PG8_SCHED;
;             PG8_LDA(At, 0, 1); PG8_STAGE(PG8_SB(0, 0), b2, voffB); PG8_STAGE(PG8_SB(0, 1), b2 + hstep, voffB); PG8_STAGE(PG8_SA(0, 0), a2, voffA);
;             PG8_WAIT_V(8); PG8_WAIT_L(0); PG8_BAR; PG8_MMA(1, 0, At, B0); PG8_MMA(1, 1, At, B1); PG8_BAR; PG8_SCHED;
.LBB0_141:
	ds_read_b128 v[130:133], v196
	ds_read_b128 v[134:137], v196 offset:1024
	ds_read_b128 v[138:141], v196 offset:2048
	ds_read_b128 v[142:145], v196 offset:3072
	s_waitcnt lgkmcnt(0)
	ds_read_b128 v[170:173], v197
	ds_read_b128 v[174:177], v197 offset:1024
	ds_read_b128 v[178:181], v197 offset:2048
	ds_read_b128 v[182:185], v197 offset:3072
	s_add_u32 s18, s84, 0xfffc0080
	s_addc_u32 s19, s85, -1
	s_cmp_eq_u32 vcc_lo, 12
	s_cselect_b32 s87, s7, s19
	s_cselect_b32 s86, s9, s18
	s_cselect_b32 s31, s10, s75
	s_cselect_b32 s30, s69, s73
	v_lshl_add_u64 v[190:191], s[84:85], 0, v[162:163]
	s_add_i32 m0, s91, 0xc000
	ds_read_b128 v[186:189], v198
	ds_read_b128 v[202:205], v198 offset:1024
	ds_read_b128 v[208:211], v198 offset:2048
	ds_read_b128 v[212:215], v198 offset:3072
	ds_read_b128 v[216:219], v198 offset:4096
	ds_read_b128 v[220:223], v198 offset:5120
	ds_read_b128 v[224:227], v198 offset:6144
	ds_read_b128 v[228:231], v198 offset:7168
	global_load_lds_dwordx4 v[190:191], off
	v_lshl_add_u64 v[190:191], s[84:85], 0, v[164:165]
	s_add_i32 m0, s91, 0xe000
	s_nop 0
	global_load_lds_dwordx4 v[190:191], off
	s_waitcnt vmcnt(8)
	s_waitcnt lgkmcnt(0)
	s_barrier
	s_setprio 1
	s_waitcnt lgkmcnt(0)
	v_mfma_f32_16x16x32_bf16 v[126:129], v[130:133], v[186:189], v[126:129]
	v_mfma_f32_16x16x32_bf16 v[122:125], v[138:141], v[186:189], v[122:125]
	v_mfma_f32_16x16x32_bf16 v[110:113], v[130:133], v[208:211], v[110:113]
	v_mfma_f32_16x16x32_bf16 v[106:109], v[138:141], v[208:211], v[106:109]
	v_mfma_f32_16x16x32_bf16 v[94:97], v[130:133], v[216:219], v[94:97]
	v_mfma_f32_16x16x32_bf16 v[90:93], v[138:141], v[216:219], v[90:93]
	v_mfma_f32_16x16x32_bf16 v[78:81], v[130:133], v[224:227], v[78:81]
	v_mfma_f32_16x16x32_bf16 v[74:77], v[138:141], v[224:227], v[74:77]
	v_mfma_f32_16x16x32_bf16 v[126:129], v[134:137], v[202:205], v[126:129]
	v_mfma_f32_16x16x32_bf16 v[122:125], v[142:145], v[202:205], v[122:125]
	v_mfma_f32_16x16x32_bf16 v[110:113], v[134:137], v[212:215], v[110:113]
	v_mfma_f32_16x16x32_bf16 v[106:109], v[142:145], v[212:215], v[106:109]
	v_mfma_f32_16x16x32_bf16 v[94:97], v[134:137], v[220:223], v[94:97]
	v_mfma_f32_16x16x32_bf16 v[90:93], v[142:145], v[220:223], v[90:93]
	v_mfma_f32_16x16x32_bf16 v[78:81], v[134:137], v[228:231], v[78:81]
	v_mfma_f32_16x16x32_bf16 v[74:77], v[142:145], v[228:231], v[74:77]
	s_setprio 0
	s_setprio 1
	v_mfma_f32_16x16x32_bf16 v[118:121], v[170:173], v[186:189], v[118:121]
	v_mfma_f32_16x16x32_bf16 v[114:117], v[178:181], v[186:189], v[114:117]
	v_mfma_f32_16x16x32_bf16 v[102:105], v[170:173], v[208:211], v[102:105]
	v_mfma_f32_16x16x32_bf16 v[98:101], v[178:181], v[208:211], v[98:101]
	v_mfma_f32_16x16x32_bf16 v[86:89], v[170:173], v[216:219], v[86:89]
	v_mfma_f32_16x16x32_bf16 v[82:85], v[178:181], v[216:219], v[82:85]
	v_mfma_f32_16x16x32_bf16 v[70:73], v[170:173], v[224:227], v[70:73]
	v_mfma_f32_16x16x32_bf16 v[66:69], v[178:181], v[224:227], v[66:69]
	v_mfma_f32_16x16x32_bf16 v[118:121], v[174:177], v[202:205], v[118:121]
	v_mfma_f32_16x16x32_bf16 v[114:117], v[182:185], v[202:205], v[114:117]
	v_mfma_f32_16x16x32_bf16 v[102:105], v[174:177], v[212:215], v[102:105]
	v_mfma_f32_16x16x32_bf16 v[98:101], v[182:185], v[212:215], v[98:101]
	v_mfma_f32_16x16x32_bf16 v[86:89], v[174:177], v[220:223], v[86:89]
	v_mfma_f32_16x16x32_bf16 v[82:85], v[182:185], v[220:223], v[82:85]
	v_mfma_f32_16x16x32_bf16 v[70:73], v[174:177], v[228:231], v[70:73]
	s_barrier
	v_mfma_f32_16x16x32_bf16 v[66:69], v[182:185], v[228:231], v[66:69]
	s_setprio 0
	s_add_i32 s18, s58, s88
	v_lshl_add_u64 v[190:191], s[30:31], 0, v[148:149]
	s_mov_b32 m0, s18
	ds_read_b128 v[186:189], v198 offset:16384
	ds_read_b128 v[202:205], v198 offset:17408
	ds_read_b128 v[208:211], v198 offset:18432
	ds_read_b128 v[212:215], v198 offset:19456
	ds_read_b128 v[216:219], v198 offset:20480
	ds_read_b128 v[220:223], v198 offset:21504
	ds_read_b128 v[224:227], v198 offset:22528
	ds_read_b128 v[228:231], v198 offset:23552
	global_load_lds_dwordx4 v[190:191], off
	s_add_i32 m0, s18, 0x2000
	s_add_u32 s18, s30, 0x40000
	v_lshl_add_u64 v[232:233], s[30:31], 0, v[152:153]
	s_addc_u32 s19, s31, 0
	s_add_i32 vcc_hi, s59, s88
	global_load_lds_dwordx4 v[232:233], off
	v_lshl_add_u64 v[234:235], s[18:19], 0, v[148:149]
	s_mov_b32 m0, vcc_hi
	v_lshl_add_u64 v[238:239], s[86:87], 0, v[150:151]
	global_load_lds_dwordx4 v[234:235], off
	v_lshl_add_u64 v[234:235], s[18:19], 0, v[152:153]
	s_add_i32 m0, vcc_hi, 0x2000
	s_nop 0
	global_load_lds_dwordx4 v[234:235], off
	v_lshl_add_u64 v[234:235], s[86:87], 0, v[146:147]
	s_mov_b32 m0, s91
	s_nop 0
	global_load_lds_dwordx4 v[234:235], off
	s_mov_b32 m0, s92
	s_nop 0
	global_load_lds_dwordx4 v[238:239], off
	s_waitcnt vmcnt(8)
	s_waitcnt lgkmcnt(0)
	s_barrier
; #define PG8_STAGE(bufoff, gbase, voff) do { _Pragma("unroll") for (int _i = 0; _i < 2; ++_i) \
;         __builtin_amdgcn_global_load_lds((const unsigned*)((const char*)(gbase) + (voff)[_i]), (PG8_LAS unsigned*)(lds + (bufoff) + ldsw + _i * 8192), 16, 0, 0); } while (0)
; #define PG8_LDA(dst, b, h) do { _Pragma("unroll") for (int m = 0; m < 4; ++m) _Pragma("unroll") for (int k = 0; k < 2; ++k) dst[m][k] = *(const PG8_LAS bf16x8*)(lds + PG8_SA(b, h) + aoff + m * 2048 + k * 1024); } while (0)
; #define PG8_LDB(dst, b, h) do { _Pragma("unroll") for (int n = 0; n < 2; ++n) _Pragma("unroll") for (int k = 0; k < 2; ++k) dst[n][k] = *(const PG8_LAS bf16x8*)(lds + PG8_SB(b, h) + boff + n * 2048 + k * 1024); } while (0)
; #define PG8_MMA(ai, bj, At, Bt) do { __builtin_amdgcn_s_setprio(1); _Pragma("unroll") for (int m = 0; m < 4; ++m) _Pragma("unroll") for (int n = 0; n < 2; ++n) _Pragma("unroll") for (int k = 0; k < 2; ++k) \
;         acc[ai][bj][m][n] = __builtin_amdgcn_mfma_f32_16x16x32_bf16(Bt[n][k], At[m][k], acc[ai][bj][m][n], 0, 0, 0); __builtin_amdgcn_s_setprio(0); } while (0)
; #define PG8_WAIT_V(n) asm volatile("s_waitcnt vmcnt(" #n ")" ::: "memory")
; #define PG8_WAIT_L(n) asm volatile("s_waitcnt lgkmcnt(" #n ")" ::: "memory")
; #define PG8_BAR __builtin_amdgcn_s_barrier()
; #define PG8_SCHED __builtin_amdgcn_sched_barrier(0)
; template <class Epi, class Sched, bool ALIGN_EPI = false, bool SP2 = false>
; __device__ __forceinline__ void gemm_phase(PG8_LAS unsigned char* lds, const Gemm g, const Sched& S, const Epi& E) {
;     ...
;             PG8_WAIT_V(8); PG8_WAIT_L(0); PG8_BAR; PG8_MMA(1, 0, At, B0); PG8_MMA(1, 1, At, B1); PG8_BAR; PG8_SCHED;
;             PG8_LDB(B0, 1, 0); PG8_LDB(B1, 1, 1); PG8_SCHED; PG8_LDA(At, 1, 0); PG8_STAGE(PG8_SA(0, 1), a2 + hstep, voffA);
;             PG8_WAIT_V(8); PG8_WAIT_L(0); PG8_BAR; PG8_MMA(0, 0, At, B0); PG8_MMA(0, 1, At, B1); PG8_BAR; PG8_SCHED;
	s_setprio 1
	s_waitcnt lgkmcnt(0)
	v_mfma_f32_16x16x32_bf16 v[62:65], v[130:133], v[186:189], v[62:65]
	v_mfma_f32_16x16x32_bf16 v[58:61], v[138:141], v[186:189], v[58:61]
	v_mfma_f32_16x16x32_bf16 v[46:49], v[130:133], v[208:211], v[46:49]
	v_mfma_f32_16x16x32_bf16 v[42:45], v[138:141], v[208:211], v[42:45]
	v_mfma_f32_16x16x32_bf16 v[30:33], v[130:133], v[216:219], v[30:33]
	v_mfma_f32_16x16x32_bf16 v[26:29], v[138:141], v[216:219], v[26:29]
	v_mfma_f32_16x16x32_bf16 v[14:17], v[130:133], v[224:227], v[14:17]
	v_mfma_f32_16x16x32_bf16 v[10:13], v[138:141], v[224:227], v[10:13]
	v_mfma_f32_16x16x32_bf16 v[62:65], v[134:137], v[202:205], v[62:65]
	v_mfma_f32_16x16x32_bf16 v[58:61], v[142:145], v[202:205], v[58:61]
	v_mfma_f32_16x16x32_bf16 v[46:49], v[134:137], v[212:215], v[46:49]
	v_mfma_f32_16x16x32_bf16 v[42:45], v[142:145], v[212:215], v[42:45]
	v_mfma_f32_16x16x32_bf16 v[30:33], v[134:137], v[220:223], v[30:33]
	v_mfma_f32_16x16x32_bf16 v[26:29], v[142:145], v[220:223], v[26:29]
	v_mfma_f32_16x16x32_bf16 v[14:17], v[134:137], v[228:231], v[14:17]
	v_mfma_f32_16x16x32_bf16 v[10:13], v[142:145], v[228:231], v[10:13]
	s_setprio 0
	s_setprio 1
	v_mfma_f32_16x16x32_bf16 v[54:57], v[170:173], v[186:189], v[54:57]
	v_mfma_f32_16x16x32_bf16 v[50:53], v[178:181], v[186:189], v[50:53]
	v_mfma_f32_16x16x32_bf16 v[38:41], v[170:173], v[208:211], v[38:41]
	v_mfma_f32_16x16x32_bf16 v[34:37], v[178:181], v[208:211], v[34:37]
	v_mfma_f32_16x16x32_bf16 v[22:25], v[170:173], v[216:219], v[22:25]
	v_mfma_f32_16x16x32_bf16 v[18:21], v[178:181], v[216:219], v[18:21]
	v_mfma_f32_16x16x32_bf16 v[6:9], v[170:173], v[224:227], v[6:9]
	v_mfma_f32_16x16x32_bf16 v[2:5], v[178:181], v[224:227], v[2:5]
	v_mfma_f32_16x16x32_bf16 v[54:57], v[174:177], v[202:205], v[54:57]
	v_mfma_f32_16x16x32_bf16 v[50:53], v[182:185], v[202:205], v[50:53]
	v_mfma_f32_16x16x32_bf16 v[38:41], v[174:177], v[212:215], v[38:41]
	v_mfma_f32_16x16x32_bf16 v[34:37], v[182:185], v[212:215], v[34:37]
	v_mfma_f32_16x16x32_bf16 v[22:25], v[174:177], v[220:223], v[22:25]
	v_mfma_f32_16x16x32_bf16 v[18:21], v[182:185], v[220:223], v[18:21]
	v_mfma_f32_16x16x32_bf16 v[6:9], v[174:177], v[228:231], v[6:9]
	s_barrier
	v_mfma_f32_16x16x32_bf16 v[2:5], v[182:185], v[228:231], v[2:5]
	s_setprio 0
	s_add_i32 vcc_hi, 0, 0x18000
	s_add_i32 s52, 0, 0x1c000
	v_add_u32_e32 v142, vcc_hi, v157
	v_add_u32_e32 v154, s52, v157
	ds_read_b128 v[130:133], v142
	ds_read_b128 v[134:137], v142 offset:1024
	ds_read_b128 v[138:141], v142 offset:2048
	ds_read_b128 v[142:145], v142 offset:3072
	ds_read_b128 v[170:173], v154
	ds_read_b128 v[174:177], v154 offset:1024
	ds_read_b128 v[178:181], v154 offset:2048
	ds_read_b128 v[182:185], v154 offset:3072
	s_add_u32 s18, s86, 0x40000
	s_addc_u32 s19, s87, 0
	s_mov_b32 m0, s93
	v_lshl_add_u64 v[240:241], s[18:19], 0, v[146:147]
	ds_read_b128 v[186:189], v198 offset:32768
	ds_read_b128 v[202:205], v198 offset:33792
	ds_read_b128 v[208:211], v198 offset:34816
	ds_read_b128 v[212:215], v198 offset:35840
	ds_read_b128 v[216:219], v198 offset:36864
	ds_read_b128 v[220:223], v198 offset:37888
	ds_read_b128 v[224:227], v198 offset:38912
	ds_read_b128 v[228:231], v198 offset:39936
	global_load_lds_dwordx4 v[240:241], off
	v_lshl_add_u64 v[240:241], s[18:19], 0, v[150:151]
	s_mov_b32 m0, s95
	s_nop 0
	global_load_lds_dwordx4 v[240:241], off
	s_waitcnt vmcnt(8)
	s_waitcnt lgkmcnt(0)
	s_barrier
	s_setprio 1
	s_waitcnt lgkmcnt(0)
	v_mfma_f32_16x16x32_bf16 v[126:129], v[130:133], v[186:189], v[126:129]
	v_mfma_f32_16x16x32_bf16 v[122:125], v[138:141], v[186:189], v[122:125]
	v_mfma_f32_16x16x32_bf16 v[110:113], v[130:133], v[208:211], v[110:113]
	v_mfma_f32_16x16x32_bf16 v[106:109], v[138:141], v[208:211], v[106:109]
	v_mfma_f32_16x16x32_bf16 v[94:97], v[130:133], v[216:219], v[94:97]
	v_mfma_f32_16x16x32_bf16 v[90:93], v[138:141], v[216:219], v[90:93]
	v_mfma_f32_16x16x32_bf16 v[78:81], v[130:133], v[224:227], v[78:81]
	v_mfma_f32_16x16x32_bf16 v[74:77], v[138:141], v[224:227], v[74:77]
	v_mfma_f32_16x16x32_bf16 v[126:129], v[134:137], v[202:205], v[126:129]
	v_mfma_f32_16x16x32_bf16 v[122:125], v[142:145], v[202:205], v[122:125]
	v_mfma_f32_16x16x32_bf16 v[110:113], v[134:137], v[212:215], v[110:113]
	v_mfma_f32_16x16x32_bf16 v[106:109], v[142:145], v[212:215], v[106:109]
	v_mfma_f32_16x16x32_bf16 v[94:97], v[134:137], v[220:223], v[94:97]
	v_mfma_f32_16x16x32_bf16 v[90:93], v[142:145], v[220:223], v[90:93]
	v_mfma_f32_16x16x32_bf16 v[78:81], v[134:137], v[228:231], v[78:81]
	v_mfma_f32_16x16x32_bf16 v[74:77], v[142:145], v[228:231], v[74:77]
	s_setprio 0
	s_setprio 1
	v_mfma_f32_16x16x32_bf16 v[118:121], v[170:173], v[186:189], v[118:121]
	v_mfma_f32_16x16x32_bf16 v[114:117], v[178:181], v[186:189], v[114:117]
	v_mfma_f32_16x16x32_bf16 v[102:105], v[170:173], v[208:211], v[102:105]
	v_mfma_f32_16x16x32_bf16 v[98:101], v[178:181], v[208:211], v[98:101]
	v_mfma_f32_16x16x32_bf16 v[86:89], v[170:173], v[216:219], v[86:89]
	v_mfma_f32_16x16x32_bf16 v[82:85], v[178:181], v[216:219], v[82:85]
	v_mfma_f32_16x16x32_bf16 v[70:73], v[170:173], v[224:227], v[70:73]
	v_mfma_f32_16x16x32_bf16 v[66:69], v[178:181], v[224:227], v[66:69]
	v_mfma_f32_16x16x32_bf16 v[118:121], v[174:177], v[202:205], v[118:121]
	v_mfma_f32_16x16x32_bf16 v[114:117], v[182:185], v[202:205], v[114:117]
	v_mfma_f32_16x16x32_bf16 v[102:105], v[174:177], v[212:215], v[102:105]
	v_mfma_f32_16x16x32_bf16 v[98:101], v[182:185], v[212:215], v[98:101]
	v_mfma_f32_16x16x32_bf16 v[86:89], v[174:177], v[220:223], v[86:89]
	v_mfma_f32_16x16x32_bf16 v[82:85], v[182:185], v[220:223], v[82:85]
	v_mfma_f32_16x16x32_bf16 v[70:73], v[174:177], v[228:231], v[70:73]
	s_barrier
; #define PG8_STAGE(bufoff, gbase, voff) do { _Pragma("unroll") for (int _i = 0; _i < 2; ++_i) \
;         __builtin_amdgcn_global_load_lds((const unsigned*)((const char*)(gbase) + (voff)[_i]), (PG8_LAS unsigned*)(lds + (bufoff) + ldsw + _i * 8192), 16, 0, 0); } while (0)
; #define PG8_LDA(dst, b, h) do { _Pragma("unroll") for (int m = 0; m < 4; ++m) _Pragma("unroll") for (int k = 0; k < 2; ++k) dst[m][k] = *(const PG8_LAS bf16x8*)(lds + PG8_SA(b, h) + aoff + m * 2048 + k * 1024); } while (0)
; #define PG8_LDB(dst, b, h) do { _Pragma("unroll") for (int n = 0; n < 2; ++n) _Pragma("unroll") for (int k = 0; k < 2; ++k) dst[n][k] = *(const PG8_LAS bf16x8*)(lds + PG8_SB(b, h) + boff + n * 2048 + k * 1024); } while (0)
; #define PG8_MMA(ai, bj, At, Bt) do { __builtin_amdgcn_s_setprio(1); _Pragma("unroll") for (int m = 0; m < 4; ++m) _Pragma("unroll") for (int n = 0; n < 2; ++n) _Pragma("unroll") for (int k = 0; k < 2; ++k) \
;         acc[ai][bj][m][n] = __builtin_amdgcn_mfma_f32_16x16x32_bf16(Bt[n][k], At[m][k], acc[ai][bj][m][n], 0, 0, 0); __builtin_amdgcn_s_setprio(0); } while (0)
; #define PG8_WAIT_V(n) asm volatile("s_waitcnt vmcnt(" #n ")" ::: "memory")
; #define PG8_WAIT_L(n) asm volatile("s_waitcnt lgkmcnt(" #n ")" ::: "memory")
; #define PG8_BAR __builtin_amdgcn_s_barrier()
; #define PG8_SCHED __builtin_amdgcn_sched_barrier(0)
; template <class Epi, class Sched, bool ALIGN_EPI = false, bool SP2 = false>
; __device__ __forceinline__ void gemm_phase(PG8_LAS unsigned char* lds, const Gemm g, const Sched& S, const Epi& E) {
;     ...
;             PG8_LDB(B0, 1, 0); PG8_LDB(B1, 1, 1); PG8_SCHED; PG8_LDA(At, 1, 0); PG8_STAGE(PG8_SA(0, 1), a2 + hstep, voffA);
;             PG8_WAIT_V(8); PG8_WAIT_L(0); PG8_BAR; PG8_MMA(0, 0, At, B0); PG8_MMA(0, 1, At, B1); PG8_BAR; PG8_SCHED;
;             PG8_LDA(At, 1, 1); PG8_STAGE(PG8_SB(1, 0), b3, voffB); PG8_STAGE(PG8_SB(1, 1), b3 + hstep, voffB); PG8_STAGE(PG8_SA(1, 0), a3, voffA);
;             PG8_WAIT_V(8); PG8_WAIT_L(0); PG8_BAR; PG8_MMA(1, 0, At, B0); PG8_MMA(1, 1, At, B1); PG8_BAR; PG8_SCHED;
;     ...
;         if constexpr (ALIGN_EPI) { if (wr == 0) PG8_BAR; }
	v_mfma_f32_16x16x32_bf16 v[66:69], v[182:185], v[228:231], v[66:69]
	s_setprio 0
	s_add_i32 s18, vcc_hi, s88
	v_lshl_add_u64 v[190:191], v[190:191], 0, s[16:17]
	s_mov_b32 m0, s18
	ds_read_b128 v[186:189], v198 offset:49152
	ds_read_b128 v[202:205], v198 offset:50176
	ds_read_b128 v[208:211], v198 offset:51200
	ds_read_b128 v[212:215], v198 offset:52224
	ds_read_b128 v[216:219], v198 offset:53248
	ds_read_b128 v[220:223], v198 offset:54272
	ds_read_b128 v[224:227], v198 offset:55296
	ds_read_b128 v[228:231], v198 offset:56320
	global_load_lds_dwordx4 v[190:191], off
	s_add_i32 m0, s18, 0x2000
	s_add_u32 s18, s30, 0x40080
	v_lshl_add_u64 v[190:191], v[232:233], 0, s[16:17]
	s_addc_u32 s19, s31, 0
	s_add_i32 s30, s52, s88
	global_load_lds_dwordx4 v[190:191], off
	v_lshl_add_u64 v[190:191], s[18:19], 0, v[148:149]
	s_mov_b32 m0, s30
	s_nop 0
	global_load_lds_dwordx4 v[190:191], off
	v_lshl_add_u64 v[190:191], s[18:19], 0, v[152:153]
	s_add_i32 m0, s30, 0x2000
	s_nop 0
	global_load_lds_dwordx4 v[190:191], off
	v_lshl_add_u64 v[190:191], v[234:235], 0, s[16:17]
	s_mov_b32 m0, s24
	s_nop 0
	global_load_lds_dwordx4 v[190:191], off
	v_lshl_add_u64 v[190:191], v[238:239], 0, s[16:17]
	s_mov_b32 m0, s25
	s_nop 0
	global_load_lds_dwordx4 v[190:191], off
	s_waitcnt vmcnt(8)
	s_waitcnt lgkmcnt(0)
	s_barrier
	s_setprio 1
	s_waitcnt lgkmcnt(0)
	v_mfma_f32_16x16x32_bf16 v[62:65], v[130:133], v[186:189], v[62:65]
	v_mfma_f32_16x16x32_bf16 v[58:61], v[138:141], v[186:189], v[58:61]
	v_mfma_f32_16x16x32_bf16 v[46:49], v[130:133], v[208:211], v[46:49]
	v_mfma_f32_16x16x32_bf16 v[42:45], v[138:141], v[208:211], v[42:45]
	v_mfma_f32_16x16x32_bf16 v[30:33], v[130:133], v[216:219], v[30:33]
	v_mfma_f32_16x16x32_bf16 v[26:29], v[138:141], v[216:219], v[26:29]
	v_mfma_f32_16x16x32_bf16 v[14:17], v[130:133], v[224:227], v[14:17]
	v_mfma_f32_16x16x32_bf16 v[10:13], v[138:141], v[224:227], v[10:13]
	v_mfma_f32_16x16x32_bf16 v[62:65], v[134:137], v[202:205], v[62:65]
	v_mfma_f32_16x16x32_bf16 v[58:61], v[142:145], v[202:205], v[58:61]
	v_mfma_f32_16x16x32_bf16 v[46:49], v[134:137], v[212:215], v[46:49]
	v_mfma_f32_16x16x32_bf16 v[42:45], v[142:145], v[212:215], v[42:45]
	v_mfma_f32_16x16x32_bf16 v[30:33], v[134:137], v[220:223], v[30:33]
	v_mfma_f32_16x16x32_bf16 v[26:29], v[142:145], v[220:223], v[26:29]
	v_mfma_f32_16x16x32_bf16 v[14:17], v[134:137], v[228:231], v[14:17]
	v_mfma_f32_16x16x32_bf16 v[10:13], v[142:145], v[228:231], v[10:13]
	s_setprio 0
	s_setprio 1
	v_mfma_f32_16x16x32_bf16 v[54:57], v[170:173], v[186:189], v[54:57]
	v_mfma_f32_16x16x32_bf16 v[50:53], v[178:181], v[186:189], v[50:53]
	v_mfma_f32_16x16x32_bf16 v[38:41], v[170:173], v[208:211], v[38:41]
	v_mfma_f32_16x16x32_bf16 v[34:37], v[178:181], v[208:211], v[34:37]
	v_mfma_f32_16x16x32_bf16 v[22:25], v[170:173], v[216:219], v[22:25]
	v_mfma_f32_16x16x32_bf16 v[18:21], v[178:181], v[216:219], v[18:21]
	v_mfma_f32_16x16x32_bf16 v[6:9], v[170:173], v[224:227], v[6:9]
	v_mfma_f32_16x16x32_bf16 v[2:5], v[178:181], v[224:227], v[2:5]
	v_mfma_f32_16x16x32_bf16 v[54:57], v[174:177], v[202:205], v[54:57]
	v_mfma_f32_16x16x32_bf16 v[50:53], v[182:185], v[202:205], v[50:53]
	v_mfma_f32_16x16x32_bf16 v[38:41], v[174:177], v[212:215], v[38:41]
	v_mfma_f32_16x16x32_bf16 v[34:37], v[182:185], v[212:215], v[34:37]
	v_mfma_f32_16x16x32_bf16 v[22:25], v[174:177], v[220:223], v[22:25]
	v_mfma_f32_16x16x32_bf16 v[18:21], v[182:185], v[220:223], v[18:21]
	v_mfma_f32_16x16x32_bf16 v[6:9], v[174:177], v[228:231], v[6:9]
	s_barrier
	v_mfma_f32_16x16x32_bf16 v[2:5], v[182:185], v[228:231], v[2:5]
	s_setprio 0
	s_add_i32 vcc_lo, vcc_lo, 2
	s_add_u32 s84, s84, 0x100
	s_addc_u32 s85, s85, 0
	s_add_u32 s73, s73, 0x100
	s_addc_u32 s75, s75, 0
	s_cmp_gt_u32 vcc_lo, 13
	s_cbranch_scc0 .LBB0_141
	s_and_b64 vcc, exec, s[26:27]
	s_cbranch_vccz .LBB0_144
	s_barrier

; #define PG8_STAGE(bufoff, gbase, voff) do { _Pragma("unroll") for (int _i = 0; _i < 2; ++_i) \
;         __builtin_amdgcn_global_load_lds((const unsigned*)((const char*)(gbase) + (voff)[_i]), (PG8_LAS unsigned*)(lds + (bufoff) + ldsw + _i * 8192), 16, 0, 0); } while (0)
; #define PG8_LDA(dst, b, h) do { _Pragma("unroll") for (int m = 0; m < 4; ++m) _Pragma("unroll") for (int k = 0; k < 2; ++k) dst[m][k] = *(const PG8_LAS bf16x8*)(lds + PG8_SA(b, h) + aoff + m * 2048 + k * 1024); } while (0)
; #define PG8_LDB(dst, b, h) do { _Pragma("unroll") for (int n = 0; n < 2; ++n) _Pragma("unroll") for (int k = 0; k < 2; ++k) dst[n][k] = *(const PG8_LAS bf16x8*)(lds + PG8_SB(b, h) + boff + n * 2048 + k * 1024); } while (0)
; #define PG8_MMA(ai, bj, At, Bt) do { __builtin_amdgcn_s_setprio(1); _Pragma("unroll") for (int m = 0; m < 4; ++m) _Pragma("unroll") for (int n = 0; n < 2; ++n) _Pragma("unroll") for (int k = 0; k < 2; ++k) \
;         acc[ai][bj][m][n] = __builtin_amdgcn_mfma_f32_16x16x32_bf16(Bt[n][k], At[m][k], acc[ai][bj][m][n], 0, 0, 0); __builtin_amdgcn_s_setprio(0); } while (0)
; #define PG8_WAIT_V(n) asm volatile("s_waitcnt vmcnt(" #n ")" ::: "memory")
; #define PG8_WAIT_L(n) asm volatile("s_waitcnt lgkmcnt(" #n ")" ::: "memory")
; #define PG8_BAR __builtin_amdgcn_s_barrier()
; #define PG8_SCHED __builtin_amdgcn_sched_barrier(0)
; template <class Epi, class Sched, bool ALIGN_EPI = false, bool SP2 = false>
; __device__ __forceinline__ void gemm_phase(PG8_LAS unsigned char* lds, const Gemm g, const Sched& S, const Epi& E) {
;     ...
;             PG8_LDB(B0, 0, 0); PG8_LDB(B1, 0, 1); PG8_SCHED; PG8_LDA(At, 0, 0); PG8_STAGE(PG8_SA(1, 1), a1 + hstep, voffA);
;             PG8_WAIT_V(8); PG8_WAIT_L(0); PG8_BAR; PG8_MMA(0, 0, At, B0); PG8_MMA(0, 1, At, B1); PG8_BAR; PG8_SCHED;
;             PG8_LDA(At, 0, 1); PG8_STAGE(PG8_SB(0, 0), b2, voffB); PG8_STAGE(PG8_SB(0, 1), b2 + hstep, voffB); PG8_STAGE(PG8_SA(0, 0), a2, voffA);
;             PG8_WAIT_V(8); PG8_WAIT_L(0); PG8_BAR; PG8_MMA(1, 0, At, B0); PG8_MMA(1, 1, At, B1); PG8_BAR; PG8_SCHED;
.LBB0_609:
	ds_read_b128 v[98:101], v239
	ds_read_b128 v[110:113], v239 offset:1024
	ds_read_b128 v[122:125], v239 offset:2048
	ds_read_b128 v[134:137], v239 offset:3072
	ds_read_b128 v[138:141], v240
	ds_read_b128 v[142:145], v240 offset:1024
	ds_read_b128 v[146:149], v240 offset:2048
	ds_read_b128 v[150:153], v240 offset:3072
	s_add_u32 s18, s40, 0xfffc0080
	s_addc_u32 s19, s41, -1
	s_cmp_eq_u32 s62, 12
	s_cselect_b32 s43, s27, s19
	s_cselect_b32 s42, s39, s18
	s_cselect_b32 s31, s17, s61
	s_cselect_b32 s30, s59, s60
	v_lshl_add_u64 v[208:209], s[40:41], 0, v[198:199]
	s_add_i32 m0, s45, 0xc000
	ds_read_b128 v[162:165], v241
	ds_read_b128 v[166:169], v241 offset:1024
	ds_read_b128 v[170:173], v241 offset:2048
	ds_read_b128 v[174:177], v241 offset:3072
	ds_read_b128 v[178:181], v241 offset:4096
	ds_read_b128 v[182:185], v241 offset:5120
	ds_read_b128 v[186:189], v241 offset:6144
	ds_read_b128 v[204:207], v241 offset:7168
	global_load_lds_dwordx4 v[208:209], off
	v_lshl_add_u64 v[208:209], s[40:41], 0, v[200:201]
	s_add_i32 m0, s45, 0xe000
	s_nop 0
	global_load_lds_dwordx4 v[208:209], off
	s_waitcnt vmcnt(8)
	s_waitcnt lgkmcnt(0)
	s_barrier
	s_setprio 1
	s_waitcnt lgkmcnt(0)
	v_mfma_f32_16x16x32_bf16 v[158:161], v[98:101], v[162:165], v[158:161]
	v_mfma_f32_16x16x32_bf16 v[154:157], v[122:125], v[162:165], v[154:157]
	v_mfma_f32_16x16x32_bf16 v[118:121], v[98:101], v[170:173], v[118:121]
	v_mfma_f32_16x16x32_bf16 v[114:117], v[122:125], v[170:173], v[114:117]
	v_mfma_f32_16x16x32_bf16 v[94:97], v[98:101], v[178:181], v[94:97]
	v_mfma_f32_16x16x32_bf16 v[90:93], v[122:125], v[178:181], v[90:93]
	v_mfma_f32_16x16x32_bf16 v[78:81], v[98:101], v[186:189], v[78:81]
	v_mfma_f32_16x16x32_bf16 v[74:77], v[122:125], v[186:189], v[74:77]
	v_mfma_f32_16x16x32_bf16 v[158:161], v[110:113], v[166:169], v[158:161]
	v_mfma_f32_16x16x32_bf16 v[154:157], v[134:137], v[166:169], v[154:157]
	v_mfma_f32_16x16x32_bf16 v[118:121], v[110:113], v[174:177], v[118:121]
	v_mfma_f32_16x16x32_bf16 v[114:117], v[134:137], v[174:177], v[114:117]
	v_mfma_f32_16x16x32_bf16 v[94:97], v[110:113], v[182:185], v[94:97]
	v_mfma_f32_16x16x32_bf16 v[90:93], v[134:137], v[182:185], v[90:93]
	v_mfma_f32_16x16x32_bf16 v[78:81], v[110:113], v[204:207], v[78:81]
	v_mfma_f32_16x16x32_bf16 v[74:77], v[134:137], v[204:207], v[74:77]
	s_setprio 0
	s_setprio 1
	v_mfma_f32_16x16x32_bf16 v[130:133], v[138:141], v[162:165], v[130:133]
	v_mfma_f32_16x16x32_bf16 v[126:129], v[146:149], v[162:165], v[126:129]
	v_mfma_f32_16x16x32_bf16 v[106:109], v[138:141], v[170:173], v[106:109]
	v_mfma_f32_16x16x32_bf16 v[102:105], v[146:149], v[170:173], v[102:105]
	v_mfma_f32_16x16x32_bf16 v[86:89], v[138:141], v[178:181], v[86:89]
	v_mfma_f32_16x16x32_bf16 v[82:85], v[146:149], v[178:181], v[82:85]
	v_mfma_f32_16x16x32_bf16 v[70:73], v[138:141], v[186:189], v[70:73]
	v_mfma_f32_16x16x32_bf16 v[66:69], v[146:149], v[186:189], v[66:69]
	v_mfma_f32_16x16x32_bf16 v[130:133], v[142:145], v[166:169], v[130:133]
	v_mfma_f32_16x16x32_bf16 v[126:129], v[150:153], v[166:169], v[126:129]
	v_mfma_f32_16x16x32_bf16 v[106:109], v[142:145], v[174:177], v[106:109]
	v_mfma_f32_16x16x32_bf16 v[102:105], v[150:153], v[174:177], v[102:105]
	v_mfma_f32_16x16x32_bf16 v[86:89], v[142:145], v[182:185], v[86:89]
	v_mfma_f32_16x16x32_bf16 v[82:85], v[150:153], v[182:185], v[82:85]
	v_mfma_f32_16x16x32_bf16 v[70:73], v[142:145], v[204:207], v[70:73]
	s_barrier
	v_mfma_f32_16x16x32_bf16 v[66:69], v[150:153], v[204:207], v[66:69]
	s_setprio 0
	s_add_i32 s18, s56, s44
	v_lshl_add_u64 v[208:209], s[30:31], 0, v[192:193]
	s_mov_b32 m0, s18
	ds_read_b128 v[162:165], v241 offset:16384
	ds_read_b128 v[166:169], v241 offset:17408
	ds_read_b128 v[170:173], v241 offset:18432
	ds_read_b128 v[174:177], v241 offset:19456
	ds_read_b128 v[178:181], v241 offset:20480
	ds_read_b128 v[182:185], v241 offset:21504
	ds_read_b128 v[186:189], v241 offset:22528
	ds_read_b128 v[204:207], v241 offset:23552
	global_load_lds_dwordx4 v[208:209], off
	s_add_i32 m0, s18, 0x2000
	s_add_u32 s18, s30, 0x40000
	v_lshl_add_u64 v[210:211], s[30:31], 0, v[196:197]
	s_addc_u32 s19, s31, 0
	s_add_i32 s63, s57, s44
	global_load_lds_dwordx4 v[210:211], off
	v_lshl_add_u64 v[212:213], s[18:19], 0, v[192:193]
	s_mov_b32 m0, s63
	v_lshl_add_u64 v[214:215], s[42:43], 0, v[194:195]
	global_load_lds_dwordx4 v[212:213], off
	v_lshl_add_u64 v[212:213], s[18:19], 0, v[196:197]
	s_add_i32 m0, s63, 0x2000
	s_nop 0
	global_load_lds_dwordx4 v[212:213], off
	v_lshl_add_u64 v[212:213], s[42:43], 0, v[190:191]
	s_mov_b32 m0, s45
	s_nop 0
	global_load_lds_dwordx4 v[212:213], off
	s_mov_b32 m0, s46
	s_nop 0
	global_load_lds_dwordx4 v[214:215], off
	s_waitcnt vmcnt(8)
	s_waitcnt lgkmcnt(0)
	s_barrier
; #define PG8_STAGE(bufoff, gbase, voff) do { _Pragma("unroll") for (int _i = 0; _i < 2; ++_i) \
;         __builtin_amdgcn_global_load_lds((const unsigned*)((const char*)(gbase) + (voff)[_i]), (PG8_LAS unsigned*)(lds + (bufoff) + ldsw + _i * 8192), 16, 0, 0); } while (0)
; #define PG8_LDA(dst, b, h) do { _Pragma("unroll") for (int m = 0; m < 4; ++m) _Pragma("unroll") for (int k = 0; k < 2; ++k) dst[m][k] = *(const PG8_LAS bf16x8*)(lds + PG8_SA(b, h) + aoff + m * 2048 + k * 1024); } while (0)
; #define PG8_LDB(dst, b, h) do { _Pragma("unroll") for (int n = 0; n < 2; ++n) _Pragma("unroll") for (int k = 0; k < 2; ++k) dst[n][k] = *(const PG8_LAS bf16x8*)(lds + PG8_SB(b, h) + boff + n * 2048 + k * 1024); } while (0)
; #define PG8_MMA(ai, bj, At, Bt) do { __builtin_amdgcn_s_setprio(1); _Pragma("unroll") for (int m = 0; m < 4; ++m) _Pragma("unroll") for (int n = 0; n < 2; ++n) _Pragma("unroll") for (int k = 0; k < 2; ++k) \
;         acc[ai][bj][m][n] = __builtin_amdgcn_mfma_f32_16x16x32_bf16(Bt[n][k], At[m][k], acc[ai][bj][m][n], 0, 0, 0); __builtin_amdgcn_s_setprio(0); } while (0)
; #define PG8_WAIT_V(n) asm volatile("s_waitcnt vmcnt(" #n ")" ::: "memory")
; #define PG8_WAIT_L(n) asm volatile("s_waitcnt lgkmcnt(" #n ")" ::: "memory")
; #define PG8_BAR __builtin_amdgcn_s_barrier()
; #define PG8_SCHED __builtin_amdgcn_sched_barrier(0)
; template <class Epi, class Sched, bool ALIGN_EPI = false, bool SP2 = false>
; __device__ __forceinline__ void gemm_phase(PG8_LAS unsigned char* lds, const Gemm g, const Sched& S, const Epi& E) {
;     ...
;             PG8_WAIT_V(8); PG8_WAIT_L(0); PG8_BAR; PG8_MMA(1, 0, At, B0); PG8_MMA(1, 1, At, B1); PG8_BAR; PG8_SCHED;
;             PG8_LDB(B0, 1, 0); PG8_LDB(B1, 1, 1); PG8_SCHED; PG8_LDA(At, 1, 0); PG8_STAGE(PG8_SA(0, 1), a2 + hstep, voffA);
;             PG8_WAIT_V(8); PG8_WAIT_L(0); PG8_BAR; PG8_MMA(0, 0, At, B0); PG8_MMA(0, 1, At, B1); PG8_BAR; PG8_SCHED;
	s_setprio 1
	s_waitcnt lgkmcnt(0)
	v_mfma_f32_16x16x32_bf16 v[62:65], v[98:101], v[162:165], v[62:65]
	v_mfma_f32_16x16x32_bf16 v[58:61], v[122:125], v[162:165], v[58:61]
	v_mfma_f32_16x16x32_bf16 v[46:49], v[98:101], v[170:173], v[46:49]
	v_mfma_f32_16x16x32_bf16 v[42:45], v[122:125], v[170:173], v[42:45]
	v_mfma_f32_16x16x32_bf16 v[30:33], v[98:101], v[178:181], v[30:33]
	v_mfma_f32_16x16x32_bf16 v[26:29], v[122:125], v[178:181], v[26:29]
	v_mfma_f32_16x16x32_bf16 v[14:17], v[98:101], v[186:189], v[14:17]
	v_mfma_f32_16x16x32_bf16 v[10:13], v[122:125], v[186:189], v[10:13]
	v_mfma_f32_16x16x32_bf16 v[62:65], v[110:113], v[166:169], v[62:65]
	v_mfma_f32_16x16x32_bf16 v[58:61], v[134:137], v[166:169], v[58:61]
	v_mfma_f32_16x16x32_bf16 v[46:49], v[110:113], v[174:177], v[46:49]
	v_mfma_f32_16x16x32_bf16 v[42:45], v[134:137], v[174:177], v[42:45]
	v_mfma_f32_16x16x32_bf16 v[30:33], v[110:113], v[182:185], v[30:33]
	v_mfma_f32_16x16x32_bf16 v[26:29], v[134:137], v[182:185], v[26:29]
	v_mfma_f32_16x16x32_bf16 v[14:17], v[110:113], v[204:207], v[14:17]
	v_mfma_f32_16x16x32_bf16 v[10:13], v[134:137], v[204:207], v[10:13]
	s_setprio 0
	s_setprio 1
	v_mfma_f32_16x16x32_bf16 v[54:57], v[138:141], v[162:165], v[54:57]
	v_mfma_f32_16x16x32_bf16 v[50:53], v[146:149], v[162:165], v[50:53]
	v_mfma_f32_16x16x32_bf16 v[38:41], v[138:141], v[170:173], v[38:41]
	v_mfma_f32_16x16x32_bf16 v[34:37], v[146:149], v[170:173], v[34:37]
	v_mfma_f32_16x16x32_bf16 v[22:25], v[138:141], v[178:181], v[22:25]
	v_mfma_f32_16x16x32_bf16 v[18:21], v[146:149], v[178:181], v[18:21]
	v_mfma_f32_16x16x32_bf16 v[6:9], v[138:141], v[186:189], v[6:9]
	v_mfma_f32_16x16x32_bf16 v[2:5], v[146:149], v[186:189], v[2:5]
	v_mfma_f32_16x16x32_bf16 v[54:57], v[142:145], v[166:169], v[54:57]
	v_mfma_f32_16x16x32_bf16 v[50:53], v[150:153], v[166:169], v[50:53]
	v_mfma_f32_16x16x32_bf16 v[38:41], v[142:145], v[174:177], v[38:41]
	v_mfma_f32_16x16x32_bf16 v[34:37], v[150:153], v[174:177], v[34:37]
	v_mfma_f32_16x16x32_bf16 v[22:25], v[142:145], v[182:185], v[22:25]
	v_mfma_f32_16x16x32_bf16 v[18:21], v[150:153], v[182:185], v[18:21]
	v_mfma_f32_16x16x32_bf16 v[6:9], v[142:145], v[204:207], v[6:9]
	s_barrier
	v_mfma_f32_16x16x32_bf16 v[2:5], v[150:153], v[204:207], v[2:5]
	s_setprio 0
	s_add_i32 s63, 0, 0x18000
	s_add_i32 s64, 0, 0x1c000
	v_add_u32_e32 v134, s63, v237
	v_add_u32_e32 v150, s64, v237
	ds_read_b128 v[98:101], v134
	ds_read_b128 v[110:113], v134 offset:1024
	ds_read_b128 v[122:125], v134 offset:2048
	ds_read_b128 v[134:137], v134 offset:3072
	ds_read_b128 v[138:141], v150
	ds_read_b128 v[142:145], v150 offset:1024
	ds_read_b128 v[146:149], v150 offset:2048
	ds_read_b128 v[150:153], v150 offset:3072
	s_add_u32 s18, s42, 0x40000
	s_addc_u32 s19, s43, 0
	s_mov_b32 m0, s47
	v_lshl_add_u64 v[216:217], s[18:19], 0, v[190:191]
	ds_read_b128 v[162:165], v241 offset:32768
	ds_read_b128 v[166:169], v241 offset:33792
	ds_read_b128 v[170:173], v241 offset:34816
	ds_read_b128 v[174:177], v241 offset:35840
	ds_read_b128 v[178:181], v241 offset:36864
	ds_read_b128 v[182:185], v241 offset:37888
	ds_read_b128 v[186:189], v241 offset:38912
	ds_read_b128 v[204:207], v241 offset:39936
	global_load_lds_dwordx4 v[216:217], off
	v_lshl_add_u64 v[216:217], s[18:19], 0, v[194:195]
	s_mov_b32 m0, s48
	s_nop 0
	global_load_lds_dwordx4 v[216:217], off
	s_waitcnt vmcnt(8)
	s_waitcnt lgkmcnt(0)
	s_barrier
	s_setprio 1
	s_waitcnt lgkmcnt(0)
	v_mfma_f32_16x16x32_bf16 v[158:161], v[98:101], v[162:165], v[158:161]
	v_mfma_f32_16x16x32_bf16 v[154:157], v[122:125], v[162:165], v[154:157]
	v_mfma_f32_16x16x32_bf16 v[118:121], v[98:101], v[170:173], v[118:121]
	v_mfma_f32_16x16x32_bf16 v[114:117], v[122:125], v[170:173], v[114:117]
	v_mfma_f32_16x16x32_bf16 v[94:97], v[98:101], v[178:181], v[94:97]
	v_mfma_f32_16x16x32_bf16 v[90:93], v[122:125], v[178:181], v[90:93]
	v_mfma_f32_16x16x32_bf16 v[78:81], v[98:101], v[186:189], v[78:81]
	v_mfma_f32_16x16x32_bf16 v[74:77], v[122:125], v[186:189], v[74:77]
	v_mfma_f32_16x16x32_bf16 v[158:161], v[110:113], v[166:169], v[158:161]
	v_mfma_f32_16x16x32_bf16 v[154:157], v[134:137], v[166:169], v[154:157]
	v_mfma_f32_16x16x32_bf16 v[118:121], v[110:113], v[174:177], v[118:121]
	v_mfma_f32_16x16x32_bf16 v[114:117], v[134:137], v[174:177], v[114:117]
	v_mfma_f32_16x16x32_bf16 v[94:97], v[110:113], v[182:185], v[94:97]
	v_mfma_f32_16x16x32_bf16 v[90:93], v[134:137], v[182:185], v[90:93]
	v_mfma_f32_16x16x32_bf16 v[78:81], v[110:113], v[204:207], v[78:81]
	v_mfma_f32_16x16x32_bf16 v[74:77], v[134:137], v[204:207], v[74:77]
	s_setprio 0
	s_setprio 1
	v_mfma_f32_16x16x32_bf16 v[130:133], v[138:141], v[162:165], v[130:133]
	v_mfma_f32_16x16x32_bf16 v[126:129], v[146:149], v[162:165], v[126:129]
	v_mfma_f32_16x16x32_bf16 v[106:109], v[138:141], v[170:173], v[106:109]
	v_mfma_f32_16x16x32_bf16 v[102:105], v[146:149], v[170:173], v[102:105]
	v_mfma_f32_16x16x32_bf16 v[86:89], v[138:141], v[178:181], v[86:89]
	v_mfma_f32_16x16x32_bf16 v[82:85], v[146:149], v[178:181], v[82:85]
	v_mfma_f32_16x16x32_bf16 v[70:73], v[138:141], v[186:189], v[70:73]
	v_mfma_f32_16x16x32_bf16 v[66:69], v[146:149], v[186:189], v[66:69]
	v_mfma_f32_16x16x32_bf16 v[130:133], v[142:145], v[166:169], v[130:133]
	v_mfma_f32_16x16x32_bf16 v[126:129], v[150:153], v[166:169], v[126:129]
	v_mfma_f32_16x16x32_bf16 v[106:109], v[142:145], v[174:177], v[106:109]
	v_mfma_f32_16x16x32_bf16 v[102:105], v[150:153], v[174:177], v[102:105]
	v_mfma_f32_16x16x32_bf16 v[86:89], v[142:145], v[182:185], v[86:89]
	v_mfma_f32_16x16x32_bf16 v[82:85], v[150:153], v[182:185], v[82:85]
	v_mfma_f32_16x16x32_bf16 v[70:73], v[142:145], v[204:207], v[70:73]
	s_barrier
; #define PG8_STAGE(bufoff, gbase, voff) do { _Pragma("unroll") for (int _i = 0; _i < 2; ++_i) \
;         __builtin_amdgcn_global_load_lds((const unsigned*)((const char*)(gbase) + (voff)[_i]), (PG8_LAS unsigned*)(lds + (bufoff) + ldsw + _i * 8192), 16, 0, 0); } while (0)
; #define PG8_LDA(dst, b, h) do { _Pragma("unroll") for (int m = 0; m < 4; ++m) _Pragma("unroll") for (int k = 0; k < 2; ++k) dst[m][k] = *(const PG8_LAS bf16x8*)(lds + PG8_SA(b, h) + aoff + m * 2048 + k * 1024); } while (0)
; #define PG8_MMA(ai, bj, At, Bt) do { __builtin_amdgcn_s_setprio(1); _Pragma("unroll") for (int m = 0; m < 4; ++m) _Pragma("unroll") for (int n = 0; n < 2; ++n) _Pragma("unroll") for (int k = 0; k < 2; ++k) \
;         acc[ai][bj][m][n] = __builtin_amdgcn_mfma_f32_16x16x32_bf16(Bt[n][k], At[m][k], acc[ai][bj][m][n], 0, 0, 0); __builtin_amdgcn_s_setprio(0); } while (0)
; #define PG8_WAIT_V(n) asm volatile("s_waitcnt vmcnt(" #n ")" ::: "memory")
; #define PG8_WAIT_L(n) asm volatile("s_waitcnt lgkmcnt(" #n ")" ::: "memory")
; #define PG8_BAR __builtin_amdgcn_s_barrier()
; #define PG8_SCHED __builtin_amdgcn_sched_barrier(0)
; template <class Epi, class Sched, bool ALIGN_EPI = false, bool SP2 = false>
; __device__ __forceinline__ void gemm_phase(PG8_LAS unsigned char* lds, const Gemm g, const Sched& S, const Epi& E) {
;     ...
;         for (int t = 0; t < nt; t += 2) {
;             const bool last = (t == nt - 2);
;             const char* a1 = cA + (size_t)(t + 1) * kstep;
;             const char* a2 = last ? nA : cA + (size_t)(t + 2) * kstep; const char* b2 = last ? nB : cB + (size_t)(t + 2) * kstep;
;             const char* a3 = a2 + kstep; const char* b3 = b2 + kstep;
;             if (last && has_next) S.a_ready(nxt);
;     ...
;             PG8_LDA(At, 1, 1); PG8_STAGE(PG8_SB(1, 0), b3, voffB); PG8_STAGE(PG8_SB(1, 1), b3 + hstep, voffB); PG8_STAGE(PG8_SA(1, 0), a3, voffA);
;             PG8_WAIT_V(8); PG8_WAIT_L(0); PG8_BAR; PG8_MMA(1, 0, At, B0); PG8_MMA(1, 1, At, B1); PG8_BAR; PG8_SCHED;
	v_mfma_f32_16x16x32_bf16 v[66:69], v[150:153], v[204:207], v[66:69]
	s_setprio 0
	s_add_i32 s18, s63, s44
	v_lshl_add_u64 v[208:209], v[208:209], 0, s[12:13]
	s_mov_b32 m0, s18
	ds_read_b128 v[162:165], v241 offset:49152
	ds_read_b128 v[166:169], v241 offset:50176
	ds_read_b128 v[170:173], v241 offset:51200
	ds_read_b128 v[174:177], v241 offset:52224
	ds_read_b128 v[178:181], v241 offset:53248
	ds_read_b128 v[182:185], v241 offset:54272
	ds_read_b128 v[186:189], v241 offset:55296
	ds_read_b128 v[204:207], v241 offset:56320
	global_load_lds_dwordx4 v[208:209], off
	s_add_i32 m0, s18, 0x2000
	s_add_u32 s18, s30, 0x40080
	v_lshl_add_u64 v[208:209], v[210:211], 0, s[12:13]
	s_addc_u32 s19, s31, 0
	s_add_i32 s30, s64, s44
	global_load_lds_dwordx4 v[208:209], off
	v_lshl_add_u64 v[208:209], s[18:19], 0, v[192:193]
	s_mov_b32 m0, s30
	s_nop 0
	global_load_lds_dwordx4 v[208:209], off
	v_lshl_add_u64 v[208:209], s[18:19], 0, v[196:197]
	s_add_i32 m0, s30, 0x2000
	s_nop 0
	global_load_lds_dwordx4 v[208:209], off
	v_lshl_add_u64 v[208:209], v[212:213], 0, s[12:13]
	s_mov_b32 m0, s52
	s_nop 0
	global_load_lds_dwordx4 v[208:209], off
	v_lshl_add_u64 v[208:209], v[214:215], 0, s[12:13]
	s_mov_b32 m0, s53
	s_nop 0
	global_load_lds_dwordx4 v[208:209], off
	s_waitcnt vmcnt(8)
	s_waitcnt lgkmcnt(0)
	s_barrier
	s_setprio 1
	s_waitcnt lgkmcnt(0)
	v_mfma_f32_16x16x32_bf16 v[62:65], v[98:101], v[162:165], v[62:65]
	v_mfma_f32_16x16x32_bf16 v[58:61], v[122:125], v[162:165], v[58:61]
	v_mfma_f32_16x16x32_bf16 v[46:49], v[98:101], v[170:173], v[46:49]
	v_mfma_f32_16x16x32_bf16 v[42:45], v[122:125], v[170:173], v[42:45]
	v_mfma_f32_16x16x32_bf16 v[30:33], v[98:101], v[178:181], v[30:33]
	v_mfma_f32_16x16x32_bf16 v[26:29], v[122:125], v[178:181], v[26:29]
	v_mfma_f32_16x16x32_bf16 v[14:17], v[98:101], v[186:189], v[14:17]
	v_mfma_f32_16x16x32_bf16 v[10:13], v[122:125], v[186:189], v[10:13]
	v_mfma_f32_16x16x32_bf16 v[62:65], v[110:113], v[166:169], v[62:65]
	v_mfma_f32_16x16x32_bf16 v[58:61], v[134:137], v[166:169], v[58:61]
	v_mfma_f32_16x16x32_bf16 v[46:49], v[110:113], v[174:177], v[46:49]
	v_mfma_f32_16x16x32_bf16 v[42:45], v[134:137], v[174:177], v[42:45]
	v_mfma_f32_16x16x32_bf16 v[30:33], v[110:113], v[182:185], v[30:33]
	v_mfma_f32_16x16x32_bf16 v[26:29], v[134:137], v[182:185], v[26:29]
	v_mfma_f32_16x16x32_bf16 v[14:17], v[110:113], v[204:207], v[14:17]
	v_mfma_f32_16x16x32_bf16 v[10:13], v[134:137], v[204:207], v[10:13]
	s_setprio 0
	s_setprio 1
	v_mfma_f32_16x16x32_bf16 v[54:57], v[138:141], v[162:165], v[54:57]
	v_mfma_f32_16x16x32_bf16 v[50:53], v[146:149], v[162:165], v[50:53]
	v_mfma_f32_16x16x32_bf16 v[38:41], v[138:141], v[170:173], v[38:41]
	v_mfma_f32_16x16x32_bf16 v[34:37], v[146:149], v[170:173], v[34:37]
	v_mfma_f32_16x16x32_bf16 v[22:25], v[138:141], v[178:181], v[22:25]
	v_mfma_f32_16x16x32_bf16 v[18:21], v[146:149], v[178:181], v[18:21]
	v_mfma_f32_16x16x32_bf16 v[6:9], v[138:141], v[186:189], v[6:9]
	v_mfma_f32_16x16x32_bf16 v[2:5], v[146:149], v[186:189], v[2:5]
	v_mfma_f32_16x16x32_bf16 v[54:57], v[142:145], v[166:169], v[54:57]
	v_mfma_f32_16x16x32_bf16 v[50:53], v[150:153], v[166:169], v[50:53]
	v_mfma_f32_16x16x32_bf16 v[38:41], v[142:145], v[174:177], v[38:41]
	v_mfma_f32_16x16x32_bf16 v[34:37], v[150:153], v[174:177], v[34:37]
	v_mfma_f32_16x16x32_bf16 v[22:25], v[142:145], v[182:185], v[22:25]
	v_mfma_f32_16x16x32_bf16 v[18:21], v[150:153], v[182:185], v[18:21]
	v_mfma_f32_16x16x32_bf16 v[6:9], v[142:145], v[204:207], v[6:9]
	s_barrier
	v_mfma_f32_16x16x32_bf16 v[2:5], v[150:153], v[204:207], v[2:5]
	s_setprio 0
	s_add_i32 s62, s62, 2
	s_add_u32 s40, s40, 0x100
	s_addc_u32 s41, s41, 0
	s_add_u32 s60, s60, 0x100
	s_addc_u32 s61, s61, 0
	s_cmp_gt_u32 s62, 13
	s_cbranch_scc1 .Lrp_gen_p3
	s_cmp_lg_u32 s62, 12
	s_cbranch_scc1 .LBB0_609
	s_cmpk_lg_i32 s33, 0x100
	s_cbranch_scc1 .LBB0_609
	ds_read_b128 v[98:101], v239
	ds_read_b128 v[110:113], v239 offset:1024
	ds_read_b128 v[122:125], v239 offset:2048
	ds_read_b128 v[134:137], v239 offset:3072
	ds_read_b128 v[138:141], v240
	ds_read_b128 v[142:145], v240 offset:1024
	ds_read_b128 v[146:149], v240 offset:2048
	ds_read_b128 v[150:153], v240 offset:3072
	s_add_u32 s18, s40, 0xfffc0080
	s_addc_u32 s19, s41, -1
	s_cmp_eq_u32 s62, 12
	s_cselect_b32 s43, s27, s19
	s_cselect_b32 s42, s39, s18
	s_cselect_b32 s31, s17, s61
	s_cselect_b32 s30, s59, s60
	v_lshl_add_u64 v[208:209], s[40:41], 0, v[198:199]
	s_add_i32 m0, s45, 0xc000
	ds_read_b128 v[162:165], v241
	ds_read_b128 v[166:169], v241 offset:1024
	ds_read_b128 v[170:173], v241 offset:2048
	ds_read_b128 v[174:177], v241 offset:3072
	ds_read_b128 v[178:181], v241 offset:4096
	ds_read_b128 v[182:185], v241 offset:5120
	ds_read_b128 v[186:189], v241 offset:6144
	ds_read_b128 v[204:207], v241 offset:7168
	global_load_lds_dwordx4 v[208:209], off
	v_lshl_add_u64 v[208:209], s[40:41], 0, v[200:201]
	s_add_i32 m0, s45, 0xe000
	s_nop 0
	global_load_lds_dwordx4 v[208:209], off
	v_lshl_or_b32 v255, s0, 8, v238
	v_lshl_add_u32 v235, s38, 8, v1
	v_lshlrev_b32_e32 v255, 1, v255
	v_lshl_add_u32 v255, v235, 11, v255
	s_mov_b64 s[84:85], s[20:21]
	global_load_dwordx4 v[242:245], v255, s[84:85]
	global_load_dwordx4 v[208:211], v255, s[84:85] offset:256
	s_add_u32 s84, s20, 0x8000
	s_addc_u32 s85, s21, 0
	global_load_dwordx4 v[212:215], v255, s[84:85]
	global_load_dwordx4 v[216:219], v255, s[84:85] offset:256
	s_add_u32 s84, s20, 0x10000
	s_addc_u32 s85, s21, 0
	global_load_dwordx4 v[220:223], v255, s[84:85]
	global_load_dwordx4 v[224:227], v255, s[84:85] offset:256
	s_add_u32 s84, s20, 0x18000
	s_addc_u32 s85, s21, 0
	global_load_dwordx4 v[228:231], v255, s[84:85]
	global_load_dwordx4 v[232:235], v255, s[84:85] offset:256
	s_add_u32 s84, s20, 0x40000
	s_addc_u32 s85, s21, 0
	global_load_dwordx4 v[246:249], v255, s[84:85]
	global_load_dwordx4 v[250:253], v255, s[84:85] offset:256
	s_waitcnt vmcnt(18)
	s_waitcnt lgkmcnt(0)
	s_barrier
; #define PG8_STAGE(bufoff, gbase, voff) do { _Pragma("unroll") for (int _i = 0; _i < 2; ++_i) \
;         __builtin_amdgcn_global_load_lds((const unsigned*)((const char*)(gbase) + (voff)[_i]), (PG8_LAS unsigned*)(lds + (bufoff) + ldsw + _i * 8192), 16, 0, 0); } while (0)
; #define PG8_LDA(dst, b, h) do { _Pragma("unroll") for (int m = 0; m < 4; ++m) _Pragma("unroll") for (int k = 0; k < 2; ++k) dst[m][k] = *(const PG8_LAS bf16x8*)(lds + PG8_SA(b, h) + aoff + m * 2048 + k * 1024); } while (0)
; #define PG8_LDB(dst, b, h) do { _Pragma("unroll") for (int n = 0; n < 2; ++n) _Pragma("unroll") for (int k = 0; k < 2; ++k) dst[n][k] = *(const PG8_LAS bf16x8*)(lds + PG8_SB(b, h) + boff + n * 2048 + k * 1024); } while (0)
; #define PG8_MMA(ai, bj, At, Bt) do { __builtin_amdgcn_s_setprio(1); _Pragma("unroll") for (int m = 0; m < 4; ++m) _Pragma("unroll") for (int n = 0; n < 2; ++n) _Pragma("unroll") for (int k = 0; k < 2; ++k) \
;         acc[ai][bj][m][n] = __builtin_amdgcn_mfma_f32_16x16x32_bf16(Bt[n][k], At[m][k], acc[ai][bj][m][n], 0, 0, 0); __builtin_amdgcn_s_setprio(0); } while (0)
; #define PG8_WAIT_V(n) asm volatile("s_waitcnt vmcnt(" #n ")" ::: "memory")
; #define PG8_WAIT_L(n) asm volatile("s_waitcnt lgkmcnt(" #n ")" ::: "memory")
; #define PG8_BAR __builtin_amdgcn_s_barrier()
; #define PG8_SCHED __builtin_amdgcn_sched_barrier(0)
; template <class Epi, class Sched, bool ALIGN_EPI = false, bool SP2 = false>
; __device__ __forceinline__ void gemm_phase(PG8_LAS unsigned char* lds, const Gemm g, const Sched& S, const Epi& E) {
;     ...
;             PG8_LDB(B0, 0, 0); PG8_LDB(B1, 0, 1); PG8_SCHED; PG8_LDA(At, 0, 0); PG8_STAGE(PG8_SA(1, 1), a1 + hstep, voffA);
;             PG8_WAIT_V(8); PG8_WAIT_L(0); PG8_BAR; PG8_MMA(0, 0, At, B0); PG8_MMA(0, 1, At, B1); PG8_BAR; PG8_SCHED;
;             PG8_LDA(At, 0, 1); PG8_STAGE(PG8_SB(0, 0), b2, voffB); PG8_STAGE(PG8_SB(0, 1), b2 + hstep, voffB); PG8_STAGE(PG8_SA(0, 0), a2, voffA);
;             PG8_WAIT_V(8); PG8_WAIT_L(0); PG8_BAR; PG8_MMA(1, 0, At, B0); PG8_MMA(1, 1, At, B1); PG8_BAR; PG8_SCHED;
;             PG8_LDB(B0, 1, 0); PG8_LDB(B1, 1, 1); PG8_SCHED; PG8_LDA(At, 1, 0); PG8_STAGE(PG8_SA(0, 1), a2 + hstep, voffA);
;             PG8_WAIT_V(8); PG8_WAIT_L(0); PG8_BAR; PG8_MMA(0, 0, At, B0); PG8_MMA(0, 1, At, B1); PG8_BAR; PG8_SCHED;
	s_setprio 1
	s_waitcnt lgkmcnt(0)
	v_mfma_f32_16x16x32_bf16 v[158:161], v[98:101], v[162:165], v[158:161]
	v_mfma_f32_16x16x32_bf16 v[154:157], v[122:125], v[162:165], v[154:157]
	v_mfma_f32_16x16x32_bf16 v[118:121], v[98:101], v[170:173], v[118:121]
	v_mfma_f32_16x16x32_bf16 v[114:117], v[122:125], v[170:173], v[114:117]
	v_mfma_f32_16x16x32_bf16 v[94:97], v[98:101], v[178:181], v[94:97]
	v_mfma_f32_16x16x32_bf16 v[90:93], v[122:125], v[178:181], v[90:93]
	v_mfma_f32_16x16x32_bf16 v[78:81], v[98:101], v[186:189], v[78:81]
	v_mfma_f32_16x16x32_bf16 v[74:77], v[122:125], v[186:189], v[74:77]
	v_mfma_f32_16x16x32_bf16 v[158:161], v[110:113], v[166:169], v[158:161]
	v_mfma_f32_16x16x32_bf16 v[154:157], v[134:137], v[166:169], v[154:157]
	v_mfma_f32_16x16x32_bf16 v[118:121], v[110:113], v[174:177], v[118:121]
	v_mfma_f32_16x16x32_bf16 v[114:117], v[134:137], v[174:177], v[114:117]
	v_mfma_f32_16x16x32_bf16 v[94:97], v[110:113], v[182:185], v[94:97]
	v_mfma_f32_16x16x32_bf16 v[90:93], v[134:137], v[182:185], v[90:93]
	v_mfma_f32_16x16x32_bf16 v[78:81], v[110:113], v[204:207], v[78:81]
	v_mfma_f32_16x16x32_bf16 v[74:77], v[134:137], v[204:207], v[74:77]
	s_setprio 0
	s_setprio 1
	v_mfma_f32_16x16x32_bf16 v[130:133], v[138:141], v[162:165], v[130:133]
	v_mfma_f32_16x16x32_bf16 v[126:129], v[146:149], v[162:165], v[126:129]
	v_mfma_f32_16x16x32_bf16 v[106:109], v[138:141], v[170:173], v[106:109]
	v_mfma_f32_16x16x32_bf16 v[102:105], v[146:149], v[170:173], v[102:105]
	v_mfma_f32_16x16x32_bf16 v[86:89], v[138:141], v[178:181], v[86:89]
	v_mfma_f32_16x16x32_bf16 v[82:85], v[146:149], v[178:181], v[82:85]
	v_mfma_f32_16x16x32_bf16 v[70:73], v[138:141], v[186:189], v[70:73]
	v_mfma_f32_16x16x32_bf16 v[66:69], v[146:149], v[186:189], v[66:69]
	v_mfma_f32_16x16x32_bf16 v[130:133], v[142:145], v[166:169], v[130:133]
	v_mfma_f32_16x16x32_bf16 v[126:129], v[150:153], v[166:169], v[126:129]
	v_mfma_f32_16x16x32_bf16 v[106:109], v[142:145], v[174:177], v[106:109]
	v_mfma_f32_16x16x32_bf16 v[102:105], v[150:153], v[174:177], v[102:105]
	v_mfma_f32_16x16x32_bf16 v[86:89], v[142:145], v[182:185], v[86:89]
	v_mfma_f32_16x16x32_bf16 v[82:85], v[150:153], v[182:185], v[82:85]
	v_mfma_f32_16x16x32_bf16 v[70:73], v[142:145], v[204:207], v[70:73]
	s_barrier
	v_mfma_f32_16x16x32_bf16 v[66:69], v[150:153], v[204:207], v[66:69]
	s_setprio 0
	s_add_i32 s18, s56, s44
	s_mov_b32 m0, s18
	ds_read_b128 v[162:165], v241 offset:16384
	ds_read_b128 v[166:169], v241 offset:17408
	ds_read_b128 v[170:173], v241 offset:18432
	ds_read_b128 v[174:177], v241 offset:19456
	ds_read_b128 v[178:181], v241 offset:20480
	ds_read_b128 v[182:185], v241 offset:21504
	ds_read_b128 v[186:189], v241 offset:22528
	ds_read_b128 v[204:207], v241 offset:23552
	s_add_i32 m0, s18, 0x2000
	s_add_u32 s18, s30, 0x40000
	s_addc_u32 s19, s31, 0
	s_add_i32 s63, s57, s44
	s_mov_b32 m0, s63
	s_add_i32 m0, s63, 0x2000
	s_nop 0
	s_mov_b32 m0, s45
	s_nop 0
	s_mov_b32 m0, s46
	s_nop 0
	s_waitcnt vmcnt(12)
	s_waitcnt lgkmcnt(0)
	s_barrier
	s_setprio 1
	s_waitcnt lgkmcnt(0)
	v_mfma_f32_16x16x32_bf16 v[62:65], v[98:101], v[162:165], v[62:65]
	v_mfma_f32_16x16x32_bf16 v[58:61], v[122:125], v[162:165], v[58:61]
	v_mfma_f32_16x16x32_bf16 v[46:49], v[98:101], v[170:173], v[46:49]
	v_mfma_f32_16x16x32_bf16 v[42:45], v[122:125], v[170:173], v[42:45]
	v_mfma_f32_16x16x32_bf16 v[30:33], v[98:101], v[178:181], v[30:33]
	v_mfma_f32_16x16x32_bf16 v[26:29], v[122:125], v[178:181], v[26:29]
	v_mfma_f32_16x16x32_bf16 v[14:17], v[98:101], v[186:189], v[14:17]
	v_mfma_f32_16x16x32_bf16 v[10:13], v[122:125], v[186:189], v[10:13]
	v_mfma_f32_16x16x32_bf16 v[62:65], v[110:113], v[166:169], v[62:65]
	v_mfma_f32_16x16x32_bf16 v[58:61], v[134:137], v[166:169], v[58:61]
	v_mfma_f32_16x16x32_bf16 v[46:49], v[110:113], v[174:177], v[46:49]
	v_mfma_f32_16x16x32_bf16 v[42:45], v[134:137], v[174:177], v[42:45]
	v_mfma_f32_16x16x32_bf16 v[30:33], v[110:113], v[182:185], v[30:33]
	v_mfma_f32_16x16x32_bf16 v[26:29], v[134:137], v[182:185], v[26:29]
	v_mfma_f32_16x16x32_bf16 v[14:17], v[110:113], v[204:207], v[14:17]
	v_mfma_f32_16x16x32_bf16 v[10:13], v[134:137], v[204:207], v[10:13]
	s_setprio 0
	s_setprio 1
	v_mfma_f32_16x16x32_bf16 v[54:57], v[138:141], v[162:165], v[54:57]
	v_mfma_f32_16x16x32_bf16 v[50:53], v[146:149], v[162:165], v[50:53]
	v_mfma_f32_16x16x32_bf16 v[38:41], v[138:141], v[170:173], v[38:41]
	v_mfma_f32_16x16x32_bf16 v[34:37], v[146:149], v[170:173], v[34:37]
	v_mfma_f32_16x16x32_bf16 v[22:25], v[138:141], v[178:181], v[22:25]
	v_mfma_f32_16x16x32_bf16 v[18:21], v[146:149], v[178:181], v[18:21]
	v_mfma_f32_16x16x32_bf16 v[6:9], v[138:141], v[186:189], v[6:9]
	v_mfma_f32_16x16x32_bf16 v[2:5], v[146:149], v[186:189], v[2:5]
	v_mfma_f32_16x16x32_bf16 v[54:57], v[142:145], v[166:169], v[54:57]
	v_mfma_f32_16x16x32_bf16 v[50:53], v[150:153], v[166:169], v[50:53]
	v_mfma_f32_16x16x32_bf16 v[38:41], v[142:145], v[174:177], v[38:41]
	v_mfma_f32_16x16x32_bf16 v[34:37], v[150:153], v[174:177], v[34:37]
	v_mfma_f32_16x16x32_bf16 v[22:25], v[142:145], v[182:185], v[22:25]
	v_mfma_f32_16x16x32_bf16 v[18:21], v[150:153], v[182:185], v[18:21]
	v_mfma_f32_16x16x32_bf16 v[6:9], v[142:145], v[204:207], v[6:9]
	s_barrier
; #define PG8_STAGE(bufoff, gbase, voff) do { _Pragma("unroll") for (int _i = 0; _i < 2; ++_i) \
;         __builtin_amdgcn_global_load_lds((const unsigned*)((const char*)(gbase) + (voff)[_i]), (PG8_LAS unsigned*)(lds + (bufoff) + ldsw + _i * 8192), 16, 0, 0); } while (0)
; #define PG8_LDA(dst, b, h) do { _Pragma("unroll") for (int m = 0; m < 4; ++m) _Pragma("unroll") for (int k = 0; k < 2; ++k) dst[m][k] = *(const PG8_LAS bf16x8*)(lds + PG8_SA(b, h) + aoff + m * 2048 + k * 1024); } while (0)
; #define PG8_LDB(dst, b, h) do { _Pragma("unroll") for (int n = 0; n < 2; ++n) _Pragma("unroll") for (int k = 0; k < 2; ++k) dst[n][k] = *(const PG8_LAS bf16x8*)(lds + PG8_SB(b, h) + boff + n * 2048 + k * 1024); } while (0)
; #define PG8_MMA(ai, bj, At, Bt) do { __builtin_amdgcn_s_setprio(1); _Pragma("unroll") for (int m = 0; m < 4; ++m) _Pragma("unroll") for (int n = 0; n < 2; ++n) _Pragma("unroll") for (int k = 0; k < 2; ++k) \
;         acc[ai][bj][m][n] = __builtin_amdgcn_mfma_f32_16x16x32_bf16(Bt[n][k], At[m][k], acc[ai][bj][m][n], 0, 0, 0); __builtin_amdgcn_s_setprio(0); } while (0)
; #define PG8_WAIT_V(n) asm volatile("s_waitcnt vmcnt(" #n ")" ::: "memory")
; #define PG8_WAIT_L(n) asm volatile("s_waitcnt lgkmcnt(" #n ")" ::: "memory")
; #define PG8_BAR __builtin_amdgcn_s_barrier()
; #define PG8_SCHED __builtin_amdgcn_sched_barrier(0)
; template <class Epi, class Sched, bool ALIGN_EPI = false, bool SP2 = false>
; __device__ __forceinline__ void gemm_phase(PG8_LAS unsigned char* lds, const Gemm g, const Sched& S, const Epi& E) {
;     ...
;             PG8_LDB(B0, 1, 0); PG8_LDB(B1, 1, 1); PG8_SCHED; PG8_LDA(At, 1, 0); PG8_STAGE(PG8_SA(0, 1), a2 + hstep, voffA);
;             PG8_WAIT_V(8); PG8_WAIT_L(0); PG8_BAR; PG8_MMA(0, 0, At, B0); PG8_MMA(0, 1, At, B1); PG8_BAR; PG8_SCHED;
;             PG8_LDA(At, 1, 1); PG8_STAGE(PG8_SB(1, 0), b3, voffB); PG8_STAGE(PG8_SB(1, 1), b3 + hstep, voffB); PG8_STAGE(PG8_SA(1, 0), a3, voffA);
;             PG8_WAIT_V(8); PG8_WAIT_L(0); PG8_BAR; PG8_MMA(1, 0, At, B0); PG8_MMA(1, 1, At, B1); PG8_BAR; PG8_SCHED;
	v_mfma_f32_16x16x32_bf16 v[2:5], v[150:153], v[204:207], v[2:5]
	s_setprio 0
	s_add_i32 s63, 0, 0x18000
	s_add_i32 s64, 0, 0x1c000
	v_add_u32_e32 v134, s63, v237
	v_add_u32_e32 v150, s64, v237
	ds_read_b128 v[98:101], v134
	ds_read_b128 v[110:113], v134 offset:1024
	ds_read_b128 v[122:125], v134 offset:2048
	ds_read_b128 v[134:137], v134 offset:3072
	ds_read_b128 v[138:141], v150
	ds_read_b128 v[142:145], v150 offset:1024
	ds_read_b128 v[146:149], v150 offset:2048
	ds_read_b128 v[150:153], v150 offset:3072
	s_add_u32 s18, s42, 0x40000
	s_addc_u32 s19, s43, 0
	s_mov_b32 m0, s47
	ds_read_b128 v[162:165], v241 offset:32768
	ds_read_b128 v[166:169], v241 offset:33792
	ds_read_b128 v[170:173], v241 offset:34816
	ds_read_b128 v[174:177], v241 offset:35840
	ds_read_b128 v[178:181], v241 offset:36864
	ds_read_b128 v[182:185], v241 offset:37888
	ds_read_b128 v[186:189], v241 offset:38912
	ds_read_b128 v[204:207], v241 offset:39936
	s_mov_b32 m0, s48
	s_nop 0
	s_waitcnt vmcnt(10)
	s_waitcnt lgkmcnt(0)
	s_barrier
	s_setprio 1
	s_waitcnt lgkmcnt(0)
	v_mfma_f32_16x16x32_bf16 v[158:161], v[98:101], v[162:165], v[158:161]
	v_mfma_f32_16x16x32_bf16 v[154:157], v[122:125], v[162:165], v[154:157]
	v_mfma_f32_16x16x32_bf16 v[118:121], v[98:101], v[170:173], v[118:121]
	v_mfma_f32_16x16x32_bf16 v[114:117], v[122:125], v[170:173], v[114:117]
	v_mfma_f32_16x16x32_bf16 v[94:97], v[98:101], v[178:181], v[94:97]
	v_mfma_f32_16x16x32_bf16 v[90:93], v[122:125], v[178:181], v[90:93]
	v_mfma_f32_16x16x32_bf16 v[78:81], v[98:101], v[186:189], v[78:81]
	v_mfma_f32_16x16x32_bf16 v[74:77], v[122:125], v[186:189], v[74:77]
	v_mfma_f32_16x16x32_bf16 v[158:161], v[110:113], v[166:169], v[158:161]
	v_mfma_f32_16x16x32_bf16 v[154:157], v[134:137], v[166:169], v[154:157]
	v_mfma_f32_16x16x32_bf16 v[118:121], v[110:113], v[174:177], v[118:121]
	v_mfma_f32_16x16x32_bf16 v[114:117], v[134:137], v[174:177], v[114:117]
	v_mfma_f32_16x16x32_bf16 v[94:97], v[110:113], v[182:185], v[94:97]
	v_mfma_f32_16x16x32_bf16 v[90:93], v[134:137], v[182:185], v[90:93]
	v_mfma_f32_16x16x32_bf16 v[78:81], v[110:113], v[204:207], v[78:81]
	v_mfma_f32_16x16x32_bf16 v[74:77], v[134:137], v[204:207], v[74:77]
	s_setprio 0
	s_setprio 1
	v_mfma_f32_16x16x32_bf16 v[130:133], v[138:141], v[162:165], v[130:133]
	v_mfma_f32_16x16x32_bf16 v[126:129], v[146:149], v[162:165], v[126:129]
	v_mfma_f32_16x16x32_bf16 v[106:109], v[138:141], v[170:173], v[106:109]
	v_mfma_f32_16x16x32_bf16 v[102:105], v[146:149], v[170:173], v[102:105]
	v_mfma_f32_16x16x32_bf16 v[86:89], v[138:141], v[178:181], v[86:89]
	v_mfma_f32_16x16x32_bf16 v[82:85], v[146:149], v[178:181], v[82:85]
	v_mfma_f32_16x16x32_bf16 v[70:73], v[138:141], v[186:189], v[70:73]
	v_mfma_f32_16x16x32_bf16 v[66:69], v[146:149], v[186:189], v[66:69]
	v_mfma_f32_16x16x32_bf16 v[130:133], v[142:145], v[166:169], v[130:133]
	v_mfma_f32_16x16x32_bf16 v[126:129], v[150:153], v[166:169], v[126:129]
	v_mfma_f32_16x16x32_bf16 v[106:109], v[142:145], v[174:177], v[106:109]
	v_mfma_f32_16x16x32_bf16 v[102:105], v[150:153], v[174:177], v[102:105]
	v_mfma_f32_16x16x32_bf16 v[86:89], v[142:145], v[182:185], v[86:89]
	v_mfma_f32_16x16x32_bf16 v[82:85], v[150:153], v[182:185], v[82:85]
	v_mfma_f32_16x16x32_bf16 v[70:73], v[142:145], v[204:207], v[70:73]
	s_barrier
	v_mfma_f32_16x16x32_bf16 v[66:69], v[150:153], v[204:207], v[66:69]
	s_setprio 0
	s_add_i32 s18, s63, s44
	s_mov_b32 m0, s18
	ds_read_b128 v[162:165], v241 offset:49152
	ds_read_b128 v[166:169], v241 offset:50176
	ds_read_b128 v[170:173], v241 offset:51200
	ds_read_b128 v[174:177], v241 offset:52224
	ds_read_b128 v[178:181], v241 offset:53248
	ds_read_b128 v[182:185], v241 offset:54272
	ds_read_b128 v[186:189], v241 offset:55296
	ds_read_b128 v[204:207], v241 offset:56320
	s_add_i32 m0, s18, 0x2000
	s_add_u32 s18, s30, 0x40080
	s_addc_u32 s19, s31, 0
	s_add_i32 s30, s64, s44
	s_mov_b32 m0, s30
	s_nop 0
	s_add_i32 m0, s30, 0x2000
	s_nop 0
	s_mov_b32 m0, s52
	s_nop 0
	s_mov_b32 m0, s53
	s_nop 0
	s_waitcnt vmcnt(10)
	s_waitcnt lgkmcnt(0)
	s_barrier
	s_setprio 1
	s_waitcnt lgkmcnt(0)
	v_mfma_f32_16x16x32_bf16 v[62:65], v[98:101], v[162:165], v[62:65]
	v_mfma_f32_16x16x32_bf16 v[58:61], v[122:125], v[162:165], v[58:61]
	v_mfma_f32_16x16x32_bf16 v[46:49], v[98:101], v[170:173], v[46:49]
	v_mfma_f32_16x16x32_bf16 v[42:45], v[122:125], v[170:173], v[42:45]
	v_mfma_f32_16x16x32_bf16 v[30:33], v[98:101], v[178:181], v[30:33]
	v_mfma_f32_16x16x32_bf16 v[26:29], v[122:125], v[178:181], v[26:29]
	v_mfma_f32_16x16x32_bf16 v[14:17], v[98:101], v[186:189], v[14:17]
	v_mfma_f32_16x16x32_bf16 v[10:13], v[122:125], v[186:189], v[10:13]
	v_mfma_f32_16x16x32_bf16 v[62:65], v[110:113], v[166:169], v[62:65]
	v_mfma_f32_16x16x32_bf16 v[58:61], v[134:137], v[166:169], v[58:61]
	v_mfma_f32_16x16x32_bf16 v[46:49], v[110:113], v[174:177], v[46:49]
	v_mfma_f32_16x16x32_bf16 v[42:45], v[134:137], v[174:177], v[42:45]
	v_mfma_f32_16x16x32_bf16 v[30:33], v[110:113], v[182:185], v[30:33]
	v_mfma_f32_16x16x32_bf16 v[26:29], v[134:137], v[182:185], v[26:29]
	v_mfma_f32_16x16x32_bf16 v[14:17], v[110:113], v[204:207], v[14:17]
	v_mfma_f32_16x16x32_bf16 v[10:13], v[134:137], v[204:207], v[10:13]
	s_setprio 0
	s_setprio 1
	v_mfma_f32_16x16x32_bf16 v[54:57], v[138:141], v[162:165], v[54:57]
	v_mfma_f32_16x16x32_bf16 v[50:53], v[146:149], v[162:165], v[50:53]
	v_mfma_f32_16x16x32_bf16 v[38:41], v[138:141], v[170:173], v[38:41]
	v_mfma_f32_16x16x32_bf16 v[34:37], v[146:149], v[170:173], v[34:37]
	v_mfma_f32_16x16x32_bf16 v[22:25], v[138:141], v[178:181], v[22:25]
	v_mfma_f32_16x16x32_bf16 v[18:21], v[146:149], v[178:181], v[18:21]
	v_mfma_f32_16x16x32_bf16 v[6:9], v[138:141], v[186:189], v[6:9]
	v_mfma_f32_16x16x32_bf16 v[2:5], v[146:149], v[186:189], v[2:5]
	v_mfma_f32_16x16x32_bf16 v[54:57], v[142:145], v[166:169], v[54:57]
	v_mfma_f32_16x16x32_bf16 v[50:53], v[150:153], v[166:169], v[50:53]
	v_mfma_f32_16x16x32_bf16 v[38:41], v[142:145], v[174:177], v[38:41]
	v_mfma_f32_16x16x32_bf16 v[34:37], v[150:153], v[174:177], v[34:37]
	v_mfma_f32_16x16x32_bf16 v[22:25], v[142:145], v[182:185], v[22:25]
	v_mfma_f32_16x16x32_bf16 v[18:21], v[150:153], v[182:185], v[18:21]
	v_mfma_f32_16x16x32_bf16 v[6:9], v[142:145], v[204:207], v[6:9]
	s_barrier
	v_mfma_f32_16x16x32_bf16 v[2:5], v[150:153], v[204:207], v[2:5]
	s_setprio 0
	s_add_i32 s62, s62, 2
	s_add_u32 s40, s40, 0x100
	s_addc_u32 s41, s41, 0
	s_add_u32 s60, s60, 0x100
	s_addc_u32 s61, s61, 0
	s_branch .Lrp_done_p3

; #define PG8_STAGE(bufoff, gbase, voff) do { _Pragma("unroll") for (int _i = 0; _i < 2; ++_i) \
;         __builtin_amdgcn_global_load_lds((const unsigned*)((const char*)(gbase) + (voff)[_i]), (PG8_LAS unsigned*)(lds + (bufoff) + ldsw + _i * 8192), 16, 0, 0); } while (0)
; #define PG8_LDA(dst, b, h) do { _Pragma("unroll") for (int m = 0; m < 4; ++m) _Pragma("unroll") for (int k = 0; k < 2; ++k) dst[m][k] = *(const PG8_LAS bf16x8*)(lds + PG8_SA(b, h) + aoff + m * 2048 + k * 1024); } while (0)
; #define PG8_LDB(dst, b, h) do { _Pragma("unroll") for (int n = 0; n < 2; ++n) _Pragma("unroll") for (int k = 0; k < 2; ++k) dst[n][k] = *(const PG8_LAS bf16x8*)(lds + PG8_SB(b, h) + boff + n * 2048 + k * 1024); } while (0)
; #define PG8_MMA(ai, bj, At, Bt) do { __builtin_amdgcn_s_setprio(1); _Pragma("unroll") for (int m = 0; m < 4; ++m) _Pragma("unroll") for (int n = 0; n < 2; ++n) _Pragma("unroll") for (int k = 0; k < 2; ++k) \
;         acc[ai][bj][m][n] = __builtin_amdgcn_mfma_f32_16x16x32_bf16(Bt[n][k], At[m][k], acc[ai][bj][m][n], 0, 0, 0); __builtin_amdgcn_s_setprio(0); } while (0)
; #define PG8_WAIT_V(n) asm volatile("s_waitcnt vmcnt(" #n ")" ::: "memory")
; #define PG8_WAIT_L(n) asm volatile("s_waitcnt lgkmcnt(" #n ")" ::: "memory")
; #define PG8_BAR __builtin_amdgcn_s_barrier()
; #define PG8_SCHED __builtin_amdgcn_sched_barrier(0)
; template <class Epi, class Sched, bool ALIGN_EPI = false, bool SP2 = false>
; __device__ __forceinline__ void gemm_phase(PG8_LAS unsigned char* lds, const Gemm g, const Sched& S, const Epi& E) {
;     ...
;             PG8_LDB(B0, 0, 0); PG8_LDB(B1, 0, 1); PG8_SCHED; PG8_LDA(At, 0, 0); PG8_STAGE(PG8_SA(1, 1), a1 + hstep, voffA);
;             PG8_WAIT_V(8); PG8_WAIT_L(0); PG8_BAR; PG8_MMA(0, 0, At, B0); PG8_MMA(0, 1, At, B1); PG8_BAR; PG8_SCHED;
;             PG8_LDA(At, 0, 1); PG8_STAGE(PG8_SB(0, 0), b2, voffB); PG8_STAGE(PG8_SB(0, 1), b2 + hstep, voffB); PG8_STAGE(PG8_SA(0, 0), a2, voffA);
;             PG8_WAIT_V(8); PG8_WAIT_L(0); PG8_BAR; PG8_MMA(1, 0, At, B0); PG8_MMA(1, 1, At, B1); PG8_BAR; PG8_SCHED;
.LBB0_738:
	ds_read_b128 v[148:151], v195
	ds_read_b128 v[152:155], v195 offset:1024
	ds_read_b128 v[156:159], v195 offset:2048
	ds_read_b128 v[160:163], v195 offset:3072
	ds_read_b128 v[164:167], v196
	ds_read_b128 v[168:171], v196 offset:1024
	ds_read_b128 v[172:175], v196 offset:2048
	ds_read_b128 v[198:201], v196 offset:3072
	s_add_u32 s6, s4, 0xfffc0080
	s_addc_u32 s7, s5, -1
	s_cmp_eq_u32 s66, 12
	s_cselect_b32 s31, s1, s7
	s_cselect_b32 s30, s41, s6
	s_cselect_b32 s7, s39, s47
	s_cselect_b32 s6, s65, s46
	v_lshl_add_u64 v[176:177], s[4:5], 0, v[140:141]
	s_add_i32 m0, s49, 0xc000
	ds_read_b128 v[202:205], v197
	ds_read_b128 v[206:209], v197 offset:1024
	ds_read_b128 v[210:213], v197 offset:2048
	ds_read_b128 v[214:217], v197 offset:3072
	ds_read_b128 v[218:221], v197 offset:4096
	ds_read_b128 v[222:225], v197 offset:5120
	ds_read_b128 v[226:229], v197 offset:6144
	ds_read_b128 v[230:233], v197 offset:7168
	global_load_lds_dwordx4 v[176:177], off
	v_lshl_add_u64 v[176:177], s[4:5], 0, v[142:143]
	s_add_i32 m0, s49, 0xe000
	s_nop 0
	global_load_lds_dwordx4 v[176:177], off
	s_waitcnt vmcnt(8)
	s_waitcnt lgkmcnt(0)
	s_barrier
	s_setprio 1
	s_waitcnt lgkmcnt(0)
	v_mfma_f32_16x16x32_bf16 v[126:129], v[148:151], v[202:205], v[126:129]
	v_mfma_f32_16x16x32_bf16 v[118:121], v[156:159], v[202:205], v[118:121]
	v_mfma_f32_16x16x32_bf16 v[110:113], v[148:151], v[210:213], v[110:113]
	v_mfma_f32_16x16x32_bf16 v[102:105], v[156:159], v[210:213], v[102:105]
	v_mfma_f32_16x16x32_bf16 v[94:97], v[148:151], v[218:221], v[94:97]
	v_mfma_f32_16x16x32_bf16 v[86:89], v[156:159], v[218:221], v[86:89]
	v_mfma_f32_16x16x32_bf16 v[78:81], v[148:151], v[226:229], v[78:81]
	v_mfma_f32_16x16x32_bf16 v[70:73], v[156:159], v[226:229], v[70:73]
	v_mfma_f32_16x16x32_bf16 v[126:129], v[152:155], v[206:209], v[126:129]
	v_mfma_f32_16x16x32_bf16 v[118:121], v[160:163], v[206:209], v[118:121]
	v_mfma_f32_16x16x32_bf16 v[110:113], v[152:155], v[214:217], v[110:113]
	v_mfma_f32_16x16x32_bf16 v[102:105], v[160:163], v[214:217], v[102:105]
	v_mfma_f32_16x16x32_bf16 v[94:97], v[152:155], v[222:225], v[94:97]
	v_mfma_f32_16x16x32_bf16 v[86:89], v[160:163], v[222:225], v[86:89]
	v_mfma_f32_16x16x32_bf16 v[78:81], v[152:155], v[230:233], v[78:81]
	v_mfma_f32_16x16x32_bf16 v[70:73], v[160:163], v[230:233], v[70:73]
	s_setprio 0
	s_setprio 1
	v_mfma_f32_16x16x32_bf16 v[122:125], v[164:167], v[202:205], v[122:125]
	v_mfma_f32_16x16x32_bf16 v[114:117], v[172:175], v[202:205], v[114:117]
	v_mfma_f32_16x16x32_bf16 v[106:109], v[164:167], v[210:213], v[106:109]
	v_mfma_f32_16x16x32_bf16 v[98:101], v[172:175], v[210:213], v[98:101]
	v_mfma_f32_16x16x32_bf16 v[90:93], v[164:167], v[218:221], v[90:93]
	v_mfma_f32_16x16x32_bf16 v[82:85], v[172:175], v[218:221], v[82:85]
	v_mfma_f32_16x16x32_bf16 v[74:77], v[164:167], v[226:229], v[74:77]
	v_mfma_f32_16x16x32_bf16 v[66:69], v[172:175], v[226:229], v[66:69]
	v_mfma_f32_16x16x32_bf16 v[122:125], v[168:171], v[206:209], v[122:125]
	v_mfma_f32_16x16x32_bf16 v[114:117], v[198:201], v[206:209], v[114:117]
	v_mfma_f32_16x16x32_bf16 v[106:109], v[168:171], v[214:217], v[106:109]
	v_mfma_f32_16x16x32_bf16 v[98:101], v[198:201], v[214:217], v[98:101]
	v_mfma_f32_16x16x32_bf16 v[90:93], v[168:171], v[222:225], v[90:93]
	v_mfma_f32_16x16x32_bf16 v[82:85], v[198:201], v[222:225], v[82:85]
	v_mfma_f32_16x16x32_bf16 v[74:77], v[168:171], v[230:233], v[74:77]
	s_barrier
	v_mfma_f32_16x16x32_bf16 v[66:69], v[198:201], v[230:233], v[66:69]
	s_setprio 0
	s_add_i32 s18, s59, s25
	v_lshl_add_u64 v[176:177], s[6:7], 0, v[134:135]
	s_mov_b32 m0, s18
	ds_read_b128 v[202:205], v197 offset:16384
	ds_read_b128 v[206:209], v197 offset:17408
	ds_read_b128 v[210:213], v197 offset:18432
	ds_read_b128 v[214:217], v197 offset:19456
	ds_read_b128 v[218:221], v197 offset:20480
	ds_read_b128 v[222:225], v197 offset:21504
	ds_read_b128 v[226:229], v197 offset:22528
	ds_read_b128 v[230:233], v197 offset:23552
	global_load_lds_dwordx4 v[176:177], off
	s_add_i32 m0, s18, 0x2000
	s_add_u32 s18, s6, 0x40000
	v_lshl_add_u64 v[234:235], s[6:7], 0, v[130:131]
	s_addc_u32 s19, s7, 0
	s_add_i32 s67, s60, s25
	global_load_lds_dwordx4 v[234:235], off
	v_lshl_add_u64 v[238:239], s[18:19], 0, v[134:135]
	s_mov_b32 m0, s67
	v_lshl_add_u64 v[240:241], s[30:31], 0, v[132:133]
	global_load_lds_dwordx4 v[238:239], off
	v_lshl_add_u64 v[238:239], s[18:19], 0, v[130:131]
	s_add_i32 m0, s67, 0x2000
	s_nop 0
	global_load_lds_dwordx4 v[238:239], off
	v_lshl_add_u64 v[238:239], s[30:31], 0, v[136:137]
	s_mov_b32 m0, s49
	s_nop 0
	global_load_lds_dwordx4 v[238:239], off
	s_mov_b32 m0, s52
	s_nop 0
	global_load_lds_dwordx4 v[240:241], off
	s_waitcnt vmcnt(8)
	s_waitcnt lgkmcnt(0)
	s_barrier
; #define PG8_STAGE(bufoff, gbase, voff) do { _Pragma("unroll") for (int _i = 0; _i < 2; ++_i) \
;         __builtin_amdgcn_global_load_lds((const unsigned*)((const char*)(gbase) + (voff)[_i]), (PG8_LAS unsigned*)(lds + (bufoff) + ldsw + _i * 8192), 16, 0, 0); } while (0)
; #define PG8_LDA(dst, b, h) do { _Pragma("unroll") for (int m = 0; m < 4; ++m) _Pragma("unroll") for (int k = 0; k < 2; ++k) dst[m][k] = *(const PG8_LAS bf16x8*)(lds + PG8_SA(b, h) + aoff + m * 2048 + k * 1024); } while (0)
; #define PG8_LDB(dst, b, h) do { _Pragma("unroll") for (int n = 0; n < 2; ++n) _Pragma("unroll") for (int k = 0; k < 2; ++k) dst[n][k] = *(const PG8_LAS bf16x8*)(lds + PG8_SB(b, h) + boff + n * 2048 + k * 1024); } while (0)
; #define PG8_MMA(ai, bj, At, Bt) do { __builtin_amdgcn_s_setprio(1); _Pragma("unroll") for (int m = 0; m < 4; ++m) _Pragma("unroll") for (int n = 0; n < 2; ++n) _Pragma("unroll") for (int k = 0; k < 2; ++k) \
;         acc[ai][bj][m][n] = __builtin_amdgcn_mfma_f32_16x16x32_bf16(Bt[n][k], At[m][k], acc[ai][bj][m][n], 0, 0, 0); __builtin_amdgcn_s_setprio(0); } while (0)
; #define PG8_WAIT_V(n) asm volatile("s_waitcnt vmcnt(" #n ")" ::: "memory")
; template <class Epi, class Sched, bool ALIGN_EPI = false, bool SP2 = false>
; __device__ __forceinline__ void gemm_phase(PG8_LAS unsigned char* lds, const Gemm g, const Sched& S, const Epi& E) {
;     ...
;             PG8_LDB(B0, 0, 0); PG8_LDB(B1, 0, 1); PG8_SCHED; PG8_LDA(At, 0, 0); PG8_STAGE(PG8_SA(1, 1), a1 + hstep, voffA);
;             PG8_WAIT_V(8); PG8_WAIT_L(0); PG8_BAR; PG8_MMA(0, 0, At, B0); PG8_MMA(0, 1, At, B1); PG8_BAR; PG8_SCHED;
;             PG8_LDA(At, 0, 1); PG8_STAGE(PG8_SB(0, 0), b2, voffB); PG8_STAGE(PG8_SB(0, 1), b2 + hstep, voffB); PG8_STAGE(PG8_SA(0, 0), a2, voffA);
;             PG8_WAIT_V(8); PG8_WAIT_L(0); PG8_BAR; PG8_MMA(1, 0, At, B0); PG8_MMA(1, 1, At, B1); PG8_BAR; PG8_SCHED;
;             PG8_LDB(B0, 1, 0); PG8_LDB(B1, 1, 1); PG8_SCHED; PG8_LDA(At, 1, 0); PG8_STAGE(PG8_SA(0, 1), a2 + hstep, voffA);
;             PG8_WAIT_V(8); PG8_WAIT_L(0); PG8_BAR; PG8_MMA(0, 0, At, B0); PG8_MMA(0, 1, At, B1); PG8_BAR; PG8_SCHED;
;             PG8_LDA(At, 1, 1); PG8_STAGE(PG8_SB(1, 0), b3, voffB); PG8_STAGE(PG8_SB(1, 1), b3 + hstep, voffB); PG8_STAGE(PG8_SA(1, 0), a3, voffA);
;             PG8_WAIT_V(8); PG8_WAIT_L(0); PG8_BAR; PG8_MMA(1, 0, At, B0); PG8_MMA(1, 1, At, B1); PG8_BAR; PG8_SCHED;
	s_setprio 1
	s_waitcnt lgkmcnt(0)
	v_mfma_f32_16x16x32_bf16 v[62:65], v[148:151], v[202:205], v[62:65]
	v_mfma_f32_16x16x32_bf16 v[54:57], v[156:159], v[202:205], v[54:57]
	v_mfma_f32_16x16x32_bf16 v[46:49], v[148:151], v[210:213], v[46:49]
	v_mfma_f32_16x16x32_bf16 v[38:41], v[156:159], v[210:213], v[38:41]
	v_mfma_f32_16x16x32_bf16 v[30:33], v[148:151], v[218:221], v[30:33]
	v_mfma_f32_16x16x32_bf16 v[22:25], v[156:159], v[218:221], v[22:25]
	v_mfma_f32_16x16x32_bf16 v[14:17], v[148:151], v[226:229], v[14:17]
	v_mfma_f32_16x16x32_bf16 v[6:9], v[156:159], v[226:229], v[6:9]
	v_mfma_f32_16x16x32_bf16 v[62:65], v[152:155], v[206:209], v[62:65]
	v_mfma_f32_16x16x32_bf16 v[54:57], v[160:163], v[206:209], v[54:57]
	v_mfma_f32_16x16x32_bf16 v[46:49], v[152:155], v[214:217], v[46:49]
	v_mfma_f32_16x16x32_bf16 v[38:41], v[160:163], v[214:217], v[38:41]
	v_mfma_f32_16x16x32_bf16 v[30:33], v[152:155], v[222:225], v[30:33]
	v_mfma_f32_16x16x32_bf16 v[22:25], v[160:163], v[222:225], v[22:25]
	v_mfma_f32_16x16x32_bf16 v[14:17], v[152:155], v[230:233], v[14:17]
	v_mfma_f32_16x16x32_bf16 v[6:9], v[160:163], v[230:233], v[6:9]
	s_setprio 0
	s_setprio 1
	v_mfma_f32_16x16x32_bf16 v[58:61], v[164:167], v[202:205], v[58:61]
	v_mfma_f32_16x16x32_bf16 v[50:53], v[172:175], v[202:205], v[50:53]
	v_mfma_f32_16x16x32_bf16 v[42:45], v[164:167], v[210:213], v[42:45]
	v_mfma_f32_16x16x32_bf16 v[34:37], v[172:175], v[210:213], v[34:37]
	v_mfma_f32_16x16x32_bf16 v[26:29], v[164:167], v[218:221], v[26:29]
	v_mfma_f32_16x16x32_bf16 v[18:21], v[172:175], v[218:221], v[18:21]
	v_mfma_f32_16x16x32_bf16 v[10:13], v[164:167], v[226:229], v[10:13]
	v_mfma_f32_16x16x32_bf16 v[2:5], v[172:175], v[226:229], v[2:5]
	v_mfma_f32_16x16x32_bf16 v[58:61], v[168:171], v[206:209], v[58:61]
	v_mfma_f32_16x16x32_bf16 v[50:53], v[198:201], v[206:209], v[50:53]
	v_mfma_f32_16x16x32_bf16 v[42:45], v[168:171], v[214:217], v[42:45]
	v_mfma_f32_16x16x32_bf16 v[34:37], v[198:201], v[214:217], v[34:37]
	v_mfma_f32_16x16x32_bf16 v[26:29], v[168:171], v[222:225], v[26:29]
	v_mfma_f32_16x16x32_bf16 v[18:21], v[198:201], v[222:225], v[18:21]
	v_mfma_f32_16x16x32_bf16 v[10:13], v[168:171], v[230:233], v[10:13]
	s_barrier
	v_mfma_f32_16x16x32_bf16 v[2:5], v[198:201], v[230:233], v[2:5]
	s_setprio 0
	s_add_i32 s67, 0, 0x18000
	s_add_i32 s68, 0, 0x1c000
	v_add_u32_e32 v160, s67, v192
	v_add_u32_e32 v198, s68, v192
	ds_read_b128 v[148:151], v160
	ds_read_b128 v[152:155], v160 offset:1024
	ds_read_b128 v[156:159], v160 offset:2048
	ds_read_b128 v[160:163], v160 offset:3072
	ds_read_b128 v[164:167], v198
	ds_read_b128 v[168:171], v198 offset:1024
	ds_read_b128 v[172:175], v198 offset:2048
	ds_read_b128 v[198:201], v198 offset:3072
	s_add_u32 s18, s30, 0x40000
	s_addc_u32 s19, s31, 0
	s_mov_b32 m0, s53
	v_lshl_add_u64 v[242:243], s[18:19], 0, v[136:137]
	ds_read_b128 v[202:205], v197 offset:32768
	ds_read_b128 v[206:209], v197 offset:33792
	ds_read_b128 v[210:213], v197 offset:34816
	ds_read_b128 v[214:217], v197 offset:35840
	ds_read_b128 v[218:221], v197 offset:36864
	ds_read_b128 v[222:225], v197 offset:37888
	ds_read_b128 v[226:229], v197 offset:38912
	ds_read_b128 v[230:233], v197 offset:39936
	global_load_lds_dwordx4 v[242:243], off
	v_lshl_add_u64 v[242:243], s[18:19], 0, v[132:133]
	s_mov_b32 m0, s54
	s_nop 0
	global_load_lds_dwordx4 v[242:243], off
	s_waitcnt vmcnt(8)
	s_waitcnt lgkmcnt(0)
	s_barrier
	s_setprio 1
	s_waitcnt lgkmcnt(0)
	v_mfma_f32_16x16x32_bf16 v[126:129], v[148:151], v[202:205], v[126:129]
	v_mfma_f32_16x16x32_bf16 v[118:121], v[156:159], v[202:205], v[118:121]
	v_mfma_f32_16x16x32_bf16 v[110:113], v[148:151], v[210:213], v[110:113]
	v_mfma_f32_16x16x32_bf16 v[102:105], v[156:159], v[210:213], v[102:105]
	v_mfma_f32_16x16x32_bf16 v[94:97], v[148:151], v[218:221], v[94:97]
	v_mfma_f32_16x16x32_bf16 v[86:89], v[156:159], v[218:221], v[86:89]
	v_mfma_f32_16x16x32_bf16 v[78:81], v[148:151], v[226:229], v[78:81]
	v_mfma_f32_16x16x32_bf16 v[70:73], v[156:159], v[226:229], v[70:73]
	v_mfma_f32_16x16x32_bf16 v[126:129], v[152:155], v[206:209], v[126:129]
	v_mfma_f32_16x16x32_bf16 v[118:121], v[160:163], v[206:209], v[118:121]
	v_mfma_f32_16x16x32_bf16 v[110:113], v[152:155], v[214:217], v[110:113]
	v_mfma_f32_16x16x32_bf16 v[102:105], v[160:163], v[214:217], v[102:105]
	v_mfma_f32_16x16x32_bf16 v[94:97], v[152:155], v[222:225], v[94:97]
	v_mfma_f32_16x16x32_bf16 v[86:89], v[160:163], v[222:225], v[86:89]
	v_mfma_f32_16x16x32_bf16 v[78:81], v[152:155], v[230:233], v[78:81]
	v_mfma_f32_16x16x32_bf16 v[70:73], v[160:163], v[230:233], v[70:73]
	s_setprio 0
	s_setprio 1
	v_mfma_f32_16x16x32_bf16 v[122:125], v[164:167], v[202:205], v[122:125]
	v_mfma_f32_16x16x32_bf16 v[114:117], v[172:175], v[202:205], v[114:117]
	v_mfma_f32_16x16x32_bf16 v[106:109], v[164:167], v[210:213], v[106:109]
	v_mfma_f32_16x16x32_bf16 v[98:101], v[172:175], v[210:213], v[98:101]
	v_mfma_f32_16x16x32_bf16 v[90:93], v[164:167], v[218:221], v[90:93]
	v_mfma_f32_16x16x32_bf16 v[82:85], v[172:175], v[218:221], v[82:85]
	v_mfma_f32_16x16x32_bf16 v[74:77], v[164:167], v[226:229], v[74:77]
	v_mfma_f32_16x16x32_bf16 v[66:69], v[172:175], v[226:229], v[66:69]
	v_mfma_f32_16x16x32_bf16 v[122:125], v[168:171], v[206:209], v[122:125]
	v_mfma_f32_16x16x32_bf16 v[114:117], v[198:201], v[206:209], v[114:117]
	v_mfma_f32_16x16x32_bf16 v[106:109], v[168:171], v[214:217], v[106:109]
	v_mfma_f32_16x16x32_bf16 v[98:101], v[198:201], v[214:217], v[98:101]
	v_mfma_f32_16x16x32_bf16 v[90:93], v[168:171], v[222:225], v[90:93]
	v_mfma_f32_16x16x32_bf16 v[82:85], v[198:201], v[222:225], v[82:85]
	v_mfma_f32_16x16x32_bf16 v[74:77], v[168:171], v[230:233], v[74:77]
	s_barrier
; #define PG8_STAGE(bufoff, gbase, voff) do { _Pragma("unroll") for (int _i = 0; _i < 2; ++_i) \
;         __builtin_amdgcn_global_load_lds((const unsigned*)((const char*)(gbase) + (voff)[_i]), (PG8_LAS unsigned*)(lds + (bufoff) + ldsw + _i * 8192), 16, 0, 0); } while (0)
; #define PG8_LDA(dst, b, h) do { _Pragma("unroll") for (int m = 0; m < 4; ++m) _Pragma("unroll") for (int k = 0; k < 2; ++k) dst[m][k] = *(const PG8_LAS bf16x8*)(lds + PG8_SA(b, h) + aoff + m * 2048 + k * 1024); } while (0)
; #define PG8_LDB(dst, b, h) do { _Pragma("unroll") for (int n = 0; n < 2; ++n) _Pragma("unroll") for (int k = 0; k < 2; ++k) dst[n][k] = *(const PG8_LAS bf16x8*)(lds + PG8_SB(b, h) + boff + n * 2048 + k * 1024); } while (0)
; #define PG8_MMA(ai, bj, At, Bt) do { __builtin_amdgcn_s_setprio(1); _Pragma("unroll") for (int m = 0; m < 4; ++m) _Pragma("unroll") for (int n = 0; n < 2; ++n) _Pragma("unroll") for (int k = 0; k < 2; ++k) \
;         acc[ai][bj][m][n] = __builtin_amdgcn_mfma_f32_16x16x32_bf16(Bt[n][k], At[m][k], acc[ai][bj][m][n], 0, 0, 0); __builtin_amdgcn_s_setprio(0); } while (0)
; template <class Epi, class Sched, bool ALIGN_EPI = false, bool SP2 = false>
; __device__ __forceinline__ void gemm_phase(PG8_LAS unsigned char* lds, const Gemm g, const Sched& S, const Epi& E) {
;     ...
;             PG8_LDB(B0, 0, 0); PG8_LDB(B1, 0, 1); PG8_SCHED; PG8_LDA(At, 0, 0); PG8_STAGE(PG8_SA(1, 1), a1 + hstep, voffA);
;             PG8_WAIT_V(8); PG8_WAIT_L(0); PG8_BAR; PG8_MMA(0, 0, At, B0); PG8_MMA(0, 1, At, B1); PG8_BAR; PG8_SCHED;
;             PG8_LDA(At, 0, 1); PG8_STAGE(PG8_SB(0, 0), b2, voffB); PG8_STAGE(PG8_SB(0, 1), b2 + hstep, voffB); PG8_STAGE(PG8_SA(0, 0), a2, voffA);
;             PG8_WAIT_V(8); PG8_WAIT_L(0); PG8_BAR; PG8_MMA(1, 0, At, B0); PG8_MMA(1, 1, At, B1); PG8_BAR; PG8_SCHED;
;             PG8_LDB(B0, 1, 0); PG8_LDB(B1, 1, 1); PG8_SCHED; PG8_LDA(At, 1, 0); PG8_STAGE(PG8_SA(0, 1), a2 + hstep, voffA);
;             PG8_WAIT_V(8); PG8_WAIT_L(0); PG8_BAR; PG8_MMA(0, 0, At, B0); PG8_MMA(0, 1, At, B1); PG8_BAR; PG8_SCHED;
;             PG8_LDA(At, 1, 1); PG8_STAGE(PG8_SB(1, 0), b3, voffB); PG8_STAGE(PG8_SB(1, 1), b3 + hstep, voffB); PG8_STAGE(PG8_SA(1, 0), a3, voffA);
;             PG8_WAIT_V(8); PG8_WAIT_L(0); PG8_BAR; PG8_MMA(1, 0, At, B0); PG8_MMA(1, 1, At, B1); PG8_BAR; PG8_SCHED;
;     ...
;         if constexpr (ALIGN_EPI) { if (wr == 0) PG8_BAR; }
	v_mfma_f32_16x16x32_bf16 v[66:69], v[198:201], v[230:233], v[66:69]
	s_setprio 0
	s_add_i32 s18, s67, s25
	v_lshl_add_u64 v[176:177], v[176:177], 0, s[14:15]
	s_mov_b32 m0, s18
	ds_read_b128 v[202:205], v197 offset:49152
	ds_read_b128 v[206:209], v197 offset:50176
	ds_read_b128 v[210:213], v197 offset:51200
	ds_read_b128 v[214:217], v197 offset:52224
	ds_read_b128 v[218:221], v197 offset:53248
	ds_read_b128 v[222:225], v197 offset:54272
	ds_read_b128 v[226:229], v197 offset:55296
	ds_read_b128 v[230:233], v197 offset:56320
	global_load_lds_dwordx4 v[176:177], off
	s_add_i32 m0, s18, 0x2000
	s_add_u32 s6, s6, 0x40080
	v_lshl_add_u64 v[176:177], v[234:235], 0, s[14:15]
	s_addc_u32 s7, s7, 0
	s_add_i32 s18, s68, s25
	global_load_lds_dwordx4 v[176:177], off
	v_lshl_add_u64 v[176:177], s[6:7], 0, v[134:135]
	s_mov_b32 m0, s18
	s_nop 0
	global_load_lds_dwordx4 v[176:177], off
	v_lshl_add_u64 v[176:177], s[6:7], 0, v[130:131]
	s_add_i32 m0, s18, 0x2000
	s_nop 0
	global_load_lds_dwordx4 v[176:177], off
	v_lshl_add_u64 v[176:177], v[238:239], 0, s[14:15]
	s_mov_b32 m0, s56
	s_nop 0
	global_load_lds_dwordx4 v[176:177], off
	v_lshl_add_u64 v[176:177], v[240:241], 0, s[14:15]
	s_mov_b32 m0, s57
	s_nop 0
	global_load_lds_dwordx4 v[176:177], off
	s_waitcnt vmcnt(8)
	s_waitcnt lgkmcnt(0)
	s_barrier
	s_setprio 1
	s_waitcnt lgkmcnt(0)
	v_mfma_f32_16x16x32_bf16 v[62:65], v[148:151], v[202:205], v[62:65]
	v_mfma_f32_16x16x32_bf16 v[54:57], v[156:159], v[202:205], v[54:57]
	v_mfma_f32_16x16x32_bf16 v[46:49], v[148:151], v[210:213], v[46:49]
	v_mfma_f32_16x16x32_bf16 v[38:41], v[156:159], v[210:213], v[38:41]
	v_mfma_f32_16x16x32_bf16 v[30:33], v[148:151], v[218:221], v[30:33]
	v_mfma_f32_16x16x32_bf16 v[22:25], v[156:159], v[218:221], v[22:25]
	v_mfma_f32_16x16x32_bf16 v[14:17], v[148:151], v[226:229], v[14:17]
	v_mfma_f32_16x16x32_bf16 v[6:9], v[156:159], v[226:229], v[6:9]
	v_mfma_f32_16x16x32_bf16 v[62:65], v[152:155], v[206:209], v[62:65]
	v_mfma_f32_16x16x32_bf16 v[54:57], v[160:163], v[206:209], v[54:57]
	v_mfma_f32_16x16x32_bf16 v[46:49], v[152:155], v[214:217], v[46:49]
	v_mfma_f32_16x16x32_bf16 v[38:41], v[160:163], v[214:217], v[38:41]
	v_mfma_f32_16x16x32_bf16 v[30:33], v[152:155], v[222:225], v[30:33]
	v_mfma_f32_16x16x32_bf16 v[22:25], v[160:163], v[222:225], v[22:25]
	v_mfma_f32_16x16x32_bf16 v[14:17], v[152:155], v[230:233], v[14:17]
	v_mfma_f32_16x16x32_bf16 v[6:9], v[160:163], v[230:233], v[6:9]
	s_setprio 0
	s_setprio 1
	v_mfma_f32_16x16x32_bf16 v[58:61], v[164:167], v[202:205], v[58:61]
	v_mfma_f32_16x16x32_bf16 v[50:53], v[172:175], v[202:205], v[50:53]
	v_mfma_f32_16x16x32_bf16 v[42:45], v[164:167], v[210:213], v[42:45]
	v_mfma_f32_16x16x32_bf16 v[34:37], v[172:175], v[210:213], v[34:37]
	v_mfma_f32_16x16x32_bf16 v[26:29], v[164:167], v[218:221], v[26:29]
	v_mfma_f32_16x16x32_bf16 v[18:21], v[172:175], v[218:221], v[18:21]
	v_mfma_f32_16x16x32_bf16 v[10:13], v[164:167], v[226:229], v[10:13]
	v_mfma_f32_16x16x32_bf16 v[2:5], v[172:175], v[226:229], v[2:5]
	v_mfma_f32_16x16x32_bf16 v[58:61], v[168:171], v[206:209], v[58:61]
	v_mfma_f32_16x16x32_bf16 v[50:53], v[198:201], v[206:209], v[50:53]
	v_mfma_f32_16x16x32_bf16 v[42:45], v[168:171], v[214:217], v[42:45]
	v_mfma_f32_16x16x32_bf16 v[34:37], v[198:201], v[214:217], v[34:37]
	v_mfma_f32_16x16x32_bf16 v[26:29], v[168:171], v[222:225], v[26:29]
	v_mfma_f32_16x16x32_bf16 v[18:21], v[198:201], v[222:225], v[18:21]
	v_mfma_f32_16x16x32_bf16 v[10:13], v[168:171], v[230:233], v[10:13]
	s_barrier
	v_mfma_f32_16x16x32_bf16 v[2:5], v[198:201], v[230:233], v[2:5]
	s_setprio 0
	s_add_i32 s66, s66, 2
	s_add_u32 s4, s4, 0x100
	s_addc_u32 s5, s5, 0
	s_add_u32 s46, s46, 0x100
	s_addc_u32 s47, s47, 0
	s_cmp_gt_u32 s66, 13
	s_cbranch_scc0 .LBB0_738
	s_and_b64 vcc, exec, s[16:17]
	s_cbranch_vccz .LBB0_741
	s_barrier

; #define PG8_STAGE(bufoff, gbase, voff) do { _Pragma("unroll") for (int _i = 0; _i < 2; ++_i) \
;         __builtin_amdgcn_global_load_lds((const unsigned*)((const char*)(gbase) + (voff)[_i]), (PG8_LAS unsigned*)(lds + (bufoff) + ldsw + _i * 8192), 16, 0, 0); } while (0)
; #define PG8_LDA(dst, b, h) do { _Pragma("unroll") for (int m = 0; m < 4; ++m) _Pragma("unroll") for (int k = 0; k < 2; ++k) dst[m][k] = *(const PG8_LAS bf16x8*)(lds + PG8_SA(b, h) + aoff + m * 2048 + k * 1024); } while (0)
; #define PG8_LDB(dst, b, h) do { _Pragma("unroll") for (int n = 0; n < 2; ++n) _Pragma("unroll") for (int k = 0; k < 2; ++k) dst[n][k] = *(const PG8_LAS bf16x8*)(lds + PG8_SB(b, h) + boff + n * 2048 + k * 1024); } while (0)
; #define PG8_MMA(ai, bj, At, Bt) do { __builtin_amdgcn_s_setprio(1); _Pragma("unroll") for (int m = 0; m < 4; ++m) _Pragma("unroll") for (int n = 0; n < 2; ++n) _Pragma("unroll") for (int k = 0; k < 2; ++k) \
;         acc[ai][bj][m][n] = __builtin_amdgcn_mfma_f32_16x16x32_bf16(Bt[n][k], At[m][k], acc[ai][bj][m][n], 0, 0, 0); __builtin_amdgcn_s_setprio(0); } while (0)
; #define PG8_WAIT_V(n) asm volatile("s_waitcnt vmcnt(" #n ")" ::: "memory")
; template <class Epi, class Sched, bool ALIGN_EPI = false, bool SP2 = false>
; __device__ __forceinline__ void gemm_phase(PG8_LAS unsigned char* lds, const Gemm g, const Sched& S, const Epi& E) {
;     ...
;             PG8_LDB(B0, 0, 0); PG8_LDB(B1, 0, 1); PG8_SCHED; PG8_LDA(At, 0, 0); PG8_STAGE(PG8_SA(1, 1), a1 + hstep, voffA);
;             PG8_WAIT_V(8); PG8_WAIT_L(0); PG8_BAR; PG8_MMA(0, 0, At, B0); PG8_MMA(0, 1, At, B1); PG8_BAR; PG8_SCHED;
;             PG8_LDA(At, 0, 1); PG8_STAGE(PG8_SB(0, 0), b2, voffB); PG8_STAGE(PG8_SB(0, 1), b2 + hstep, voffB); PG8_STAGE(PG8_SA(0, 0), a2, voffA);
;             PG8_WAIT_V(8); PG8_WAIT_L(0); PG8_BAR; PG8_MMA(1, 0, At, B0); PG8_MMA(1, 1, At, B1); PG8_BAR; PG8_SCHED;
;             PG8_LDB(B0, 1, 0); PG8_LDB(B1, 1, 1); PG8_SCHED; PG8_LDA(At, 1, 0); PG8_STAGE(PG8_SA(0, 1), a2 + hstep, voffA);
;             PG8_WAIT_V(8); PG8_WAIT_L(0); PG8_BAR; PG8_MMA(0, 0, At, B0); PG8_MMA(0, 1, At, B1); PG8_BAR; PG8_SCHED;
;             PG8_LDA(At, 1, 1); PG8_STAGE(PG8_SB(1, 0), b3, voffB); PG8_STAGE(PG8_SB(1, 1), b3 + hstep, voffB); PG8_STAGE(PG8_SA(1, 0), a3, voffA);
;             PG8_WAIT_V(8); PG8_WAIT_L(0); PG8_BAR; PG8_MMA(1, 0, At, B0); PG8_MMA(1, 1, At, B1); PG8_BAR; PG8_SCHED;
.LBB0_777:
	ds_read_b128 v[148:151], v1
	ds_read_b128 v[152:155], v1 offset:1024
	ds_read_b128 v[156:159], v1 offset:2048
	ds_read_b128 v[160:163], v1 offset:3072
	ds_read_b128 v[164:167], v145
	ds_read_b128 v[168:171], v145 offset:1024
	ds_read_b128 v[172:175], v145 offset:2048
	ds_read_b128 v[176:179], v145 offset:3072
	s_add_i32 s76, s30, 2
	s_add_u32 s18, s46, 0x80
	s_addc_u32 s19, s47, 0
	s_cmp_eq_u32 s67, s30
	s_cselect_b32 s30, s42, s18
	s_cselect_b32 s31, s43, s19
	s_cselect_b32 s19, s45, s49
	s_cselect_b32 s18, s44, s48
	v_lshl_add_u64 v[212:213], s[46:47], 0, v[138:139]
	s_add_i32 m0, s53, 0xc000
	ds_read_b128 v[180:183], v146
	ds_read_b128 v[184:187], v146 offset:1024
	ds_read_b128 v[188:191], v146 offset:2048
	ds_read_b128 v[192:195], v146 offset:3072
	ds_read_b128 v[196:199], v146 offset:4096
	ds_read_b128 v[200:203], v146 offset:5120
	ds_read_b128 v[204:207], v146 offset:6144
	ds_read_b128 v[208:211], v146 offset:7168
	global_load_lds_dwordx4 v[212:213], off
	v_lshl_add_u64 v[212:213], s[46:47], 0, v[140:141]
	s_add_i32 m0, s53, 0xe000
	s_nop 0
	global_load_lds_dwordx4 v[212:213], off
	s_waitcnt vmcnt(8)
	s_waitcnt lgkmcnt(0)
	s_barrier
	s_setprio 1
	s_waitcnt lgkmcnt(0)
	v_mfma_f32_16x16x32_bf16 v[122:125], v[148:151], v[180:183], v[122:125]
	v_mfma_f32_16x16x32_bf16 v[126:129], v[156:159], v[180:183], v[126:129]
	v_mfma_f32_16x16x32_bf16 v[110:113], v[148:151], v[188:191], v[110:113]
	v_mfma_f32_16x16x32_bf16 v[106:109], v[156:159], v[188:191], v[106:109]
	v_mfma_f32_16x16x32_bf16 v[94:97], v[148:151], v[196:199], v[94:97]
	v_mfma_f32_16x16x32_bf16 v[90:93], v[156:159], v[196:199], v[90:93]
	v_mfma_f32_16x16x32_bf16 v[78:81], v[148:151], v[204:207], v[78:81]
	v_mfma_f32_16x16x32_bf16 v[74:77], v[156:159], v[204:207], v[74:77]
	v_mfma_f32_16x16x32_bf16 v[122:125], v[152:155], v[184:187], v[122:125]
	v_mfma_f32_16x16x32_bf16 v[126:129], v[160:163], v[184:187], v[126:129]
	v_mfma_f32_16x16x32_bf16 v[110:113], v[152:155], v[192:195], v[110:113]
	v_mfma_f32_16x16x32_bf16 v[106:109], v[160:163], v[192:195], v[106:109]
	v_mfma_f32_16x16x32_bf16 v[94:97], v[152:155], v[200:203], v[94:97]
	v_mfma_f32_16x16x32_bf16 v[90:93], v[160:163], v[200:203], v[90:93]
	v_mfma_f32_16x16x32_bf16 v[78:81], v[152:155], v[208:211], v[78:81]
	v_mfma_f32_16x16x32_bf16 v[74:77], v[160:163], v[208:211], v[74:77]
	s_setprio 0
	s_setprio 1
	v_mfma_f32_16x16x32_bf16 v[118:121], v[164:167], v[180:183], v[118:121]
	v_mfma_f32_16x16x32_bf16 v[114:117], v[172:175], v[180:183], v[114:117]
	v_mfma_f32_16x16x32_bf16 v[102:105], v[164:167], v[188:191], v[102:105]
	v_mfma_f32_16x16x32_bf16 v[98:101], v[172:175], v[188:191], v[98:101]
	v_mfma_f32_16x16x32_bf16 v[86:89], v[164:167], v[196:199], v[86:89]
	v_mfma_f32_16x16x32_bf16 v[82:85], v[172:175], v[196:199], v[82:85]
	v_mfma_f32_16x16x32_bf16 v[70:73], v[164:167], v[204:207], v[70:73]
	v_mfma_f32_16x16x32_bf16 v[66:69], v[172:175], v[204:207], v[66:69]
	v_mfma_f32_16x16x32_bf16 v[118:121], v[168:171], v[184:187], v[118:121]
	v_mfma_f32_16x16x32_bf16 v[114:117], v[176:179], v[184:187], v[114:117]
	v_mfma_f32_16x16x32_bf16 v[102:105], v[168:171], v[192:195], v[102:105]
	v_mfma_f32_16x16x32_bf16 v[98:101], v[176:179], v[192:195], v[98:101]
	v_mfma_f32_16x16x32_bf16 v[86:89], v[168:171], v[200:203], v[86:89]
	v_mfma_f32_16x16x32_bf16 v[82:85], v[176:179], v[200:203], v[82:85]
	v_mfma_f32_16x16x32_bf16 v[70:73], v[168:171], v[208:211], v[70:73]
	s_barrier
	v_mfma_f32_16x16x32_bf16 v[66:69], v[176:179], v[208:211], v[66:69]
	s_setprio 0
	s_add_i32 s77, s68, s52
	v_lshl_add_u64 v[212:213], s[18:19], 0, v[132:133]
	s_mov_b32 m0, s77
	ds_read_b128 v[180:183], v146 offset:16384
	ds_read_b128 v[184:187], v146 offset:17408
	ds_read_b128 v[188:191], v146 offset:18432
	ds_read_b128 v[192:195], v146 offset:19456
	ds_read_b128 v[196:199], v146 offset:20480
	ds_read_b128 v[200:203], v146 offset:21504
	ds_read_b128 v[204:207], v146 offset:22528
	ds_read_b128 v[208:211], v146 offset:23552
	global_load_lds_dwordx4 v[212:213], off
	s_add_i32 m0, s77, 0x2000
	v_lshl_add_u64 v[214:215], s[18:19], 0, v[136:137]
	s_add_u32 s18, s18, s4
	s_addc_u32 s19, s19, s5
	s_add_i32 s77, s69, s52
	global_load_lds_dwordx4 v[214:215], off
	v_lshl_add_u64 v[216:217], s[18:19], 0, v[132:133]
	s_mov_b32 m0, s77
	v_lshl_add_u64 v[218:219], s[18:19], 0, v[136:137]
	global_load_lds_dwordx4 v[216:217], off
	s_add_i32 m0, s77, 0x2000
	v_lshl_add_u64 v[220:221], s[30:31], 0, v[130:131]
	global_load_lds_dwordx4 v[218:219], off
	s_mov_b32 m0, s53
	v_lshl_add_u64 v[222:223], s[30:31], 0, v[134:135]
	global_load_lds_dwordx4 v[220:221], off
	s_mov_b32 m0, s54
	s_nop 0
	global_load_lds_dwordx4 v[222:223], off
	s_waitcnt vmcnt(8)
	s_waitcnt lgkmcnt(0)
	s_barrier
; #define PG8_STAGE(bufoff, gbase, voff) do { _Pragma("unroll") for (int _i = 0; _i < 2; ++_i) \
;         __builtin_amdgcn_global_load_lds((const unsigned*)((const char*)(gbase) + (voff)[_i]), (PG8_LAS unsigned*)(lds + (bufoff) + ldsw + _i * 8192), 16, 0, 0); } while (0)
; #define PG8_LDA(dst, b, h) do { _Pragma("unroll") for (int m = 0; m < 4; ++m) _Pragma("unroll") for (int k = 0; k < 2; ++k) dst[m][k] = *(const PG8_LAS bf16x8*)(lds + PG8_SA(b, h) + aoff + m * 2048 + k * 1024); } while (0)
; #define PG8_LDB(dst, b, h) do { _Pragma("unroll") for (int n = 0; n < 2; ++n) _Pragma("unroll") for (int k = 0; k < 2; ++k) dst[n][k] = *(const PG8_LAS bf16x8*)(lds + PG8_SB(b, h) + boff + n * 2048 + k * 1024); } while (0)
; #define PG8_MMA(ai, bj, At, Bt) do { __builtin_amdgcn_s_setprio(1); _Pragma("unroll") for (int m = 0; m < 4; ++m) _Pragma("unroll") for (int n = 0; n < 2; ++n) _Pragma("unroll") for (int k = 0; k < 2; ++k) \
;         acc[ai][bj][m][n] = __builtin_amdgcn_mfma_f32_16x16x32_bf16(Bt[n][k], At[m][k], acc[ai][bj][m][n], 0, 0, 0); __builtin_amdgcn_s_setprio(0); } while (0)
; #define PG8_WAIT_V(n) asm volatile("s_waitcnt vmcnt(" #n ")" ::: "memory")
; template <class Epi, class Sched, bool ALIGN_EPI = false, bool SP2 = false>
; __device__ __forceinline__ void gemm_phase(PG8_LAS unsigned char* lds, const Gemm g, const Sched& S, const Epi& E) {
;     ...
;             PG8_LDB(B0, 0, 0); PG8_LDB(B1, 0, 1); PG8_SCHED; PG8_LDA(At, 0, 0); PG8_STAGE(PG8_SA(1, 1), a1 + hstep, voffA);
;             PG8_WAIT_V(8); PG8_WAIT_L(0); PG8_BAR; PG8_MMA(0, 0, At, B0); PG8_MMA(0, 1, At, B1); PG8_BAR; PG8_SCHED;
;             PG8_LDA(At, 0, 1); PG8_STAGE(PG8_SB(0, 0), b2, voffB); PG8_STAGE(PG8_SB(0, 1), b2 + hstep, voffB); PG8_STAGE(PG8_SA(0, 0), a2, voffA);
;             PG8_WAIT_V(8); PG8_WAIT_L(0); PG8_BAR; PG8_MMA(1, 0, At, B0); PG8_MMA(1, 1, At, B1); PG8_BAR; PG8_SCHED;
;             PG8_LDB(B0, 1, 0); PG8_LDB(B1, 1, 1); PG8_SCHED; PG8_LDA(At, 1, 0); PG8_STAGE(PG8_SA(0, 1), a2 + hstep, voffA);
;             PG8_WAIT_V(8); PG8_WAIT_L(0); PG8_BAR; PG8_MMA(0, 0, At, B0); PG8_MMA(0, 1, At, B1); PG8_BAR; PG8_SCHED;
;             PG8_LDA(At, 1, 1); PG8_STAGE(PG8_SB(1, 0), b3, voffB); PG8_STAGE(PG8_SB(1, 1), b3 + hstep, voffB); PG8_STAGE(PG8_SA(1, 0), a3, voffA);
;             PG8_WAIT_V(8); PG8_WAIT_L(0); PG8_BAR; PG8_MMA(1, 0, At, B0); PG8_MMA(1, 1, At, B1); PG8_BAR; PG8_SCHED;
	s_setprio 1
	s_waitcnt lgkmcnt(0)
	v_mfma_f32_16x16x32_bf16 v[62:65], v[148:151], v[180:183], v[62:65]
	v_mfma_f32_16x16x32_bf16 v[58:61], v[156:159], v[180:183], v[58:61]
	v_mfma_f32_16x16x32_bf16 v[46:49], v[148:151], v[188:191], v[46:49]
	v_mfma_f32_16x16x32_bf16 v[42:45], v[156:159], v[188:191], v[42:45]
	v_mfma_f32_16x16x32_bf16 v[30:33], v[148:151], v[196:199], v[30:33]
	v_mfma_f32_16x16x32_bf16 v[26:29], v[156:159], v[196:199], v[26:29]
	v_mfma_f32_16x16x32_bf16 v[14:17], v[148:151], v[204:207], v[14:17]
	v_mfma_f32_16x16x32_bf16 v[10:13], v[156:159], v[204:207], v[10:13]
	v_mfma_f32_16x16x32_bf16 v[62:65], v[152:155], v[184:187], v[62:65]
	v_mfma_f32_16x16x32_bf16 v[58:61], v[160:163], v[184:187], v[58:61]
	v_mfma_f32_16x16x32_bf16 v[46:49], v[152:155], v[192:195], v[46:49]
	v_mfma_f32_16x16x32_bf16 v[42:45], v[160:163], v[192:195], v[42:45]
	v_mfma_f32_16x16x32_bf16 v[30:33], v[152:155], v[200:203], v[30:33]
	v_mfma_f32_16x16x32_bf16 v[26:29], v[160:163], v[200:203], v[26:29]
	v_mfma_f32_16x16x32_bf16 v[14:17], v[152:155], v[208:211], v[14:17]
	v_mfma_f32_16x16x32_bf16 v[10:13], v[160:163], v[208:211], v[10:13]
	s_setprio 0
	s_setprio 1
	v_mfma_f32_16x16x32_bf16 v[54:57], v[164:167], v[180:183], v[54:57]
	v_mfma_f32_16x16x32_bf16 v[50:53], v[172:175], v[180:183], v[50:53]
	v_mfma_f32_16x16x32_bf16 v[38:41], v[164:167], v[188:191], v[38:41]
	v_mfma_f32_16x16x32_bf16 v[34:37], v[172:175], v[188:191], v[34:37]
	v_mfma_f32_16x16x32_bf16 v[22:25], v[164:167], v[196:199], v[22:25]
	v_mfma_f32_16x16x32_bf16 v[18:21], v[172:175], v[196:199], v[18:21]
	v_mfma_f32_16x16x32_bf16 v[6:9], v[164:167], v[204:207], v[6:9]
	v_mfma_f32_16x16x32_bf16 v[2:5], v[172:175], v[204:207], v[2:5]
	v_mfma_f32_16x16x32_bf16 v[54:57], v[168:171], v[184:187], v[54:57]
	v_mfma_f32_16x16x32_bf16 v[50:53], v[176:179], v[184:187], v[50:53]
	v_mfma_f32_16x16x32_bf16 v[38:41], v[168:171], v[192:195], v[38:41]
	v_mfma_f32_16x16x32_bf16 v[34:37], v[176:179], v[192:195], v[34:37]
	v_mfma_f32_16x16x32_bf16 v[22:25], v[168:171], v[200:203], v[22:25]
	v_mfma_f32_16x16x32_bf16 v[18:21], v[176:179], v[200:203], v[18:21]
	v_mfma_f32_16x16x32_bf16 v[6:9], v[168:171], v[208:211], v[6:9]
	s_barrier
	v_mfma_f32_16x16x32_bf16 v[2:5], v[176:179], v[208:211], v[2:5]
	s_setprio 0
	s_add_i32 s77, 0, 0x18000
	v_add_u32_e32 v147, s77, v143
	s_add_i32 s78, 0, 0x1c000
	ds_read_b128 v[148:151], v147
	ds_read_b128 v[152:155], v147 offset:1024
	ds_read_b128 v[156:159], v147 offset:2048
	ds_read_b128 v[160:163], v147 offset:3072
	v_add_u32_e32 v147, s78, v143
	ds_read_b128 v[164:167], v147
	ds_read_b128 v[168:171], v147 offset:1024
	ds_read_b128 v[172:175], v147 offset:2048
	ds_read_b128 v[176:179], v147 offset:3072
	s_add_u32 s18, s30, s4
	s_addc_u32 s19, s31, s5
	s_mov_b32 m0, s55
	v_lshl_add_u64 v[224:225], s[18:19], 0, v[130:131]
	ds_read_b128 v[180:183], v146 offset:32768
	ds_read_b128 v[184:187], v146 offset:33792
	ds_read_b128 v[188:191], v146 offset:34816
	ds_read_b128 v[192:195], v146 offset:35840
	ds_read_b128 v[196:199], v146 offset:36864
	ds_read_b128 v[200:203], v146 offset:37888
	ds_read_b128 v[204:207], v146 offset:38912
	ds_read_b128 v[208:211], v146 offset:39936
	global_load_lds_dwordx4 v[224:225], off
	v_lshl_add_u64 v[224:225], s[18:19], 0, v[134:135]
	s_mov_b32 m0, s56
	s_nop 0
	global_load_lds_dwordx4 v[224:225], off
	s_waitcnt vmcnt(8)
	s_waitcnt lgkmcnt(0)
	s_barrier
	s_setprio 1
	s_waitcnt lgkmcnt(0)
	v_mfma_f32_16x16x32_bf16 v[122:125], v[148:151], v[180:183], v[122:125]
	v_mfma_f32_16x16x32_bf16 v[126:129], v[156:159], v[180:183], v[126:129]
	v_mfma_f32_16x16x32_bf16 v[110:113], v[148:151], v[188:191], v[110:113]
	v_mfma_f32_16x16x32_bf16 v[106:109], v[156:159], v[188:191], v[106:109]
	v_mfma_f32_16x16x32_bf16 v[94:97], v[148:151], v[196:199], v[94:97]
	v_mfma_f32_16x16x32_bf16 v[90:93], v[156:159], v[196:199], v[90:93]
	v_mfma_f32_16x16x32_bf16 v[78:81], v[148:151], v[204:207], v[78:81]
	v_mfma_f32_16x16x32_bf16 v[74:77], v[156:159], v[204:207], v[74:77]
	v_mfma_f32_16x16x32_bf16 v[122:125], v[152:155], v[184:187], v[122:125]
	v_mfma_f32_16x16x32_bf16 v[126:129], v[160:163], v[184:187], v[126:129]
	v_mfma_f32_16x16x32_bf16 v[110:113], v[152:155], v[192:195], v[110:113]
	v_mfma_f32_16x16x32_bf16 v[106:109], v[160:163], v[192:195], v[106:109]
	v_mfma_f32_16x16x32_bf16 v[94:97], v[152:155], v[200:203], v[94:97]
	v_mfma_f32_16x16x32_bf16 v[90:93], v[160:163], v[200:203], v[90:93]
	v_mfma_f32_16x16x32_bf16 v[78:81], v[152:155], v[208:211], v[78:81]
	v_mfma_f32_16x16x32_bf16 v[74:77], v[160:163], v[208:211], v[74:77]
	s_setprio 0
	s_setprio 1
	v_mfma_f32_16x16x32_bf16 v[118:121], v[164:167], v[180:183], v[118:121]
	v_mfma_f32_16x16x32_bf16 v[114:117], v[172:175], v[180:183], v[114:117]
	v_mfma_f32_16x16x32_bf16 v[102:105], v[164:167], v[188:191], v[102:105]
	v_mfma_f32_16x16x32_bf16 v[98:101], v[172:175], v[188:191], v[98:101]
	v_mfma_f32_16x16x32_bf16 v[86:89], v[164:167], v[196:199], v[86:89]
	v_mfma_f32_16x16x32_bf16 v[82:85], v[172:175], v[196:199], v[82:85]
	v_mfma_f32_16x16x32_bf16 v[70:73], v[164:167], v[204:207], v[70:73]
	v_mfma_f32_16x16x32_bf16 v[66:69], v[172:175], v[204:207], v[66:69]
	v_mfma_f32_16x16x32_bf16 v[118:121], v[168:171], v[184:187], v[118:121]
	v_mfma_f32_16x16x32_bf16 v[114:117], v[176:179], v[184:187], v[114:117]
	v_mfma_f32_16x16x32_bf16 v[102:105], v[168:171], v[192:195], v[102:105]
	v_mfma_f32_16x16x32_bf16 v[98:101], v[176:179], v[192:195], v[98:101]
	v_mfma_f32_16x16x32_bf16 v[86:89], v[168:171], v[200:203], v[86:89]
	v_mfma_f32_16x16x32_bf16 v[82:85], v[176:179], v[200:203], v[82:85]
	v_mfma_f32_16x16x32_bf16 v[70:73], v[168:171], v[208:211], v[70:73]
	s_barrier
; #define PG8_STAGE(bufoff, gbase, voff) do { _Pragma("unroll") for (int _i = 0; _i < 2; ++_i) \
;         __builtin_amdgcn_global_load_lds((const unsigned*)((const char*)(gbase) + (voff)[_i]), (PG8_LAS unsigned*)(lds + (bufoff) + ldsw + _i * 8192), 16, 0, 0); } while (0)
; #define PG8_LDA(dst, b, h) do { _Pragma("unroll") for (int m = 0; m < 4; ++m) _Pragma("unroll") for (int k = 0; k < 2; ++k) dst[m][k] = *(const PG8_LAS bf16x8*)(lds + PG8_SA(b, h) + aoff + m * 2048 + k * 1024); } while (0)
; #define PG8_LDB(dst, b, h) do { _Pragma("unroll") for (int n = 0; n < 2; ++n) _Pragma("unroll") for (int k = 0; k < 2; ++k) dst[n][k] = *(const PG8_LAS bf16x8*)(lds + PG8_SB(b, h) + boff + n * 2048 + k * 1024); } while (0)
; #define PG8_MMA(ai, bj, At, Bt) do { __builtin_amdgcn_s_setprio(1); _Pragma("unroll") for (int m = 0; m < 4; ++m) _Pragma("unroll") for (int n = 0; n < 2; ++n) _Pragma("unroll") for (int k = 0; k < 2; ++k) \
;         acc[ai][bj][m][n] = __builtin_amdgcn_mfma_f32_16x16x32_bf16(Bt[n][k], At[m][k], acc[ai][bj][m][n], 0, 0, 0); __builtin_amdgcn_s_setprio(0); } while (0)
; template <class Epi, class Sched, bool ALIGN_EPI = false, bool SP2 = false>
; __device__ __forceinline__ void gemm_phase(PG8_LAS unsigned char* lds, const Gemm g, const Sched& S, const Epi& E) {
;     ...
;         for (int t = 0; t < nt; t += 2) {
;     ...
;             PG8_LDB(B0, 0, 0); PG8_LDB(B1, 0, 1); PG8_SCHED; PG8_LDA(At, 0, 0); PG8_STAGE(PG8_SA(1, 1), a1 + hstep, voffA);
;             PG8_WAIT_V(8); PG8_WAIT_L(0); PG8_BAR; PG8_MMA(0, 0, At, B0); PG8_MMA(0, 1, At, B1); PG8_BAR; PG8_SCHED;
;             PG8_LDA(At, 0, 1); PG8_STAGE(PG8_SB(0, 0), b2, voffB); PG8_STAGE(PG8_SB(0, 1), b2 + hstep, voffB); PG8_STAGE(PG8_SA(0, 0), a2, voffA);
;             PG8_WAIT_V(8); PG8_WAIT_L(0); PG8_BAR; PG8_MMA(1, 0, At, B0); PG8_MMA(1, 1, At, B1); PG8_BAR; PG8_SCHED;
;             PG8_LDB(B0, 1, 0); PG8_LDB(B1, 1, 1); PG8_SCHED; PG8_LDA(At, 1, 0); PG8_STAGE(PG8_SA(0, 1), a2 + hstep, voffA);
;             PG8_WAIT_V(8); PG8_WAIT_L(0); PG8_BAR; PG8_MMA(0, 0, At, B0); PG8_MMA(0, 1, At, B1); PG8_BAR; PG8_SCHED;
;             PG8_LDA(At, 1, 1); PG8_STAGE(PG8_SB(1, 0), b3, voffB); PG8_STAGE(PG8_SB(1, 1), b3 + hstep, voffB); PG8_STAGE(PG8_SA(1, 0), a3, voffA);
;             PG8_WAIT_V(8); PG8_WAIT_L(0); PG8_BAR; PG8_MMA(1, 0, At, B0); PG8_MMA(1, 1, At, B1); PG8_BAR; PG8_SCHED;
	v_mfma_f32_16x16x32_bf16 v[66:69], v[176:179], v[208:211], v[66:69]
	s_setprio 0
	s_add_i32 s18, s77, s52
	v_lshl_add_u64 v[212:213], v[212:213], 0, s[14:15]
	s_mov_b32 m0, s18
	ds_read_b128 v[180:183], v146 offset:49152
	ds_read_b128 v[184:187], v146 offset:50176
	ds_read_b128 v[188:191], v146 offset:51200
	ds_read_b128 v[192:195], v146 offset:52224
	ds_read_b128 v[196:199], v146 offset:53248
	ds_read_b128 v[200:203], v146 offset:54272
	ds_read_b128 v[204:207], v146 offset:55296
	ds_read_b128 v[208:211], v146 offset:56320
	global_load_lds_dwordx4 v[212:213], off
	v_lshl_add_u64 v[212:213], v[214:215], 0, s[14:15]
	s_add_i32 m0, s18, 0x2000
	s_add_i32 s18, s78, s52
	global_load_lds_dwordx4 v[212:213], off
	v_lshl_add_u64 v[212:213], v[216:217], 0, s[14:15]
	s_mov_b32 m0, s18
	s_nop 0
	global_load_lds_dwordx4 v[212:213], off
	v_lshl_add_u64 v[212:213], v[218:219], 0, s[14:15]
	s_add_i32 m0, s18, 0x2000
	s_nop 0
	global_load_lds_dwordx4 v[212:213], off
	v_lshl_add_u64 v[212:213], v[220:221], 0, s[14:15]
	s_mov_b32 m0, s58
	s_nop 0
	global_load_lds_dwordx4 v[212:213], off
	v_lshl_add_u64 v[212:213], v[222:223], 0, s[14:15]
	s_mov_b32 m0, s59
	s_nop 0
	global_load_lds_dwordx4 v[212:213], off
	s_waitcnt vmcnt(8)
	s_waitcnt lgkmcnt(0)
	s_barrier
	s_setprio 1
	s_waitcnt lgkmcnt(0)
	v_mfma_f32_16x16x32_bf16 v[62:65], v[148:151], v[180:183], v[62:65]
	v_mfma_f32_16x16x32_bf16 v[58:61], v[156:159], v[180:183], v[58:61]
	v_mfma_f32_16x16x32_bf16 v[46:49], v[148:151], v[188:191], v[46:49]
	v_mfma_f32_16x16x32_bf16 v[42:45], v[156:159], v[188:191], v[42:45]
	v_mfma_f32_16x16x32_bf16 v[30:33], v[148:151], v[196:199], v[30:33]
	v_mfma_f32_16x16x32_bf16 v[26:29], v[156:159], v[196:199], v[26:29]
	v_mfma_f32_16x16x32_bf16 v[14:17], v[148:151], v[204:207], v[14:17]
	v_mfma_f32_16x16x32_bf16 v[10:13], v[156:159], v[204:207], v[10:13]
	v_mfma_f32_16x16x32_bf16 v[62:65], v[152:155], v[184:187], v[62:65]
	v_mfma_f32_16x16x32_bf16 v[58:61], v[160:163], v[184:187], v[58:61]
	v_mfma_f32_16x16x32_bf16 v[46:49], v[152:155], v[192:195], v[46:49]
	v_mfma_f32_16x16x32_bf16 v[42:45], v[160:163], v[192:195], v[42:45]
	v_mfma_f32_16x16x32_bf16 v[30:33], v[152:155], v[200:203], v[30:33]
	v_mfma_f32_16x16x32_bf16 v[26:29], v[160:163], v[200:203], v[26:29]
	v_mfma_f32_16x16x32_bf16 v[14:17], v[152:155], v[208:211], v[14:17]
	v_mfma_f32_16x16x32_bf16 v[10:13], v[160:163], v[208:211], v[10:13]
	s_setprio 0
	s_setprio 1
	v_mfma_f32_16x16x32_bf16 v[54:57], v[164:167], v[180:183], v[54:57]
	v_mfma_f32_16x16x32_bf16 v[50:53], v[172:175], v[180:183], v[50:53]
	v_mfma_f32_16x16x32_bf16 v[38:41], v[164:167], v[188:191], v[38:41]
	v_mfma_f32_16x16x32_bf16 v[34:37], v[172:175], v[188:191], v[34:37]
	v_mfma_f32_16x16x32_bf16 v[22:25], v[164:167], v[196:199], v[22:25]
	v_mfma_f32_16x16x32_bf16 v[18:21], v[172:175], v[196:199], v[18:21]
	v_mfma_f32_16x16x32_bf16 v[6:9], v[164:167], v[204:207], v[6:9]
	v_mfma_f32_16x16x32_bf16 v[2:5], v[172:175], v[204:207], v[2:5]
	v_mfma_f32_16x16x32_bf16 v[54:57], v[168:171], v[184:187], v[54:57]
	v_mfma_f32_16x16x32_bf16 v[50:53], v[176:179], v[184:187], v[50:53]
	v_mfma_f32_16x16x32_bf16 v[38:41], v[168:171], v[192:195], v[38:41]
	v_mfma_f32_16x16x32_bf16 v[34:37], v[176:179], v[192:195], v[34:37]
	v_mfma_f32_16x16x32_bf16 v[22:25], v[168:171], v[200:203], v[22:25]
	v_mfma_f32_16x16x32_bf16 v[18:21], v[176:179], v[200:203], v[18:21]
	v_mfma_f32_16x16x32_bf16 v[6:9], v[168:171], v[208:211], v[6:9]
	s_barrier
	v_mfma_f32_16x16x32_bf16 v[2:5], v[176:179], v[208:211], v[2:5]
	s_setprio 0
	s_add_u32 s46, s46, 0x100
	s_addc_u32 s47, s47, 0
	s_add_u32 s48, s48, 0x100
	s_addc_u32 s49, s49, 0
	s_cmp_ge_i32 s76, s60
	s_mov_b32 s30, s76
	s_cbranch_scc0 .LBB0_777

; #define PG8_STAGE(bufoff, gbase, voff) do { _Pragma("unroll") for (int _i = 0; _i < 2; ++_i) \
;         __builtin_amdgcn_global_load_lds((const unsigned*)((const char*)(gbase) + (voff)[_i]), (PG8_LAS unsigned*)(lds + (bufoff) + ldsw + _i * 8192), 16, 0, 0); } while (0)
; #define PG8_LDA(dst, b, h) do { _Pragma("unroll") for (int m = 0; m < 4; ++m) _Pragma("unroll") for (int k = 0; k < 2; ++k) dst[m][k] = *(const PG8_LAS bf16x8*)(lds + PG8_SA(b, h) + aoff + m * 2048 + k * 1024); } while (0)
; #define PG8_LDB(dst, b, h) do { _Pragma("unroll") for (int n = 0; n < 2; ++n) _Pragma("unroll") for (int k = 0; k < 2; ++k) dst[n][k] = *(const PG8_LAS bf16x8*)(lds + PG8_SB(b, h) + boff + n * 2048 + k * 1024); } while (0)
; #define PG8_MMA(ai, bj, At, Bt) do { __builtin_amdgcn_s_setprio(1); _Pragma("unroll") for (int m = 0; m < 4; ++m) _Pragma("unroll") for (int n = 0; n < 2; ++n) _Pragma("unroll") for (int k = 0; k < 2; ++k) \
;         acc[ai][bj][m][n] = __builtin_amdgcn_mfma_f32_16x16x32_bf16(Bt[n][k], At[m][k], acc[ai][bj][m][n], 0, 0, 0); __builtin_amdgcn_s_setprio(0); } while (0)
; #define PG8_WAIT_V(n) asm volatile("s_waitcnt vmcnt(" #n ")" ::: "memory")
; template <class Epi, class Sched, bool ALIGN_EPI = false, bool SP2 = false>
; __device__ __forceinline__ void gemm_phase(PG8_LAS unsigned char* lds, const Gemm g, const Sched& S, const Epi& E) {
;     ...
;             PG8_LDB(B0, 0, 0); PG8_LDB(B1, 0, 1); PG8_SCHED; PG8_LDA(At, 0, 0); PG8_STAGE(PG8_SA(1, 1), a1 + hstep, voffA);
;             PG8_WAIT_V(8); PG8_WAIT_L(0); PG8_BAR; PG8_MMA(0, 0, At, B0); PG8_MMA(0, 1, At, B1); PG8_BAR; PG8_SCHED;
;             PG8_LDA(At, 0, 1); PG8_STAGE(PG8_SB(0, 0), b2, voffB); PG8_STAGE(PG8_SB(0, 1), b2 + hstep, voffB); PG8_STAGE(PG8_SA(0, 0), a2, voffA);
;             PG8_WAIT_V(8); PG8_WAIT_L(0); PG8_BAR; PG8_MMA(1, 0, At, B0); PG8_MMA(1, 1, At, B1); PG8_BAR; PG8_SCHED;
;             PG8_LDB(B0, 1, 0); PG8_LDB(B1, 1, 1); PG8_SCHED; PG8_LDA(At, 1, 0); PG8_STAGE(PG8_SA(0, 1), a2 + hstep, voffA);
;             PG8_WAIT_V(8); PG8_WAIT_L(0); PG8_BAR; PG8_MMA(0, 0, At, B0); PG8_MMA(0, 1, At, B1); PG8_BAR; PG8_SCHED;
;             PG8_LDA(At, 1, 1); PG8_STAGE(PG8_SB(1, 0), b3, voffB); PG8_STAGE(PG8_SB(1, 1), b3 + hstep, voffB); PG8_STAGE(PG8_SA(1, 0), a3, voffA);
;             PG8_WAIT_V(8); PG8_WAIT_L(0); PG8_BAR; PG8_MMA(1, 0, At, B0); PG8_MMA(1, 1, At, B1); PG8_BAR; PG8_SCHED;
.LBB0_892:
	ds_read_b128 v[98:101], v239
	ds_read_b128 v[110:113], v239 offset:1024
	ds_read_b128 v[122:125], v239 offset:2048
	ds_read_b128 v[134:137], v239 offset:3072
	ds_read_b128 v[138:141], v240
	ds_read_b128 v[142:145], v240 offset:1024
	ds_read_b128 v[146:149], v240 offset:2048
	ds_read_b128 v[150:153], v240 offset:3072
	s_add_u32 s18, s34, 0xfff50080
	s_addc_u32 s19, s35, -1
	s_cmp_eq_u32 s60, 40
	s_cselect_b32 s39, s1, s19
	s_cselect_b32 s38, s0, s18
	s_cselect_b32 s37, s31, s59
	s_cselect_b32 s36, s30, s58
	v_lshl_add_u64 v[208:209], s[34:35], 0, v[198:199]
	s_add_i32 m0, s41, 0xc000
	ds_read_b128 v[162:165], v241
	ds_read_b128 v[166:169], v241 offset:1024
	ds_read_b128 v[170:173], v241 offset:2048
	ds_read_b128 v[174:177], v241 offset:3072
	ds_read_b128 v[178:181], v241 offset:4096
	ds_read_b128 v[182:185], v241 offset:5120
	ds_read_b128 v[186:189], v241 offset:6144
	ds_read_b128 v[204:207], v241 offset:7168
	global_load_lds_dwordx4 v[208:209], off
	v_lshl_add_u64 v[208:209], s[34:35], 0, v[200:201]
	s_add_i32 m0, s41, 0xe000
	s_nop 0
	global_load_lds_dwordx4 v[208:209], off
	s_waitcnt vmcnt(8)
	s_waitcnt lgkmcnt(0)
	s_barrier
	s_setprio 1
	s_waitcnt lgkmcnt(0)
	v_mfma_f32_16x16x32_bf16 v[158:161], v[98:101], v[162:165], v[158:161]
	v_mfma_f32_16x16x32_bf16 v[154:157], v[122:125], v[162:165], v[154:157]
	v_mfma_f32_16x16x32_bf16 v[118:121], v[98:101], v[170:173], v[118:121]
	v_mfma_f32_16x16x32_bf16 v[114:117], v[122:125], v[170:173], v[114:117]
	v_mfma_f32_16x16x32_bf16 v[94:97], v[98:101], v[178:181], v[94:97]
	v_mfma_f32_16x16x32_bf16 v[90:93], v[122:125], v[178:181], v[90:93]
	v_mfma_f32_16x16x32_bf16 v[78:81], v[98:101], v[186:189], v[78:81]
	v_mfma_f32_16x16x32_bf16 v[74:77], v[122:125], v[186:189], v[74:77]
	v_mfma_f32_16x16x32_bf16 v[158:161], v[110:113], v[166:169], v[158:161]
	v_mfma_f32_16x16x32_bf16 v[154:157], v[134:137], v[166:169], v[154:157]
	v_mfma_f32_16x16x32_bf16 v[118:121], v[110:113], v[174:177], v[118:121]
	v_mfma_f32_16x16x32_bf16 v[114:117], v[134:137], v[174:177], v[114:117]
	v_mfma_f32_16x16x32_bf16 v[94:97], v[110:113], v[182:185], v[94:97]
	v_mfma_f32_16x16x32_bf16 v[90:93], v[134:137], v[182:185], v[90:93]
	v_mfma_f32_16x16x32_bf16 v[78:81], v[110:113], v[204:207], v[78:81]
	v_mfma_f32_16x16x32_bf16 v[74:77], v[134:137], v[204:207], v[74:77]
	s_setprio 0
	s_setprio 1
	v_mfma_f32_16x16x32_bf16 v[130:133], v[138:141], v[162:165], v[130:133]
	v_mfma_f32_16x16x32_bf16 v[126:129], v[146:149], v[162:165], v[126:129]
	v_mfma_f32_16x16x32_bf16 v[106:109], v[138:141], v[170:173], v[106:109]
	v_mfma_f32_16x16x32_bf16 v[102:105], v[146:149], v[170:173], v[102:105]
	v_mfma_f32_16x16x32_bf16 v[86:89], v[138:141], v[178:181], v[86:89]
	v_mfma_f32_16x16x32_bf16 v[82:85], v[146:149], v[178:181], v[82:85]
	v_mfma_f32_16x16x32_bf16 v[70:73], v[138:141], v[186:189], v[70:73]
	v_mfma_f32_16x16x32_bf16 v[66:69], v[146:149], v[186:189], v[66:69]
	v_mfma_f32_16x16x32_bf16 v[130:133], v[142:145], v[166:169], v[130:133]
	v_mfma_f32_16x16x32_bf16 v[126:129], v[150:153], v[166:169], v[126:129]
	v_mfma_f32_16x16x32_bf16 v[106:109], v[142:145], v[174:177], v[106:109]
	v_mfma_f32_16x16x32_bf16 v[102:105], v[150:153], v[174:177], v[102:105]
	v_mfma_f32_16x16x32_bf16 v[86:89], v[142:145], v[182:185], v[86:89]
	v_mfma_f32_16x16x32_bf16 v[82:85], v[150:153], v[182:185], v[82:85]
	v_mfma_f32_16x16x32_bf16 v[70:73], v[142:145], v[204:207], v[70:73]
	s_barrier
	v_mfma_f32_16x16x32_bf16 v[66:69], v[150:153], v[204:207], v[66:69]
	s_setprio 0
	s_add_i32 s18, s52, s40
	v_lshl_add_u64 v[208:209], s[36:37], 0, v[192:193]
	s_mov_b32 m0, s18
	ds_read_b128 v[162:165], v241 offset:16384
	ds_read_b128 v[166:169], v241 offset:17408
	ds_read_b128 v[170:173], v241 offset:18432
	ds_read_b128 v[174:177], v241 offset:19456
	ds_read_b128 v[178:181], v241 offset:20480
	ds_read_b128 v[182:185], v241 offset:21504
	ds_read_b128 v[186:189], v241 offset:22528
	ds_read_b128 v[204:207], v241 offset:23552
	global_load_lds_dwordx4 v[208:209], off
	s_add_i32 m0, s18, 0x2000
	s_add_u32 s18, s36, 0xb0000
	v_lshl_add_u64 v[210:211], s[36:37], 0, v[196:197]
	s_addc_u32 s19, s37, 0
	s_add_i32 s61, s53, s40
	global_load_lds_dwordx4 v[210:211], off
	v_lshl_add_u64 v[212:213], s[18:19], 0, v[192:193]
	s_mov_b32 m0, s61
	v_lshl_add_u64 v[214:215], s[38:39], 0, v[194:195]
	global_load_lds_dwordx4 v[212:213], off
	v_lshl_add_u64 v[212:213], s[18:19], 0, v[196:197]
	s_add_i32 m0, s61, 0x2000
	s_nop 0
	global_load_lds_dwordx4 v[212:213], off
	v_lshl_add_u64 v[212:213], s[38:39], 0, v[190:191]
	s_mov_b32 m0, s41
	s_nop 0
	global_load_lds_dwordx4 v[212:213], off
	s_mov_b32 m0, s42
	s_nop 0
	global_load_lds_dwordx4 v[214:215], off
	s_waitcnt vmcnt(8)
	s_waitcnt lgkmcnt(0)
	s_barrier
; #define PG8_STAGE(bufoff, gbase, voff) do { _Pragma("unroll") for (int _i = 0; _i < 2; ++_i) \
;         __builtin_amdgcn_global_load_lds((const unsigned*)((const char*)(gbase) + (voff)[_i]), (PG8_LAS unsigned*)(lds + (bufoff) + ldsw + _i * 8192), 16, 0, 0); } while (0)
; #define PG8_LDA(dst, b, h) do { _Pragma("unroll") for (int m = 0; m < 4; ++m) _Pragma("unroll") for (int k = 0; k < 2; ++k) dst[m][k] = *(const PG8_LAS bf16x8*)(lds + PG8_SA(b, h) + aoff + m * 2048 + k * 1024); } while (0)
; #define PG8_LDB(dst, b, h) do { _Pragma("unroll") for (int n = 0; n < 2; ++n) _Pragma("unroll") for (int k = 0; k < 2; ++k) dst[n][k] = *(const PG8_LAS bf16x8*)(lds + PG8_SB(b, h) + boff + n * 2048 + k * 1024); } while (0)
; #define PG8_MMA(ai, bj, At, Bt) do { __builtin_amdgcn_s_setprio(1); _Pragma("unroll") for (int m = 0; m < 4; ++m) _Pragma("unroll") for (int n = 0; n < 2; ++n) _Pragma("unroll") for (int k = 0; k < 2; ++k) \
;         acc[ai][bj][m][n] = __builtin_amdgcn_mfma_f32_16x16x32_bf16(Bt[n][k], At[m][k], acc[ai][bj][m][n], 0, 0, 0); __builtin_amdgcn_s_setprio(0); } while (0)
; #define PG8_WAIT_V(n) asm volatile("s_waitcnt vmcnt(" #n ")" ::: "memory")
; template <class Epi, class Sched, bool ALIGN_EPI = false, bool SP2 = false>
; __device__ __forceinline__ void gemm_phase(PG8_LAS unsigned char* lds, const Gemm g, const Sched& S, const Epi& E) {
;     ...
;             PG8_LDB(B0, 0, 0); PG8_LDB(B1, 0, 1); PG8_SCHED; PG8_LDA(At, 0, 0); PG8_STAGE(PG8_SA(1, 1), a1 + hstep, voffA);
;             PG8_WAIT_V(8); PG8_WAIT_L(0); PG8_BAR; PG8_MMA(0, 0, At, B0); PG8_MMA(0, 1, At, B1); PG8_BAR; PG8_SCHED;
;             PG8_LDA(At, 0, 1); PG8_STAGE(PG8_SB(0, 0), b2, voffB); PG8_STAGE(PG8_SB(0, 1), b2 + hstep, voffB); PG8_STAGE(PG8_SA(0, 0), a2, voffA);
;             PG8_WAIT_V(8); PG8_WAIT_L(0); PG8_BAR; PG8_MMA(1, 0, At, B0); PG8_MMA(1, 1, At, B1); PG8_BAR; PG8_SCHED;
;             PG8_LDB(B0, 1, 0); PG8_LDB(B1, 1, 1); PG8_SCHED; PG8_LDA(At, 1, 0); PG8_STAGE(PG8_SA(0, 1), a2 + hstep, voffA);
;             PG8_WAIT_V(8); PG8_WAIT_L(0); PG8_BAR; PG8_MMA(0, 0, At, B0); PG8_MMA(0, 1, At, B1); PG8_BAR; PG8_SCHED;
;             PG8_LDA(At, 1, 1); PG8_STAGE(PG8_SB(1, 0), b3, voffB); PG8_STAGE(PG8_SB(1, 1), b3 + hstep, voffB); PG8_STAGE(PG8_SA(1, 0), a3, voffA);
;             PG8_WAIT_V(8); PG8_WAIT_L(0); PG8_BAR; PG8_MMA(1, 0, At, B0); PG8_MMA(1, 1, At, B1); PG8_BAR; PG8_SCHED;
	s_setprio 1
	s_waitcnt lgkmcnt(0)
	v_mfma_f32_16x16x32_bf16 v[62:65], v[98:101], v[162:165], v[62:65]
	v_mfma_f32_16x16x32_bf16 v[58:61], v[122:125], v[162:165], v[58:61]
	v_mfma_f32_16x16x32_bf16 v[46:49], v[98:101], v[170:173], v[46:49]
	v_mfma_f32_16x16x32_bf16 v[42:45], v[122:125], v[170:173], v[42:45]
	v_mfma_f32_16x16x32_bf16 v[30:33], v[98:101], v[178:181], v[30:33]
	v_mfma_f32_16x16x32_bf16 v[26:29], v[122:125], v[178:181], v[26:29]
	v_mfma_f32_16x16x32_bf16 v[14:17], v[98:101], v[186:189], v[14:17]
	v_mfma_f32_16x16x32_bf16 v[10:13], v[122:125], v[186:189], v[10:13]
	v_mfma_f32_16x16x32_bf16 v[62:65], v[110:113], v[166:169], v[62:65]
	v_mfma_f32_16x16x32_bf16 v[58:61], v[134:137], v[166:169], v[58:61]
	v_mfma_f32_16x16x32_bf16 v[46:49], v[110:113], v[174:177], v[46:49]
	v_mfma_f32_16x16x32_bf16 v[42:45], v[134:137], v[174:177], v[42:45]
	v_mfma_f32_16x16x32_bf16 v[30:33], v[110:113], v[182:185], v[30:33]
	v_mfma_f32_16x16x32_bf16 v[26:29], v[134:137], v[182:185], v[26:29]
	v_mfma_f32_16x16x32_bf16 v[14:17], v[110:113], v[204:207], v[14:17]
	v_mfma_f32_16x16x32_bf16 v[10:13], v[134:137], v[204:207], v[10:13]
	s_setprio 0
	s_setprio 1
	v_mfma_f32_16x16x32_bf16 v[54:57], v[138:141], v[162:165], v[54:57]
	v_mfma_f32_16x16x32_bf16 v[50:53], v[146:149], v[162:165], v[50:53]
	v_mfma_f32_16x16x32_bf16 v[38:41], v[138:141], v[170:173], v[38:41]
	v_mfma_f32_16x16x32_bf16 v[34:37], v[146:149], v[170:173], v[34:37]
	v_mfma_f32_16x16x32_bf16 v[22:25], v[138:141], v[178:181], v[22:25]
	v_mfma_f32_16x16x32_bf16 v[18:21], v[146:149], v[178:181], v[18:21]
	v_mfma_f32_16x16x32_bf16 v[6:9], v[138:141], v[186:189], v[6:9]
	v_mfma_f32_16x16x32_bf16 v[2:5], v[146:149], v[186:189], v[2:5]
	v_mfma_f32_16x16x32_bf16 v[54:57], v[142:145], v[166:169], v[54:57]
	v_mfma_f32_16x16x32_bf16 v[50:53], v[150:153], v[166:169], v[50:53]
	v_mfma_f32_16x16x32_bf16 v[38:41], v[142:145], v[174:177], v[38:41]
	v_mfma_f32_16x16x32_bf16 v[34:37], v[150:153], v[174:177], v[34:37]
	v_mfma_f32_16x16x32_bf16 v[22:25], v[142:145], v[182:185], v[22:25]
	v_mfma_f32_16x16x32_bf16 v[18:21], v[150:153], v[182:185], v[18:21]
	v_mfma_f32_16x16x32_bf16 v[6:9], v[142:145], v[204:207], v[6:9]
	s_barrier
	v_mfma_f32_16x16x32_bf16 v[2:5], v[150:153], v[204:207], v[2:5]
	s_setprio 0
	s_add_i32 s61, 0, 0x18000
	s_add_i32 s62, 0, 0x1c000
	v_add_u32_e32 v134, s61, v237
	v_add_u32_e32 v150, s62, v237
	ds_read_b128 v[98:101], v134
	ds_read_b128 v[110:113], v134 offset:1024
	ds_read_b128 v[122:125], v134 offset:2048
	ds_read_b128 v[134:137], v134 offset:3072
	ds_read_b128 v[138:141], v150
	ds_read_b128 v[142:145], v150 offset:1024
	ds_read_b128 v[146:149], v150 offset:2048
	ds_read_b128 v[150:153], v150 offset:3072
	s_add_u32 s18, s38, 0xb0000
	s_addc_u32 s19, s39, 0
	s_mov_b32 m0, s43
	v_lshl_add_u64 v[216:217], s[18:19], 0, v[190:191]
	ds_read_b128 v[162:165], v241 offset:32768
	ds_read_b128 v[166:169], v241 offset:33792
	ds_read_b128 v[170:173], v241 offset:34816
	ds_read_b128 v[174:177], v241 offset:35840
	ds_read_b128 v[178:181], v241 offset:36864
	ds_read_b128 v[182:185], v241 offset:37888
	ds_read_b128 v[186:189], v241 offset:38912
	ds_read_b128 v[204:207], v241 offset:39936
	global_load_lds_dwordx4 v[216:217], off
	v_lshl_add_u64 v[216:217], s[18:19], 0, v[194:195]
	s_mov_b32 m0, s44
	s_nop 0
	global_load_lds_dwordx4 v[216:217], off
	s_waitcnt vmcnt(8)
	s_waitcnt lgkmcnt(0)
	s_barrier
	s_setprio 1
	s_waitcnt lgkmcnt(0)
	v_mfma_f32_16x16x32_bf16 v[158:161], v[98:101], v[162:165], v[158:161]
	v_mfma_f32_16x16x32_bf16 v[154:157], v[122:125], v[162:165], v[154:157]
	v_mfma_f32_16x16x32_bf16 v[118:121], v[98:101], v[170:173], v[118:121]
	v_mfma_f32_16x16x32_bf16 v[114:117], v[122:125], v[170:173], v[114:117]
	v_mfma_f32_16x16x32_bf16 v[94:97], v[98:101], v[178:181], v[94:97]
	v_mfma_f32_16x16x32_bf16 v[90:93], v[122:125], v[178:181], v[90:93]
	v_mfma_f32_16x16x32_bf16 v[78:81], v[98:101], v[186:189], v[78:81]
	v_mfma_f32_16x16x32_bf16 v[74:77], v[122:125], v[186:189], v[74:77]
	v_mfma_f32_16x16x32_bf16 v[158:161], v[110:113], v[166:169], v[158:161]
	v_mfma_f32_16x16x32_bf16 v[154:157], v[134:137], v[166:169], v[154:157]
	v_mfma_f32_16x16x32_bf16 v[118:121], v[110:113], v[174:177], v[118:121]
	v_mfma_f32_16x16x32_bf16 v[114:117], v[134:137], v[174:177], v[114:117]
	v_mfma_f32_16x16x32_bf16 v[94:97], v[110:113], v[182:185], v[94:97]
	v_mfma_f32_16x16x32_bf16 v[90:93], v[134:137], v[182:185], v[90:93]
	v_mfma_f32_16x16x32_bf16 v[78:81], v[110:113], v[204:207], v[78:81]
	v_mfma_f32_16x16x32_bf16 v[74:77], v[134:137], v[204:207], v[74:77]
	s_setprio 0
	s_setprio 1
	v_mfma_f32_16x16x32_bf16 v[130:133], v[138:141], v[162:165], v[130:133]
	v_mfma_f32_16x16x32_bf16 v[126:129], v[146:149], v[162:165], v[126:129]
	v_mfma_f32_16x16x32_bf16 v[106:109], v[138:141], v[170:173], v[106:109]
	v_mfma_f32_16x16x32_bf16 v[102:105], v[146:149], v[170:173], v[102:105]
	v_mfma_f32_16x16x32_bf16 v[86:89], v[138:141], v[178:181], v[86:89]
	v_mfma_f32_16x16x32_bf16 v[82:85], v[146:149], v[178:181], v[82:85]
	v_mfma_f32_16x16x32_bf16 v[70:73], v[138:141], v[186:189], v[70:73]
	v_mfma_f32_16x16x32_bf16 v[66:69], v[146:149], v[186:189], v[66:69]
	v_mfma_f32_16x16x32_bf16 v[130:133], v[142:145], v[166:169], v[130:133]
	v_mfma_f32_16x16x32_bf16 v[126:129], v[150:153], v[166:169], v[126:129]
	v_mfma_f32_16x16x32_bf16 v[106:109], v[142:145], v[174:177], v[106:109]
	v_mfma_f32_16x16x32_bf16 v[102:105], v[150:153], v[174:177], v[102:105]
	v_mfma_f32_16x16x32_bf16 v[86:89], v[142:145], v[182:185], v[86:89]
	v_mfma_f32_16x16x32_bf16 v[82:85], v[150:153], v[182:185], v[82:85]
	v_mfma_f32_16x16x32_bf16 v[70:73], v[142:145], v[204:207], v[70:73]
	s_barrier
; #define PG8_STAGE(bufoff, gbase, voff) do { _Pragma("unroll") for (int _i = 0; _i < 2; ++_i) \
;         __builtin_amdgcn_global_load_lds((const unsigned*)((const char*)(gbase) + (voff)[_i]), (PG8_LAS unsigned*)(lds + (bufoff) + ldsw + _i * 8192), 16, 0, 0); } while (0)
; #define PG8_LDA(dst, b, h) do { _Pragma("unroll") for (int m = 0; m < 4; ++m) _Pragma("unroll") for (int k = 0; k < 2; ++k) dst[m][k] = *(const PG8_LAS bf16x8*)(lds + PG8_SA(b, h) + aoff + m * 2048 + k * 1024); } while (0)
; #define PG8_LDB(dst, b, h) do { _Pragma("unroll") for (int n = 0; n < 2; ++n) _Pragma("unroll") for (int k = 0; k < 2; ++k) dst[n][k] = *(const PG8_LAS bf16x8*)(lds + PG8_SB(b, h) + boff + n * 2048 + k * 1024); } while (0)
; #define PG8_WAIT_V(n) asm volatile("s_waitcnt vmcnt(" #n ")" ::: "memory")
; #define PG8_WAIT_L(n) asm volatile("s_waitcnt lgkmcnt(" #n ")" ::: "memory")
;     __device__ __forceinline__ void operator()(const f32x4 (&acc)[2][2][4][2], const Unit& u, int wr, int wc, int fr, int fq) const {
;     ...
;                 for (int bj = 0; bj < 2; ++bj) bva[ai][m][bj] = *(const u32x4*)(Xb + (size_t)(row0 + ai * HALF + m * 16) * DM + col0 + bj * HALF);
; template <class Epi, class Sched, bool ALIGN_EPI = false, bool SP2 = false>
; __device__ __forceinline__ void gemm_phase(PG8_LAS unsigned char* lds, const Gemm g, const Sched& S, const Epi& E) {
;     ...
;             PG8_LDB(B0, 0, 0); PG8_LDB(B1, 0, 1); PG8_SCHED; PG8_LDA(At, 0, 0); PG8_STAGE(PG8_SA(1, 1), a1 + hstep, voffA);
;             PG8_WAIT_V(8); PG8_WAIT_L(0); PG8_BAR; PG8_MMA(0, 0, At, B0); PG8_MMA(0, 1, At, B1); PG8_BAR; PG8_SCHED;
;             PG8_LDA(At, 0, 1); PG8_STAGE(PG8_SB(0, 0), b2, voffB); PG8_STAGE(PG8_SB(0, 1), b2 + hstep, voffB); PG8_STAGE(PG8_SA(0, 0), a2, voffA);
;             PG8_WAIT_V(8); PG8_WAIT_L(0); PG8_BAR; PG8_MMA(1, 0, At, B0); PG8_MMA(1, 1, At, B1); PG8_BAR; PG8_SCHED;
;             PG8_LDB(B0, 1, 0); PG8_LDB(B1, 1, 1); PG8_SCHED; PG8_LDA(At, 1, 0); PG8_STAGE(PG8_SA(0, 1), a2 + hstep, voffA);
;             PG8_WAIT_V(8); PG8_WAIT_L(0); PG8_BAR; PG8_MMA(0, 0, At, B0); PG8_MMA(0, 1, At, B1); PG8_BAR; PG8_SCHED;
;             PG8_LDA(At, 1, 1); PG8_STAGE(PG8_SB(1, 0), b3, voffB); PG8_STAGE(PG8_SB(1, 1), b3 + hstep, voffB); PG8_STAGE(PG8_SA(1, 0), a3, voffA);
;             PG8_WAIT_V(8); PG8_WAIT_L(0); PG8_BAR; PG8_MMA(1, 0, At, B0); PG8_MMA(1, 1, At, B1); PG8_BAR; PG8_SCHED;
	v_mfma_f32_16x16x32_bf16 v[66:69], v[150:153], v[204:207], v[66:69]
	s_setprio 0
	s_add_i32 s18, s61, s40
	v_lshl_add_u64 v[208:209], v[208:209], 0, s[16:17]
	s_mov_b32 m0, s18
	ds_read_b128 v[162:165], v241 offset:49152
	ds_read_b128 v[166:169], v241 offset:50176
	ds_read_b128 v[170:173], v241 offset:51200
	ds_read_b128 v[174:177], v241 offset:52224
	ds_read_b128 v[178:181], v241 offset:53248
	ds_read_b128 v[182:185], v241 offset:54272
	ds_read_b128 v[186:189], v241 offset:55296
	ds_read_b128 v[204:207], v241 offset:56320
	global_load_lds_dwordx4 v[208:209], off
	s_add_i32 m0, s18, 0x2000
	s_add_u32 s18, s36, 0xb0080
	v_lshl_add_u64 v[208:209], v[210:211], 0, s[16:17]
	s_addc_u32 s19, s37, 0
	s_add_i32 s36, s62, s40
	global_load_lds_dwordx4 v[208:209], off
	v_lshl_add_u64 v[208:209], s[18:19], 0, v[192:193]
	s_mov_b32 m0, s36
	s_nop 0
	global_load_lds_dwordx4 v[208:209], off
	v_lshl_add_u64 v[208:209], s[18:19], 0, v[196:197]
	s_add_i32 m0, s36, 0x2000
	s_nop 0
	global_load_lds_dwordx4 v[208:209], off
	v_lshl_add_u64 v[208:209], v[212:213], 0, s[16:17]
	s_mov_b32 m0, s46
	s_nop 0
	global_load_lds_dwordx4 v[208:209], off
	v_lshl_add_u64 v[208:209], v[214:215], 0, s[16:17]
	s_mov_b32 m0, s47
	s_nop 0
	global_load_lds_dwordx4 v[208:209], off
	s_waitcnt vmcnt(8)
	s_waitcnt lgkmcnt(0)
	s_barrier
	s_setprio 1
	s_waitcnt lgkmcnt(0)
	v_mfma_f32_16x16x32_bf16 v[62:65], v[98:101], v[162:165], v[62:65]
	v_mfma_f32_16x16x32_bf16 v[58:61], v[122:125], v[162:165], v[58:61]
	v_mfma_f32_16x16x32_bf16 v[46:49], v[98:101], v[170:173], v[46:49]
	v_mfma_f32_16x16x32_bf16 v[42:45], v[122:125], v[170:173], v[42:45]
	v_mfma_f32_16x16x32_bf16 v[30:33], v[98:101], v[178:181], v[30:33]
	v_mfma_f32_16x16x32_bf16 v[26:29], v[122:125], v[178:181], v[26:29]
	v_mfma_f32_16x16x32_bf16 v[14:17], v[98:101], v[186:189], v[14:17]
	v_mfma_f32_16x16x32_bf16 v[10:13], v[122:125], v[186:189], v[10:13]
	v_mfma_f32_16x16x32_bf16 v[62:65], v[110:113], v[166:169], v[62:65]
	v_mfma_f32_16x16x32_bf16 v[58:61], v[134:137], v[166:169], v[58:61]
	v_mfma_f32_16x16x32_bf16 v[46:49], v[110:113], v[174:177], v[46:49]
	v_mfma_f32_16x16x32_bf16 v[42:45], v[134:137], v[174:177], v[42:45]
	v_mfma_f32_16x16x32_bf16 v[30:33], v[110:113], v[182:185], v[30:33]
	v_mfma_f32_16x16x32_bf16 v[26:29], v[134:137], v[182:185], v[26:29]
	v_mfma_f32_16x16x32_bf16 v[14:17], v[110:113], v[204:207], v[14:17]
	v_mfma_f32_16x16x32_bf16 v[10:13], v[134:137], v[204:207], v[10:13]
	s_setprio 0
	s_setprio 1
	v_mfma_f32_16x16x32_bf16 v[54:57], v[138:141], v[162:165], v[54:57]
	v_mfma_f32_16x16x32_bf16 v[50:53], v[146:149], v[162:165], v[50:53]
	v_mfma_f32_16x16x32_bf16 v[38:41], v[138:141], v[170:173], v[38:41]
	v_mfma_f32_16x16x32_bf16 v[34:37], v[146:149], v[170:173], v[34:37]
	v_mfma_f32_16x16x32_bf16 v[22:25], v[138:141], v[178:181], v[22:25]
	v_mfma_f32_16x16x32_bf16 v[18:21], v[146:149], v[178:181], v[18:21]
	v_mfma_f32_16x16x32_bf16 v[6:9], v[138:141], v[186:189], v[6:9]
	v_mfma_f32_16x16x32_bf16 v[2:5], v[146:149], v[186:189], v[2:5]
	v_mfma_f32_16x16x32_bf16 v[54:57], v[142:145], v[166:169], v[54:57]
	v_mfma_f32_16x16x32_bf16 v[50:53], v[150:153], v[166:169], v[50:53]
	v_mfma_f32_16x16x32_bf16 v[38:41], v[142:145], v[174:177], v[38:41]
	v_mfma_f32_16x16x32_bf16 v[34:37], v[150:153], v[174:177], v[34:37]
	v_mfma_f32_16x16x32_bf16 v[22:25], v[142:145], v[182:185], v[22:25]
	v_mfma_f32_16x16x32_bf16 v[18:21], v[150:153], v[182:185], v[18:21]
	v_mfma_f32_16x16x32_bf16 v[6:9], v[142:145], v[204:207], v[6:9]
	s_barrier
	v_mfma_f32_16x16x32_bf16 v[2:5], v[150:153], v[204:207], v[2:5]
	s_setprio 0
	s_add_i32 s60, s60, 2
	s_add_u32 s34, s34, 0x100
	s_addc_u32 s35, s35, 0
	s_add_u32 s58, s58, 0x100
	s_addc_u32 s59, s59, 0
	s_cmp_gt_u32 s60, 41
	s_cbranch_scc1 .Lrp_gen_p5
	s_cmp_lg_u32 s60, 40
	s_cbranch_scc1 .LBB0_892
	s_cmpk_lg_i32 s33, 0x100
	s_cbranch_scc1 .LBB0_892
	ds_read_b128 v[98:101], v239
	ds_read_b128 v[110:113], v239 offset:1024
	ds_read_b128 v[122:125], v239 offset:2048
	ds_read_b128 v[134:137], v239 offset:3072
	ds_read_b128 v[138:141], v240
	ds_read_b128 v[142:145], v240 offset:1024
	ds_read_b128 v[146:149], v240 offset:2048
	ds_read_b128 v[150:153], v240 offset:3072
	s_add_u32 s18, s34, 0xfff50080
	s_addc_u32 s19, s35, -1
	s_cmp_eq_u32 s60, 40
	s_cselect_b32 s39, s1, s19
	s_cselect_b32 s38, s0, s18
	s_cselect_b32 s37, s31, s59
	s_cselect_b32 s36, s30, s58
	v_lshl_add_u64 v[208:209], s[34:35], 0, v[198:199]
	s_add_i32 m0, s41, 0xc000
	ds_read_b128 v[162:165], v241
	ds_read_b128 v[166:169], v241 offset:1024
	ds_read_b128 v[170:173], v241 offset:2048
	ds_read_b128 v[174:177], v241 offset:3072
	ds_read_b128 v[178:181], v241 offset:4096
	ds_read_b128 v[182:185], v241 offset:5120
	ds_read_b128 v[186:189], v241 offset:6144
	ds_read_b128 v[204:207], v241 offset:7168
	global_load_lds_dwordx4 v[208:209], off
	v_lshl_add_u64 v[208:209], s[34:35], 0, v[200:201]
	s_add_i32 m0, s41, 0xe000
	s_nop 0
	global_load_lds_dwordx4 v[208:209], off
	v_lshl_or_b32 v255, s12, 8, v238
	v_lshl_add_u32 v235, s57, 8, v1
	v_lshlrev_b32_e32 v255, 1, v255
	v_lshl_add_u32 v255, v235, 11, v255
	s_mov_b64 s[84:85], s[20:21]
	global_load_dwordx4 v[242:245], v255, s[84:85]
	global_load_dwordx4 v[208:211], v255, s[84:85] offset:256
	s_add_u32 s84, s20, 0x8000
	s_addc_u32 s85, s21, 0
	global_load_dwordx4 v[212:215], v255, s[84:85]
	global_load_dwordx4 v[216:219], v255, s[84:85] offset:256
	s_add_u32 s84, s20, 0x10000
	s_addc_u32 s85, s21, 0
	global_load_dwordx4 v[220:223], v255, s[84:85]
	global_load_dwordx4 v[224:227], v255, s[84:85] offset:256
	s_add_u32 s84, s20, 0x18000
	s_addc_u32 s85, s21, 0
	global_load_dwordx4 v[228:231], v255, s[84:85]
	global_load_dwordx4 v[232:235], v255, s[84:85] offset:256
	s_add_u32 s84, s20, 0x40000
	s_addc_u32 s85, s21, 0
	global_load_dwordx4 v[246:249], v255, s[84:85]
	global_load_dwordx4 v[250:253], v255, s[84:85] offset:256
	s_waitcnt vmcnt(18)
	s_waitcnt lgkmcnt(0)
	s_barrier
; #define PG8_STAGE(bufoff, gbase, voff) do { _Pragma("unroll") for (int _i = 0; _i < 2; ++_i) \
;         __builtin_amdgcn_global_load_lds((const unsigned*)((const char*)(gbase) + (voff)[_i]), (PG8_LAS unsigned*)(lds + (bufoff) + ldsw + _i * 8192), 16, 0, 0); } while (0)
; #define PG8_LDA(dst, b, h) do { _Pragma("unroll") for (int m = 0; m < 4; ++m) _Pragma("unroll") for (int k = 0; k < 2; ++k) dst[m][k] = *(const PG8_LAS bf16x8*)(lds + PG8_SA(b, h) + aoff + m * 2048 + k * 1024); } while (0)
; #define PG8_LDB(dst, b, h) do { _Pragma("unroll") for (int n = 0; n < 2; ++n) _Pragma("unroll") for (int k = 0; k < 2; ++k) dst[n][k] = *(const PG8_LAS bf16x8*)(lds + PG8_SB(b, h) + boff + n * 2048 + k * 1024); } while (0)
; #define PG8_MMA(ai, bj, At, Bt) do { __builtin_amdgcn_s_setprio(1); _Pragma("unroll") for (int m = 0; m < 4; ++m) _Pragma("unroll") for (int n = 0; n < 2; ++n) _Pragma("unroll") for (int k = 0; k < 2; ++k) \
;         acc[ai][bj][m][n] = __builtin_amdgcn_mfma_f32_16x16x32_bf16(Bt[n][k], At[m][k], acc[ai][bj][m][n], 0, 0, 0); __builtin_amdgcn_s_setprio(0); } while (0)
; #define PG8_WAIT_V(n) asm volatile("s_waitcnt vmcnt(" #n ")" ::: "memory")
; template <class Epi, class Sched, bool ALIGN_EPI = false, bool SP2 = false>
; __device__ __forceinline__ void gemm_phase(PG8_LAS unsigned char* lds, const Gemm g, const Sched& S, const Epi& E) {
;     ...
;             PG8_LDB(B0, 0, 0); PG8_LDB(B1, 0, 1); PG8_SCHED; PG8_LDA(At, 0, 0); PG8_STAGE(PG8_SA(1, 1), a1 + hstep, voffA);
;             PG8_WAIT_V(8); PG8_WAIT_L(0); PG8_BAR; PG8_MMA(0, 0, At, B0); PG8_MMA(0, 1, At, B1); PG8_BAR; PG8_SCHED;
;             PG8_LDA(At, 0, 1); PG8_STAGE(PG8_SB(0, 0), b2, voffB); PG8_STAGE(PG8_SB(0, 1), b2 + hstep, voffB); PG8_STAGE(PG8_SA(0, 0), a2, voffA);
;             PG8_WAIT_V(8); PG8_WAIT_L(0); PG8_BAR; PG8_MMA(1, 0, At, B0); PG8_MMA(1, 1, At, B1); PG8_BAR; PG8_SCHED;
;             PG8_LDB(B0, 1, 0); PG8_LDB(B1, 1, 1); PG8_SCHED; PG8_LDA(At, 1, 0); PG8_STAGE(PG8_SA(0, 1), a2 + hstep, voffA);
;             PG8_WAIT_V(8); PG8_WAIT_L(0); PG8_BAR; PG8_MMA(0, 0, At, B0); PG8_MMA(0, 1, At, B1); PG8_BAR; PG8_SCHED;
;             PG8_LDA(At, 1, 1); PG8_STAGE(PG8_SB(1, 0), b3, voffB); PG8_STAGE(PG8_SB(1, 1), b3 + hstep, voffB); PG8_STAGE(PG8_SA(1, 0), a3, voffA);
;             PG8_WAIT_V(8); PG8_WAIT_L(0); PG8_BAR; PG8_MMA(1, 0, At, B0); PG8_MMA(1, 1, At, B1); PG8_BAR; PG8_SCHED;
	s_setprio 1
	s_waitcnt lgkmcnt(0)
	v_mfma_f32_16x16x32_bf16 v[158:161], v[98:101], v[162:165], v[158:161]
	v_mfma_f32_16x16x32_bf16 v[154:157], v[122:125], v[162:165], v[154:157]
	v_mfma_f32_16x16x32_bf16 v[118:121], v[98:101], v[170:173], v[118:121]
	v_mfma_f32_16x16x32_bf16 v[114:117], v[122:125], v[170:173], v[114:117]
	v_mfma_f32_16x16x32_bf16 v[94:97], v[98:101], v[178:181], v[94:97]
	v_mfma_f32_16x16x32_bf16 v[90:93], v[122:125], v[178:181], v[90:93]
	v_mfma_f32_16x16x32_bf16 v[78:81], v[98:101], v[186:189], v[78:81]
	v_mfma_f32_16x16x32_bf16 v[74:77], v[122:125], v[186:189], v[74:77]
	v_mfma_f32_16x16x32_bf16 v[158:161], v[110:113], v[166:169], v[158:161]
	v_mfma_f32_16x16x32_bf16 v[154:157], v[134:137], v[166:169], v[154:157]
	v_mfma_f32_16x16x32_bf16 v[118:121], v[110:113], v[174:177], v[118:121]
	v_mfma_f32_16x16x32_bf16 v[114:117], v[134:137], v[174:177], v[114:117]
	v_mfma_f32_16x16x32_bf16 v[94:97], v[110:113], v[182:185], v[94:97]
	v_mfma_f32_16x16x32_bf16 v[90:93], v[134:137], v[182:185], v[90:93]
	v_mfma_f32_16x16x32_bf16 v[78:81], v[110:113], v[204:207], v[78:81]
	v_mfma_f32_16x16x32_bf16 v[74:77], v[134:137], v[204:207], v[74:77]
	s_setprio 0
	s_setprio 1
	v_mfma_f32_16x16x32_bf16 v[130:133], v[138:141], v[162:165], v[130:133]
	v_mfma_f32_16x16x32_bf16 v[126:129], v[146:149], v[162:165], v[126:129]
	v_mfma_f32_16x16x32_bf16 v[106:109], v[138:141], v[170:173], v[106:109]
	v_mfma_f32_16x16x32_bf16 v[102:105], v[146:149], v[170:173], v[102:105]
	v_mfma_f32_16x16x32_bf16 v[86:89], v[138:141], v[178:181], v[86:89]
	v_mfma_f32_16x16x32_bf16 v[82:85], v[146:149], v[178:181], v[82:85]
	v_mfma_f32_16x16x32_bf16 v[70:73], v[138:141], v[186:189], v[70:73]
	v_mfma_f32_16x16x32_bf16 v[66:69], v[146:149], v[186:189], v[66:69]
	v_mfma_f32_16x16x32_bf16 v[130:133], v[142:145], v[166:169], v[130:133]
	v_mfma_f32_16x16x32_bf16 v[126:129], v[150:153], v[166:169], v[126:129]
	v_mfma_f32_16x16x32_bf16 v[106:109], v[142:145], v[174:177], v[106:109]
	v_mfma_f32_16x16x32_bf16 v[102:105], v[150:153], v[174:177], v[102:105]
	v_mfma_f32_16x16x32_bf16 v[86:89], v[142:145], v[182:185], v[86:89]
	v_mfma_f32_16x16x32_bf16 v[82:85], v[150:153], v[182:185], v[82:85]
	v_mfma_f32_16x16x32_bf16 v[70:73], v[142:145], v[204:207], v[70:73]
	s_barrier
	v_mfma_f32_16x16x32_bf16 v[66:69], v[150:153], v[204:207], v[66:69]
	s_setprio 0
	s_add_i32 s18, s52, s40
	s_mov_b32 m0, s18
	ds_read_b128 v[162:165], v241 offset:16384
	ds_read_b128 v[166:169], v241 offset:17408
	ds_read_b128 v[170:173], v241 offset:18432
	ds_read_b128 v[174:177], v241 offset:19456
	ds_read_b128 v[178:181], v241 offset:20480
	ds_read_b128 v[182:185], v241 offset:21504
	ds_read_b128 v[186:189], v241 offset:22528
	ds_read_b128 v[204:207], v241 offset:23552
	s_add_i32 m0, s18, 0x2000
	s_add_u32 s18, s36, 0xb0000
	s_addc_u32 s19, s37, 0
	s_add_i32 s61, s53, s40
	s_mov_b32 m0, s61
	s_add_i32 m0, s61, 0x2000
	s_nop 0
	s_mov_b32 m0, s41
	s_nop 0
	s_mov_b32 m0, s42
	s_nop 0
	s_waitcnt vmcnt(12)
	s_waitcnt lgkmcnt(0)
	s_barrier
	s_setprio 1
	s_waitcnt lgkmcnt(0)
	v_mfma_f32_16x16x32_bf16 v[62:65], v[98:101], v[162:165], v[62:65]
	v_mfma_f32_16x16x32_bf16 v[58:61], v[122:125], v[162:165], v[58:61]
	v_mfma_f32_16x16x32_bf16 v[46:49], v[98:101], v[170:173], v[46:49]
	v_mfma_f32_16x16x32_bf16 v[42:45], v[122:125], v[170:173], v[42:45]
	v_mfma_f32_16x16x32_bf16 v[30:33], v[98:101], v[178:181], v[30:33]
	v_mfma_f32_16x16x32_bf16 v[26:29], v[122:125], v[178:181], v[26:29]
	v_mfma_f32_16x16x32_bf16 v[14:17], v[98:101], v[186:189], v[14:17]
	v_mfma_f32_16x16x32_bf16 v[10:13], v[122:125], v[186:189], v[10:13]
	v_mfma_f32_16x16x32_bf16 v[62:65], v[110:113], v[166:169], v[62:65]
	v_mfma_f32_16x16x32_bf16 v[58:61], v[134:137], v[166:169], v[58:61]
	v_mfma_f32_16x16x32_bf16 v[46:49], v[110:113], v[174:177], v[46:49]
	v_mfma_f32_16x16x32_bf16 v[42:45], v[134:137], v[174:177], v[42:45]
	v_mfma_f32_16x16x32_bf16 v[30:33], v[110:113], v[182:185], v[30:33]
	v_mfma_f32_16x16x32_bf16 v[26:29], v[134:137], v[182:185], v[26:29]
	v_mfma_f32_16x16x32_bf16 v[14:17], v[110:113], v[204:207], v[14:17]
	v_mfma_f32_16x16x32_bf16 v[10:13], v[134:137], v[204:207], v[10:13]
	s_setprio 0
	s_setprio 1
	v_mfma_f32_16x16x32_bf16 v[54:57], v[138:141], v[162:165], v[54:57]
	v_mfma_f32_16x16x32_bf16 v[50:53], v[146:149], v[162:165], v[50:53]
	v_mfma_f32_16x16x32_bf16 v[38:41], v[138:141], v[170:173], v[38:41]
	v_mfma_f32_16x16x32_bf16 v[34:37], v[146:149], v[170:173], v[34:37]
	v_mfma_f32_16x16x32_bf16 v[22:25], v[138:141], v[178:181], v[22:25]
	v_mfma_f32_16x16x32_bf16 v[18:21], v[146:149], v[178:181], v[18:21]
	v_mfma_f32_16x16x32_bf16 v[6:9], v[138:141], v[186:189], v[6:9]
	v_mfma_f32_16x16x32_bf16 v[2:5], v[146:149], v[186:189], v[2:5]
	v_mfma_f32_16x16x32_bf16 v[54:57], v[142:145], v[166:169], v[54:57]
	v_mfma_f32_16x16x32_bf16 v[50:53], v[150:153], v[166:169], v[50:53]
	v_mfma_f32_16x16x32_bf16 v[38:41], v[142:145], v[174:177], v[38:41]
	v_mfma_f32_16x16x32_bf16 v[34:37], v[150:153], v[174:177], v[34:37]
	v_mfma_f32_16x16x32_bf16 v[22:25], v[142:145], v[182:185], v[22:25]
	v_mfma_f32_16x16x32_bf16 v[18:21], v[150:153], v[182:185], v[18:21]
	v_mfma_f32_16x16x32_bf16 v[6:9], v[142:145], v[204:207], v[6:9]
	s_barrier
; #define PG8_STAGE(bufoff, gbase, voff) do { _Pragma("unroll") for (int _i = 0; _i < 2; ++_i) \
;         __builtin_amdgcn_global_load_lds((const unsigned*)((const char*)(gbase) + (voff)[_i]), (PG8_LAS unsigned*)(lds + (bufoff) + ldsw + _i * 8192), 16, 0, 0); } while (0)
; #define PG8_LDA(dst, b, h) do { _Pragma("unroll") for (int m = 0; m < 4; ++m) _Pragma("unroll") for (int k = 0; k < 2; ++k) dst[m][k] = *(const PG8_LAS bf16x8*)(lds + PG8_SA(b, h) + aoff + m * 2048 + k * 1024); } while (0)
; #define PG8_LDB(dst, b, h) do { _Pragma("unroll") for (int n = 0; n < 2; ++n) _Pragma("unroll") for (int k = 0; k < 2; ++k) dst[n][k] = *(const PG8_LAS bf16x8*)(lds + PG8_SB(b, h) + boff + n * 2048 + k * 1024); } while (0)
; #define PG8_MMA(ai, bj, At, Bt) do { __builtin_amdgcn_s_setprio(1); _Pragma("unroll") for (int m = 0; m < 4; ++m) _Pragma("unroll") for (int n = 0; n < 2; ++n) _Pragma("unroll") for (int k = 0; k < 2; ++k) \
;         acc[ai][bj][m][n] = __builtin_amdgcn_mfma_f32_16x16x32_bf16(Bt[n][k], At[m][k], acc[ai][bj][m][n], 0, 0, 0); __builtin_amdgcn_s_setprio(0); } while (0)
; #define PG8_WAIT_V(n) asm volatile("s_waitcnt vmcnt(" #n ")" ::: "memory")
; template <class Epi, class Sched, bool ALIGN_EPI = false, bool SP2 = false>
; __device__ __forceinline__ void gemm_phase(PG8_LAS unsigned char* lds, const Gemm g, const Sched& S, const Epi& E) {
;     ...
;             PG8_LDB(B0, 0, 0); PG8_LDB(B1, 0, 1); PG8_SCHED; PG8_LDA(At, 0, 0); PG8_STAGE(PG8_SA(1, 1), a1 + hstep, voffA);
;             PG8_WAIT_V(8); PG8_WAIT_L(0); PG8_BAR; PG8_MMA(0, 0, At, B0); PG8_MMA(0, 1, At, B1); PG8_BAR; PG8_SCHED;
;             PG8_LDA(At, 0, 1); PG8_STAGE(PG8_SB(0, 0), b2, voffB); PG8_STAGE(PG8_SB(0, 1), b2 + hstep, voffB); PG8_STAGE(PG8_SA(0, 0), a2, voffA);
;             PG8_WAIT_V(8); PG8_WAIT_L(0); PG8_BAR; PG8_MMA(1, 0, At, B0); PG8_MMA(1, 1, At, B1); PG8_BAR; PG8_SCHED;
;             PG8_LDB(B0, 1, 0); PG8_LDB(B1, 1, 1); PG8_SCHED; PG8_LDA(At, 1, 0); PG8_STAGE(PG8_SA(0, 1), a2 + hstep, voffA);
;             PG8_WAIT_V(8); PG8_WAIT_L(0); PG8_BAR; PG8_MMA(0, 0, At, B0); PG8_MMA(0, 1, At, B1); PG8_BAR; PG8_SCHED;
;             PG8_LDA(At, 1, 1); PG8_STAGE(PG8_SB(1, 0), b3, voffB); PG8_STAGE(PG8_SB(1, 1), b3 + hstep, voffB); PG8_STAGE(PG8_SA(1, 0), a3, voffA);
;             PG8_WAIT_V(8); PG8_WAIT_L(0); PG8_BAR; PG8_MMA(1, 0, At, B0); PG8_MMA(1, 1, At, B1); PG8_BAR; PG8_SCHED;
	v_mfma_f32_16x16x32_bf16 v[2:5], v[150:153], v[204:207], v[2:5]
	s_setprio 0
	s_add_i32 s61, 0, 0x18000
	s_add_i32 s62, 0, 0x1c000
	v_add_u32_e32 v134, s61, v237
	v_add_u32_e32 v150, s62, v237
	ds_read_b128 v[98:101], v134
	ds_read_b128 v[110:113], v134 offset:1024
	ds_read_b128 v[122:125], v134 offset:2048
	ds_read_b128 v[134:137], v134 offset:3072
	ds_read_b128 v[138:141], v150
	ds_read_b128 v[142:145], v150 offset:1024
	ds_read_b128 v[146:149], v150 offset:2048
	ds_read_b128 v[150:153], v150 offset:3072
	s_add_u32 s18, s38, 0xb0000
	s_addc_u32 s19, s39, 0
	s_mov_b32 m0, s43
	ds_read_b128 v[162:165], v241 offset:32768
	ds_read_b128 v[166:169], v241 offset:33792
	ds_read_b128 v[170:173], v241 offset:34816
	ds_read_b128 v[174:177], v241 offset:35840
	ds_read_b128 v[178:181], v241 offset:36864
	ds_read_b128 v[182:185], v241 offset:37888
	ds_read_b128 v[186:189], v241 offset:38912
	ds_read_b128 v[204:207], v241 offset:39936
	s_mov_b32 m0, s44
	s_nop 0
	s_waitcnt vmcnt(10)
	s_waitcnt lgkmcnt(0)
	s_barrier
	s_setprio 1
	s_waitcnt lgkmcnt(0)
	v_mfma_f32_16x16x32_bf16 v[158:161], v[98:101], v[162:165], v[158:161]
	v_mfma_f32_16x16x32_bf16 v[154:157], v[122:125], v[162:165], v[154:157]
	v_mfma_f32_16x16x32_bf16 v[118:121], v[98:101], v[170:173], v[118:121]
	v_mfma_f32_16x16x32_bf16 v[114:117], v[122:125], v[170:173], v[114:117]
	v_mfma_f32_16x16x32_bf16 v[94:97], v[98:101], v[178:181], v[94:97]
	v_mfma_f32_16x16x32_bf16 v[90:93], v[122:125], v[178:181], v[90:93]
	v_mfma_f32_16x16x32_bf16 v[78:81], v[98:101], v[186:189], v[78:81]
	v_mfma_f32_16x16x32_bf16 v[74:77], v[122:125], v[186:189], v[74:77]
	v_mfma_f32_16x16x32_bf16 v[158:161], v[110:113], v[166:169], v[158:161]
	v_mfma_f32_16x16x32_bf16 v[154:157], v[134:137], v[166:169], v[154:157]
	v_mfma_f32_16x16x32_bf16 v[118:121], v[110:113], v[174:177], v[118:121]
	v_mfma_f32_16x16x32_bf16 v[114:117], v[134:137], v[174:177], v[114:117]
	v_mfma_f32_16x16x32_bf16 v[94:97], v[110:113], v[182:185], v[94:97]
	v_mfma_f32_16x16x32_bf16 v[90:93], v[134:137], v[182:185], v[90:93]
	v_mfma_f32_16x16x32_bf16 v[78:81], v[110:113], v[204:207], v[78:81]
	v_mfma_f32_16x16x32_bf16 v[74:77], v[134:137], v[204:207], v[74:77]
	s_setprio 0
	s_setprio 1
	v_mfma_f32_16x16x32_bf16 v[130:133], v[138:141], v[162:165], v[130:133]
	v_mfma_f32_16x16x32_bf16 v[126:129], v[146:149], v[162:165], v[126:129]
	v_mfma_f32_16x16x32_bf16 v[106:109], v[138:141], v[170:173], v[106:109]
	v_mfma_f32_16x16x32_bf16 v[102:105], v[146:149], v[170:173], v[102:105]
	v_mfma_f32_16x16x32_bf16 v[86:89], v[138:141], v[178:181], v[86:89]
	v_mfma_f32_16x16x32_bf16 v[82:85], v[146:149], v[178:181], v[82:85]
	v_mfma_f32_16x16x32_bf16 v[70:73], v[138:141], v[186:189], v[70:73]
	v_mfma_f32_16x16x32_bf16 v[66:69], v[146:149], v[186:189], v[66:69]
	v_mfma_f32_16x16x32_bf16 v[130:133], v[142:145], v[166:169], v[130:133]
	v_mfma_f32_16x16x32_bf16 v[126:129], v[150:153], v[166:169], v[126:129]
	v_mfma_f32_16x16x32_bf16 v[106:109], v[142:145], v[174:177], v[106:109]
	v_mfma_f32_16x16x32_bf16 v[102:105], v[150:153], v[174:177], v[102:105]
	v_mfma_f32_16x16x32_bf16 v[86:89], v[142:145], v[182:185], v[86:89]
	v_mfma_f32_16x16x32_bf16 v[82:85], v[150:153], v[182:185], v[82:85]
	v_mfma_f32_16x16x32_bf16 v[70:73], v[142:145], v[204:207], v[70:73]
	s_barrier
	v_mfma_f32_16x16x32_bf16 v[66:69], v[150:153], v[204:207], v[66:69]
	s_setprio 0
	s_add_i32 s18, s61, s40
	s_mov_b32 m0, s18
	ds_read_b128 v[162:165], v241 offset:49152
	ds_read_b128 v[166:169], v241 offset:50176
	ds_read_b128 v[170:173], v241 offset:51200
	ds_read_b128 v[174:177], v241 offset:52224
	ds_read_b128 v[178:181], v241 offset:53248
	ds_read_b128 v[182:185], v241 offset:54272
	ds_read_b128 v[186:189], v241 offset:55296
	ds_read_b128 v[204:207], v241 offset:56320
	s_add_i32 m0, s18, 0x2000
	s_add_u32 s18, s36, 0xb0080
	s_addc_u32 s19, s37, 0
	s_add_i32 s36, s62, s40
	s_mov_b32 m0, s36
	s_nop 0
	s_add_i32 m0, s36, 0x2000
	s_nop 0
	s_mov_b32 m0, s46
	s_nop 0
	s_mov_b32 m0, s47
	s_nop 0
	s_waitcnt vmcnt(10)
	s_waitcnt lgkmcnt(0)
	s_barrier
	s_setprio 1
	s_waitcnt lgkmcnt(0)
	v_mfma_f32_16x16x32_bf16 v[62:65], v[98:101], v[162:165], v[62:65]
	v_mfma_f32_16x16x32_bf16 v[58:61], v[122:125], v[162:165], v[58:61]
	v_mfma_f32_16x16x32_bf16 v[46:49], v[98:101], v[170:173], v[46:49]
	v_mfma_f32_16x16x32_bf16 v[42:45], v[122:125], v[170:173], v[42:45]
	v_mfma_f32_16x16x32_bf16 v[30:33], v[98:101], v[178:181], v[30:33]
	v_mfma_f32_16x16x32_bf16 v[26:29], v[122:125], v[178:181], v[26:29]
	v_mfma_f32_16x16x32_bf16 v[14:17], v[98:101], v[186:189], v[14:17]
	v_mfma_f32_16x16x32_bf16 v[10:13], v[122:125], v[186:189], v[10:13]
	v_mfma_f32_16x16x32_bf16 v[62:65], v[110:113], v[166:169], v[62:65]
	v_mfma_f32_16x16x32_bf16 v[58:61], v[134:137], v[166:169], v[58:61]
	v_mfma_f32_16x16x32_bf16 v[46:49], v[110:113], v[174:177], v[46:49]
	v_mfma_f32_16x16x32_bf16 v[42:45], v[134:137], v[174:177], v[42:45]
	v_mfma_f32_16x16x32_bf16 v[30:33], v[110:113], v[182:185], v[30:33]
	v_mfma_f32_16x16x32_bf16 v[26:29], v[134:137], v[182:185], v[26:29]
	v_mfma_f32_16x16x32_bf16 v[14:17], v[110:113], v[204:207], v[14:17]
	v_mfma_f32_16x16x32_bf16 v[10:13], v[134:137], v[204:207], v[10:13]
	s_setprio 0
	s_setprio 1
	v_mfma_f32_16x16x32_bf16 v[54:57], v[138:141], v[162:165], v[54:57]
	v_mfma_f32_16x16x32_bf16 v[50:53], v[146:149], v[162:165], v[50:53]
	v_mfma_f32_16x16x32_bf16 v[38:41], v[138:141], v[170:173], v[38:41]
	v_mfma_f32_16x16x32_bf16 v[34:37], v[146:149], v[170:173], v[34:37]
	v_mfma_f32_16x16x32_bf16 v[22:25], v[138:141], v[178:181], v[22:25]
	v_mfma_f32_16x16x32_bf16 v[18:21], v[146:149], v[178:181], v[18:21]
	v_mfma_f32_16x16x32_bf16 v[6:9], v[138:141], v[186:189], v[6:9]
	v_mfma_f32_16x16x32_bf16 v[2:5], v[146:149], v[186:189], v[2:5]
	v_mfma_f32_16x16x32_bf16 v[54:57], v[142:145], v[166:169], v[54:57]
	v_mfma_f32_16x16x32_bf16 v[50:53], v[150:153], v[166:169], v[50:53]
	v_mfma_f32_16x16x32_bf16 v[38:41], v[142:145], v[174:177], v[38:41]
	v_mfma_f32_16x16x32_bf16 v[34:37], v[150:153], v[174:177], v[34:37]
	v_mfma_f32_16x16x32_bf16 v[22:25], v[142:145], v[182:185], v[22:25]
	v_mfma_f32_16x16x32_bf16 v[18:21], v[150:153], v[182:185], v[18:21]
	v_mfma_f32_16x16x32_bf16 v[6:9], v[142:145], v[204:207], v[6:9]
	s_barrier
	v_mfma_f32_16x16x32_bf16 v[2:5], v[150:153], v[204:207], v[2:5]
	s_setprio 0
	s_add_i32 s60, s60, 2
	s_add_u32 s34, s34, 0x100
	s_addc_u32 s35, s35, 0
	s_add_u32 s58, s58, 0x100
	s_addc_u32 s59, s59, 0
	s_branch .Lrp_done_p5

; #define PG8_STAGE(bufoff, gbase, voff) do { _Pragma("unroll") for (int _i = 0; _i < 2; ++_i) \
;         __builtin_amdgcn_global_load_lds((const unsigned*)((const char*)(gbase) + (voff)[_i]), (PG8_LAS unsigned*)(lds + (bufoff) + ldsw + _i * 8192), 16, 0, 0); } while (0)
; #define PG8_LDA(dst, b, h) do { _Pragma("unroll") for (int m = 0; m < 4; ++m) _Pragma("unroll") for (int k = 0; k < 2; ++k) dst[m][k] = *(const PG8_LAS bf16x8*)(lds + PG8_SA(b, h) + aoff + m * 2048 + k * 1024); } while (0)
; #define PG8_LDB(dst, b, h) do { _Pragma("unroll") for (int n = 0; n < 2; ++n) _Pragma("unroll") for (int k = 0; k < 2; ++k) dst[n][k] = *(const PG8_LAS bf16x8*)(lds + PG8_SB(b, h) + boff + n * 2048 + k * 1024); } while (0)
; #define PG8_MMA(ai, bj, At, Bt) do { __builtin_amdgcn_s_setprio(1); _Pragma("unroll") for (int m = 0; m < 4; ++m) _Pragma("unroll") for (int n = 0; n < 2; ++n) _Pragma("unroll") for (int k = 0; k < 2; ++k) \
;         acc[ai][bj][m][n] = __builtin_amdgcn_mfma_f32_16x16x32_bf16(Bt[n][k], At[m][k], acc[ai][bj][m][n], 0, 0, 0); __builtin_amdgcn_s_setprio(0); } while (0)
; #define PG8_WAIT_V(n) asm volatile("s_waitcnt vmcnt(" #n ")" ::: "memory")
; template <class Epi, class Sched, bool ALIGN_EPI = false, bool SP2 = false>
; __device__ __forceinline__ void gemm_phase(PG8_LAS unsigned char* lds, const Gemm g, const Sched& S, const Epi& E) {
;     ...
;             PG8_LDB(B0, 0, 0); PG8_LDB(B1, 0, 1); PG8_SCHED; PG8_LDA(At, 0, 0); PG8_STAGE(PG8_SA(1, 1), a1 + hstep, voffA);
;             PG8_WAIT_V(8); PG8_WAIT_L(0); PG8_BAR; PG8_MMA(0, 0, At, B0); PG8_MMA(0, 1, At, B1); PG8_BAR; PG8_SCHED;
;             PG8_LDA(At, 0, 1); PG8_STAGE(PG8_SB(0, 0), b2, voffB); PG8_STAGE(PG8_SB(0, 1), b2 + hstep, voffB); PG8_STAGE(PG8_SA(0, 0), a2, voffA);
;             PG8_WAIT_V(8); PG8_WAIT_L(0); PG8_BAR; PG8_MMA(1, 0, At, B0); PG8_MMA(1, 1, At, B1); PG8_BAR; PG8_SCHED;
;             PG8_LDB(B0, 1, 0); PG8_LDB(B1, 1, 1); PG8_SCHED; PG8_LDA(At, 1, 0); PG8_STAGE(PG8_SA(0, 1), a2 + hstep, voffA);
;             PG8_WAIT_V(8); PG8_WAIT_L(0); PG8_BAR; PG8_MMA(0, 0, At, B0); PG8_MMA(0, 1, At, B1); PG8_BAR; PG8_SCHED;
;             PG8_LDA(At, 1, 1); PG8_STAGE(PG8_SB(1, 0), b3, voffB); PG8_STAGE(PG8_SB(1, 1), b3 + hstep, voffB); PG8_STAGE(PG8_SA(1, 0), a3, voffA);
;             PG8_WAIT_V(8); PG8_WAIT_L(0); PG8_BAR; PG8_MMA(1, 0, At, B0); PG8_MMA(1, 1, At, B1); PG8_BAR; PG8_SCHED;
.LBB0_1033:
	ds_read_b128 v[128:131], v202
	ds_read_b128 v[132:135], v202 offset:1024
	ds_read_b128 v[136:139], v202 offset:2048
	ds_read_b128 v[140:143], v202 offset:3072
	ds_read_b128 v[144:147], v203
	ds_read_b128 v[148:151], v203 offset:1024
	ds_read_b128 v[152:155], v203 offset:2048
	ds_read_b128 v[156:159], v203 offset:3072
	s_add_u32 s6, s4, 0xfffc0080
	s_addc_u32 s7, s5, -1
	s_cmp_eq_u32 s62, 12
	s_cselect_b32 s41, s3, s7
	s_cselect_b32 s40, s35, s6
	s_cselect_b32 s7, s31, s61
	s_cselect_b32 s6, s59, s60
	v_lshl_add_u64 v[218:219], s[4:5], 0, v[170:171]
	s_add_i32 m0, s44, 0xc000
	ds_read_b128 v[178:181], v204
	ds_read_b128 v[182:185], v204 offset:1024
	ds_read_b128 v[186:189], v204 offset:2048
	ds_read_b128 v[190:193], v204 offset:3072
	ds_read_b128 v[194:197], v204 offset:4096
	ds_read_b128 v[206:209], v204 offset:5120
	ds_read_b128 v[210:213], v204 offset:6144
	ds_read_b128 v[214:217], v204 offset:7168
	global_load_lds_dwordx4 v[218:219], off
	v_lshl_add_u64 v[218:219], s[4:5], 0, v[172:173]
	s_add_i32 m0, s44, 0xe000
	s_nop 0
	global_load_lds_dwordx4 v[218:219], off
	s_waitcnt vmcnt(8)
	s_waitcnt lgkmcnt(0)
	s_barrier
	s_setprio 1
	s_waitcnt lgkmcnt(0)
	v_mfma_f32_16x16x32_bf16 v[124:127], v[128:131], v[178:181], v[124:127]
	v_mfma_f32_16x16x32_bf16 v[120:123], v[136:139], v[178:181], v[120:123]
	v_mfma_f32_16x16x32_bf16 v[108:111], v[128:131], v[186:189], v[108:111]
	v_mfma_f32_16x16x32_bf16 v[104:107], v[136:139], v[186:189], v[104:107]
	v_mfma_f32_16x16x32_bf16 v[92:95], v[128:131], v[194:197], v[92:95]
	v_mfma_f32_16x16x32_bf16 v[88:91], v[136:139], v[194:197], v[88:91]
	v_mfma_f32_16x16x32_bf16 v[76:79], v[128:131], v[210:213], v[76:79]
	v_mfma_f32_16x16x32_bf16 v[72:75], v[136:139], v[210:213], v[72:75]
	v_mfma_f32_16x16x32_bf16 v[124:127], v[132:135], v[182:185], v[124:127]
	v_mfma_f32_16x16x32_bf16 v[120:123], v[140:143], v[182:185], v[120:123]
	v_mfma_f32_16x16x32_bf16 v[108:111], v[132:135], v[190:193], v[108:111]
	v_mfma_f32_16x16x32_bf16 v[104:107], v[140:143], v[190:193], v[104:107]
	v_mfma_f32_16x16x32_bf16 v[92:95], v[132:135], v[206:209], v[92:95]
	v_mfma_f32_16x16x32_bf16 v[88:91], v[140:143], v[206:209], v[88:91]
	v_mfma_f32_16x16x32_bf16 v[76:79], v[132:135], v[214:217], v[76:79]
	v_mfma_f32_16x16x32_bf16 v[72:75], v[140:143], v[214:217], v[72:75]
	s_setprio 0
	s_setprio 1
	v_mfma_f32_16x16x32_bf16 v[116:119], v[144:147], v[178:181], v[116:119]
	v_mfma_f32_16x16x32_bf16 v[112:115], v[152:155], v[178:181], v[112:115]
	v_mfma_f32_16x16x32_bf16 v[100:103], v[144:147], v[186:189], v[100:103]
	v_mfma_f32_16x16x32_bf16 v[96:99], v[152:155], v[186:189], v[96:99]
	v_mfma_f32_16x16x32_bf16 v[84:87], v[144:147], v[194:197], v[84:87]
	v_mfma_f32_16x16x32_bf16 v[80:83], v[152:155], v[194:197], v[80:83]
	v_mfma_f32_16x16x32_bf16 v[68:71], v[144:147], v[210:213], v[68:71]
	v_mfma_f32_16x16x32_bf16 v[64:67], v[152:155], v[210:213], v[64:67]
	v_mfma_f32_16x16x32_bf16 v[116:119], v[148:151], v[182:185], v[116:119]
	v_mfma_f32_16x16x32_bf16 v[112:115], v[156:159], v[182:185], v[112:115]
	v_mfma_f32_16x16x32_bf16 v[100:103], v[148:151], v[190:193], v[100:103]
	v_mfma_f32_16x16x32_bf16 v[96:99], v[156:159], v[190:193], v[96:99]
	v_mfma_f32_16x16x32_bf16 v[84:87], v[148:151], v[206:209], v[84:87]
	v_mfma_f32_16x16x32_bf16 v[80:83], v[156:159], v[206:209], v[80:83]
	v_mfma_f32_16x16x32_bf16 v[68:71], v[148:151], v[214:217], v[68:71]
	s_barrier
	v_mfma_f32_16x16x32_bf16 v[64:67], v[156:159], v[214:217], v[64:67]
	s_setprio 0
	s_add_i32 s63, s55, s42
	v_lshl_add_u64 v[218:219], s[6:7], 0, v[162:163]
	s_mov_b32 m0, s63
	ds_read_b128 v[178:181], v204 offset:16384
	ds_read_b128 v[182:185], v204 offset:17408
	ds_read_b128 v[186:189], v204 offset:18432
	ds_read_b128 v[190:193], v204 offset:19456
	ds_read_b128 v[194:197], v204 offset:20480
	ds_read_b128 v[206:209], v204 offset:21504
	ds_read_b128 v[210:213], v204 offset:22528
	ds_read_b128 v[214:217], v204 offset:23552
	global_load_lds_dwordx4 v[218:219], off
	s_add_i32 m0, s63, 0x2000
	s_add_u32 s64, s6, 0x40000
	v_lshl_add_u64 v[220:221], s[6:7], 0, v[166:167]
	s_addc_u32 s65, s7, 0
	s_add_i32 s63, s56, s42
	global_load_lds_dwordx4 v[220:221], off
	v_lshl_add_u64 v[222:223], s[64:65], 0, v[162:163]
	s_mov_b32 m0, s63
	v_lshl_add_u64 v[224:225], s[40:41], 0, v[164:165]
	global_load_lds_dwordx4 v[222:223], off
	v_lshl_add_u64 v[222:223], s[64:65], 0, v[166:167]
	s_add_i32 m0, s63, 0x2000
	s_nop 0
	global_load_lds_dwordx4 v[222:223], off
	v_lshl_add_u64 v[222:223], s[40:41], 0, v[160:161]
	s_mov_b32 m0, s44
	s_nop 0
	global_load_lds_dwordx4 v[222:223], off
	s_mov_b32 m0, s45
	s_nop 0
	global_load_lds_dwordx4 v[224:225], off
	s_waitcnt vmcnt(8)
	s_waitcnt lgkmcnt(0)
	s_barrier
; #define PG8_STAGE(bufoff, gbase, voff) do { _Pragma("unroll") for (int _i = 0; _i < 2; ++_i) \
;         __builtin_amdgcn_global_load_lds((const unsigned*)((const char*)(gbase) + (voff)[_i]), (PG8_LAS unsigned*)(lds + (bufoff) + ldsw + _i * 8192), 16, 0, 0); } while (0)
; #define PG8_LDA(dst, b, h) do { _Pragma("unroll") for (int m = 0; m < 4; ++m) _Pragma("unroll") for (int k = 0; k < 2; ++k) dst[m][k] = *(const PG8_LAS bf16x8*)(lds + PG8_SA(b, h) + aoff + m * 2048 + k * 1024); } while (0)
; #define PG8_LDB(dst, b, h) do { _Pragma("unroll") for (int n = 0; n < 2; ++n) _Pragma("unroll") for (int k = 0; k < 2; ++k) dst[n][k] = *(const PG8_LAS bf16x8*)(lds + PG8_SB(b, h) + boff + n * 2048 + k * 1024); } while (0)
; #define PG8_MMA(ai, bj, At, Bt) do { __builtin_amdgcn_s_setprio(1); _Pragma("unroll") for (int m = 0; m < 4; ++m) _Pragma("unroll") for (int n = 0; n < 2; ++n) _Pragma("unroll") for (int k = 0; k < 2; ++k) \
;         acc[ai][bj][m][n] = __builtin_amdgcn_mfma_f32_16x16x32_bf16(Bt[n][k], At[m][k], acc[ai][bj][m][n], 0, 0, 0); __builtin_amdgcn_s_setprio(0); } while (0)
; #define PG8_WAIT_V(n) asm volatile("s_waitcnt vmcnt(" #n ")" ::: "memory")
; template <class Epi, class Sched, bool ALIGN_EPI = false, bool SP2 = false>
; __device__ __forceinline__ void gemm_phase(PG8_LAS unsigned char* lds, const Gemm g, const Sched& S, const Epi& E) {
;     ...
;             PG8_LDB(B0, 0, 0); PG8_LDB(B1, 0, 1); PG8_SCHED; PG8_LDA(At, 0, 0); PG8_STAGE(PG8_SA(1, 1), a1 + hstep, voffA);
;             PG8_WAIT_V(8); PG8_WAIT_L(0); PG8_BAR; PG8_MMA(0, 0, At, B0); PG8_MMA(0, 1, At, B1); PG8_BAR; PG8_SCHED;
;             PG8_LDA(At, 0, 1); PG8_STAGE(PG8_SB(0, 0), b2, voffB); PG8_STAGE(PG8_SB(0, 1), b2 + hstep, voffB); PG8_STAGE(PG8_SA(0, 0), a2, voffA);
;             PG8_WAIT_V(8); PG8_WAIT_L(0); PG8_BAR; PG8_MMA(1, 0, At, B0); PG8_MMA(1, 1, At, B1); PG8_BAR; PG8_SCHED;
;             PG8_LDB(B0, 1, 0); PG8_LDB(B1, 1, 1); PG8_SCHED; PG8_LDA(At, 1, 0); PG8_STAGE(PG8_SA(0, 1), a2 + hstep, voffA);
;             PG8_WAIT_V(8); PG8_WAIT_L(0); PG8_BAR; PG8_MMA(0, 0, At, B0); PG8_MMA(0, 1, At, B1); PG8_BAR; PG8_SCHED;
;             PG8_LDA(At, 1, 1); PG8_STAGE(PG8_SB(1, 0), b3, voffB); PG8_STAGE(PG8_SB(1, 1), b3 + hstep, voffB); PG8_STAGE(PG8_SA(1, 0), a3, voffA);
;             PG8_WAIT_V(8); PG8_WAIT_L(0); PG8_BAR; PG8_MMA(1, 0, At, B0); PG8_MMA(1, 1, At, B1); PG8_BAR; PG8_SCHED;
	s_setprio 1
	s_waitcnt lgkmcnt(0)
	v_mfma_f32_16x16x32_bf16 v[60:63], v[128:131], v[178:181], v[60:63]
	v_mfma_f32_16x16x32_bf16 v[56:59], v[136:139], v[178:181], v[56:59]
	v_mfma_f32_16x16x32_bf16 v[44:47], v[128:131], v[186:189], v[44:47]
	v_mfma_f32_16x16x32_bf16 v[40:43], v[136:139], v[186:189], v[40:43]
	v_mfma_f32_16x16x32_bf16 v[28:31], v[128:131], v[194:197], v[28:31]
	v_mfma_f32_16x16x32_bf16 v[24:27], v[136:139], v[194:197], v[24:27]
	v_mfma_f32_16x16x32_bf16 v[12:15], v[128:131], v[210:213], v[12:15]
	v_mfma_f32_16x16x32_bf16 v[8:11], v[136:139], v[210:213], v[8:11]
	v_mfma_f32_16x16x32_bf16 v[60:63], v[132:135], v[182:185], v[60:63]
	v_mfma_f32_16x16x32_bf16 v[56:59], v[140:143], v[182:185], v[56:59]
	v_mfma_f32_16x16x32_bf16 v[44:47], v[132:135], v[190:193], v[44:47]
	v_mfma_f32_16x16x32_bf16 v[40:43], v[140:143], v[190:193], v[40:43]
	v_mfma_f32_16x16x32_bf16 v[28:31], v[132:135], v[206:209], v[28:31]
	v_mfma_f32_16x16x32_bf16 v[24:27], v[140:143], v[206:209], v[24:27]
	v_mfma_f32_16x16x32_bf16 v[12:15], v[132:135], v[214:217], v[12:15]
	v_mfma_f32_16x16x32_bf16 v[8:11], v[140:143], v[214:217], v[8:11]
	s_setprio 0
	s_setprio 1
	v_mfma_f32_16x16x32_bf16 v[52:55], v[144:147], v[178:181], v[52:55]
	v_mfma_f32_16x16x32_bf16 v[48:51], v[152:155], v[178:181], v[48:51]
	v_mfma_f32_16x16x32_bf16 v[36:39], v[144:147], v[186:189], v[36:39]
	v_mfma_f32_16x16x32_bf16 v[32:35], v[152:155], v[186:189], v[32:35]
	v_mfma_f32_16x16x32_bf16 v[20:23], v[144:147], v[194:197], v[20:23]
	v_mfma_f32_16x16x32_bf16 v[16:19], v[152:155], v[194:197], v[16:19]
	v_mfma_f32_16x16x32_bf16 v[4:7], v[144:147], v[210:213], v[4:7]
	v_mfma_f32_16x16x32_bf16 v[0:3], v[152:155], v[210:213], v[0:3]
	v_mfma_f32_16x16x32_bf16 v[52:55], v[148:151], v[182:185], v[52:55]
	v_mfma_f32_16x16x32_bf16 v[48:51], v[156:159], v[182:185], v[48:51]
	v_mfma_f32_16x16x32_bf16 v[36:39], v[148:151], v[190:193], v[36:39]
	v_mfma_f32_16x16x32_bf16 v[32:35], v[156:159], v[190:193], v[32:35]
	v_mfma_f32_16x16x32_bf16 v[20:23], v[148:151], v[206:209], v[20:23]
	v_mfma_f32_16x16x32_bf16 v[16:19], v[156:159], v[206:209], v[16:19]
	v_mfma_f32_16x16x32_bf16 v[4:7], v[148:151], v[214:217], v[4:7]
	s_barrier
	v_mfma_f32_16x16x32_bf16 v[0:3], v[156:159], v[214:217], v[0:3]
	s_setprio 0
	s_add_i32 s63, 0, 0x18000
	s_add_i32 s64, 0, 0x1c000
	v_add_u32_e32 v140, s63, v199
	v_add_u32_e32 v156, s64, v199
	ds_read_b128 v[128:131], v140
	ds_read_b128 v[132:135], v140 offset:1024
	ds_read_b128 v[136:139], v140 offset:2048
	ds_read_b128 v[140:143], v140 offset:3072
	ds_read_b128 v[144:147], v156
	ds_read_b128 v[148:151], v156 offset:1024
	ds_read_b128 v[152:155], v156 offset:2048
	ds_read_b128 v[156:159], v156 offset:3072
	s_add_u32 s40, s40, 0x40000
	s_addc_u32 s41, s41, 0
	s_mov_b32 m0, s46
	v_lshl_add_u64 v[226:227], s[40:41], 0, v[160:161]
	ds_read_b128 v[178:181], v204 offset:32768
	ds_read_b128 v[182:185], v204 offset:33792
	ds_read_b128 v[186:189], v204 offset:34816
	ds_read_b128 v[190:193], v204 offset:35840
	ds_read_b128 v[194:197], v204 offset:36864
	ds_read_b128 v[206:209], v204 offset:37888
	ds_read_b128 v[210:213], v204 offset:38912
	ds_read_b128 v[214:217], v204 offset:39936
	global_load_lds_dwordx4 v[226:227], off
	v_lshl_add_u64 v[226:227], s[40:41], 0, v[164:165]
	s_mov_b32 m0, s47
	s_nop 0
	global_load_lds_dwordx4 v[226:227], off
	s_waitcnt vmcnt(8)
	s_waitcnt lgkmcnt(0)
	s_barrier
	s_setprio 1
	s_waitcnt lgkmcnt(0)
	v_mfma_f32_16x16x32_bf16 v[124:127], v[128:131], v[178:181], v[124:127]
	v_mfma_f32_16x16x32_bf16 v[120:123], v[136:139], v[178:181], v[120:123]
	v_mfma_f32_16x16x32_bf16 v[108:111], v[128:131], v[186:189], v[108:111]
	v_mfma_f32_16x16x32_bf16 v[104:107], v[136:139], v[186:189], v[104:107]
	v_mfma_f32_16x16x32_bf16 v[92:95], v[128:131], v[194:197], v[92:95]
	v_mfma_f32_16x16x32_bf16 v[88:91], v[136:139], v[194:197], v[88:91]
	v_mfma_f32_16x16x32_bf16 v[76:79], v[128:131], v[210:213], v[76:79]
	v_mfma_f32_16x16x32_bf16 v[72:75], v[136:139], v[210:213], v[72:75]
	v_mfma_f32_16x16x32_bf16 v[124:127], v[132:135], v[182:185], v[124:127]
	v_mfma_f32_16x16x32_bf16 v[120:123], v[140:143], v[182:185], v[120:123]
	v_mfma_f32_16x16x32_bf16 v[108:111], v[132:135], v[190:193], v[108:111]
	v_mfma_f32_16x16x32_bf16 v[104:107], v[140:143], v[190:193], v[104:107]
	v_mfma_f32_16x16x32_bf16 v[92:95], v[132:135], v[206:209], v[92:95]
	v_mfma_f32_16x16x32_bf16 v[88:91], v[140:143], v[206:209], v[88:91]
	v_mfma_f32_16x16x32_bf16 v[76:79], v[132:135], v[214:217], v[76:79]
	v_mfma_f32_16x16x32_bf16 v[72:75], v[140:143], v[214:217], v[72:75]
	s_setprio 0
	s_setprio 1
	v_mfma_f32_16x16x32_bf16 v[116:119], v[144:147], v[178:181], v[116:119]
	v_mfma_f32_16x16x32_bf16 v[112:115], v[152:155], v[178:181], v[112:115]
	v_mfma_f32_16x16x32_bf16 v[100:103], v[144:147], v[186:189], v[100:103]
	v_mfma_f32_16x16x32_bf16 v[96:99], v[152:155], v[186:189], v[96:99]
	v_mfma_f32_16x16x32_bf16 v[84:87], v[144:147], v[194:197], v[84:87]
	v_mfma_f32_16x16x32_bf16 v[80:83], v[152:155], v[194:197], v[80:83]
	v_mfma_f32_16x16x32_bf16 v[68:71], v[144:147], v[210:213], v[68:71]
	v_mfma_f32_16x16x32_bf16 v[64:67], v[152:155], v[210:213], v[64:67]
	v_mfma_f32_16x16x32_bf16 v[116:119], v[148:151], v[182:185], v[116:119]
	v_mfma_f32_16x16x32_bf16 v[112:115], v[156:159], v[182:185], v[112:115]
	v_mfma_f32_16x16x32_bf16 v[100:103], v[148:151], v[190:193], v[100:103]
	v_mfma_f32_16x16x32_bf16 v[96:99], v[156:159], v[190:193], v[96:99]
	v_mfma_f32_16x16x32_bf16 v[84:87], v[148:151], v[206:209], v[84:87]
	v_mfma_f32_16x16x32_bf16 v[80:83], v[156:159], v[206:209], v[80:83]
	v_mfma_f32_16x16x32_bf16 v[68:71], v[148:151], v[214:217], v[68:71]
	s_barrier
; #define PG8_STAGE(bufoff, gbase, voff) do { _Pragma("unroll") for (int _i = 0; _i < 2; ++_i) \
;         __builtin_amdgcn_global_load_lds((const unsigned*)((const char*)(gbase) + (voff)[_i]), (PG8_LAS unsigned*)(lds + (bufoff) + ldsw + _i * 8192), 16, 0, 0); } while (0)
; #define PG8_LDA(dst, b, h) do { _Pragma("unroll") for (int m = 0; m < 4; ++m) _Pragma("unroll") for (int k = 0; k < 2; ++k) dst[m][k] = *(const PG8_LAS bf16x8*)(lds + PG8_SA(b, h) + aoff + m * 2048 + k * 1024); } while (0)
; #define PG8_LDB(dst, b, h) do { _Pragma("unroll") for (int n = 0; n < 2; ++n) _Pragma("unroll") for (int k = 0; k < 2; ++k) dst[n][k] = *(const PG8_LAS bf16x8*)(lds + PG8_SB(b, h) + boff + n * 2048 + k * 1024); } while (0)
; #define PG8_MMA(ai, bj, At, Bt) do { __builtin_amdgcn_s_setprio(1); _Pragma("unroll") for (int m = 0; m < 4; ++m) _Pragma("unroll") for (int n = 0; n < 2; ++n) _Pragma("unroll") for (int k = 0; k < 2; ++k) \
;         acc[ai][bj][m][n] = __builtin_amdgcn_mfma_f32_16x16x32_bf16(Bt[n][k], At[m][k], acc[ai][bj][m][n], 0, 0, 0); __builtin_amdgcn_s_setprio(0); } while (0)
; template <class Epi, class Sched, bool ALIGN_EPI = false, bool SP2 = false>
; __device__ __forceinline__ void gemm_phase(PG8_LAS unsigned char* lds, const Gemm g, const Sched& S, const Epi& E) {
;     ...
;             PG8_LDB(B0, 0, 0); PG8_LDB(B1, 0, 1); PG8_SCHED; PG8_LDA(At, 0, 0); PG8_STAGE(PG8_SA(1, 1), a1 + hstep, voffA);
;             PG8_WAIT_V(8); PG8_WAIT_L(0); PG8_BAR; PG8_MMA(0, 0, At, B0); PG8_MMA(0, 1, At, B1); PG8_BAR; PG8_SCHED;
;             PG8_LDA(At, 0, 1); PG8_STAGE(PG8_SB(0, 0), b2, voffB); PG8_STAGE(PG8_SB(0, 1), b2 + hstep, voffB); PG8_STAGE(PG8_SA(0, 0), a2, voffA);
;             PG8_WAIT_V(8); PG8_WAIT_L(0); PG8_BAR; PG8_MMA(1, 0, At, B0); PG8_MMA(1, 1, At, B1); PG8_BAR; PG8_SCHED;
;             PG8_LDB(B0, 1, 0); PG8_LDB(B1, 1, 1); PG8_SCHED; PG8_LDA(At, 1, 0); PG8_STAGE(PG8_SA(0, 1), a2 + hstep, voffA);
;             PG8_WAIT_V(8); PG8_WAIT_L(0); PG8_BAR; PG8_MMA(0, 0, At, B0); PG8_MMA(0, 1, At, B1); PG8_BAR; PG8_SCHED;
;             PG8_LDA(At, 1, 1); PG8_STAGE(PG8_SB(1, 0), b3, voffB); PG8_STAGE(PG8_SB(1, 1), b3 + hstep, voffB); PG8_STAGE(PG8_SA(1, 0), a3, voffA);
;             PG8_WAIT_V(8); PG8_WAIT_L(0); PG8_BAR; PG8_MMA(1, 0, At, B0); PG8_MMA(1, 1, At, B1); PG8_BAR; PG8_SCHED;
;     ...
;         if constexpr (ALIGN_EPI) { if (wr == 0) PG8_BAR; }
	v_mfma_f32_16x16x32_bf16 v[64:67], v[156:159], v[214:217], v[64:67]
	s_setprio 0
	s_add_i32 s40, s63, s42
	v_lshl_add_u64 v[218:219], v[218:219], 0, s[12:13]
	s_mov_b32 m0, s40
	ds_read_b128 v[178:181], v204 offset:49152
	ds_read_b128 v[182:185], v204 offset:50176
	ds_read_b128 v[186:189], v204 offset:51200
	ds_read_b128 v[190:193], v204 offset:52224
	ds_read_b128 v[194:197], v204 offset:53248
	ds_read_b128 v[206:209], v204 offset:54272
	ds_read_b128 v[210:213], v204 offset:55296
	ds_read_b128 v[214:217], v204 offset:56320
	global_load_lds_dwordx4 v[218:219], off
	s_add_i32 m0, s40, 0x2000
	s_add_u32 s6, s6, 0x40080
	v_lshl_add_u64 v[218:219], v[220:221], 0, s[12:13]
	s_addc_u32 s7, s7, 0
	s_add_i32 s40, s64, s42
	global_load_lds_dwordx4 v[218:219], off
	v_lshl_add_u64 v[218:219], s[6:7], 0, v[162:163]
	s_mov_b32 m0, s40
	s_nop 0
	global_load_lds_dwordx4 v[218:219], off
	v_lshl_add_u64 v[218:219], s[6:7], 0, v[166:167]
	s_add_i32 m0, s40, 0x2000
	s_nop 0
	global_load_lds_dwordx4 v[218:219], off
	v_lshl_add_u64 v[218:219], v[222:223], 0, s[12:13]
	s_mov_b32 m0, s52
	s_nop 0
	global_load_lds_dwordx4 v[218:219], off
	v_lshl_add_u64 v[218:219], v[224:225], 0, s[12:13]
	s_mov_b32 m0, s53
	s_nop 0
	global_load_lds_dwordx4 v[218:219], off
	s_waitcnt vmcnt(8)
	s_waitcnt lgkmcnt(0)
	s_barrier
	s_setprio 1
	s_waitcnt lgkmcnt(0)
	v_mfma_f32_16x16x32_bf16 v[60:63], v[128:131], v[178:181], v[60:63]
	v_mfma_f32_16x16x32_bf16 v[56:59], v[136:139], v[178:181], v[56:59]
	v_mfma_f32_16x16x32_bf16 v[44:47], v[128:131], v[186:189], v[44:47]
	v_mfma_f32_16x16x32_bf16 v[40:43], v[136:139], v[186:189], v[40:43]
	v_mfma_f32_16x16x32_bf16 v[28:31], v[128:131], v[194:197], v[28:31]
	v_mfma_f32_16x16x32_bf16 v[24:27], v[136:139], v[194:197], v[24:27]
	v_mfma_f32_16x16x32_bf16 v[12:15], v[128:131], v[210:213], v[12:15]
	v_mfma_f32_16x16x32_bf16 v[8:11], v[136:139], v[210:213], v[8:11]
	v_mfma_f32_16x16x32_bf16 v[60:63], v[132:135], v[182:185], v[60:63]
	v_mfma_f32_16x16x32_bf16 v[56:59], v[140:143], v[182:185], v[56:59]
	v_mfma_f32_16x16x32_bf16 v[44:47], v[132:135], v[190:193], v[44:47]
	v_mfma_f32_16x16x32_bf16 v[40:43], v[140:143], v[190:193], v[40:43]
	v_mfma_f32_16x16x32_bf16 v[28:31], v[132:135], v[206:209], v[28:31]
	v_mfma_f32_16x16x32_bf16 v[24:27], v[140:143], v[206:209], v[24:27]
	v_mfma_f32_16x16x32_bf16 v[12:15], v[132:135], v[214:217], v[12:15]
	v_mfma_f32_16x16x32_bf16 v[8:11], v[140:143], v[214:217], v[8:11]
	s_setprio 0
	s_setprio 1
	v_mfma_f32_16x16x32_bf16 v[52:55], v[144:147], v[178:181], v[52:55]
	v_mfma_f32_16x16x32_bf16 v[48:51], v[152:155], v[178:181], v[48:51]
	v_mfma_f32_16x16x32_bf16 v[36:39], v[144:147], v[186:189], v[36:39]
	v_mfma_f32_16x16x32_bf16 v[32:35], v[152:155], v[186:189], v[32:35]
	v_mfma_f32_16x16x32_bf16 v[20:23], v[144:147], v[194:197], v[20:23]
	v_mfma_f32_16x16x32_bf16 v[16:19], v[152:155], v[194:197], v[16:19]
	v_mfma_f32_16x16x32_bf16 v[4:7], v[144:147], v[210:213], v[4:7]
	v_mfma_f32_16x16x32_bf16 v[0:3], v[152:155], v[210:213], v[0:3]
	v_mfma_f32_16x16x32_bf16 v[52:55], v[148:151], v[182:185], v[52:55]
	v_mfma_f32_16x16x32_bf16 v[48:51], v[156:159], v[182:185], v[48:51]
	v_mfma_f32_16x16x32_bf16 v[36:39], v[148:151], v[190:193], v[36:39]
	v_mfma_f32_16x16x32_bf16 v[32:35], v[156:159], v[190:193], v[32:35]
	v_mfma_f32_16x16x32_bf16 v[20:23], v[148:151], v[206:209], v[20:23]
	v_mfma_f32_16x16x32_bf16 v[16:19], v[156:159], v[206:209], v[16:19]
	v_mfma_f32_16x16x32_bf16 v[4:7], v[148:151], v[214:217], v[4:7]
	s_barrier
	v_mfma_f32_16x16x32_bf16 v[0:3], v[156:159], v[214:217], v[0:3]
	s_setprio 0
	s_add_i32 s62, s62, 2
	s_add_u32 s4, s4, 0x100
	s_addc_u32 s5, s5, 0
	s_add_u32 s60, s60, 0x100
	s_addc_u32 s61, s61, 0
	s_cmp_gt_u32 s62, 13
	s_cbranch_scc0 .LBB0_1033
	s_and_b64 vcc, exec, s[14:15]
	s_cbranch_vccz .LBB0_1036
	s_barrier
